# write-through wide stores also in P0, P3 outputs, P4 epilogue and the final-norm outputs
# speedup vs baseline: 1.0071x; 1.0060x over previous
; __device__ __forceinline__ void p0_prep(const Params& p, LAS unsigned char* lds) {
;     ...
;     for (int i = blockIdx.x * 512 + threadIdx.x; i < (MPAD - MALL) * D / 8; i += gridDim.x * 512) ((u32x4*)(ws + OFF_XN16 + (size_t)MALL * D * 2))[i] = (u32x4){0u, 0u, 0u, 0u};
.LBB0_12:
	v_ashrrev_i32_e32 v9, 31, v8
	v_lshl_add_u64 v[10:11], v[8:9], 4, s[8:9]
	v_add_u32_e32 v8, s3, v8
	v_cmp_lt_i32_e32 vcc, s12, v8
	s_or_b64 s[10:11], vcc, s[10:11]
	global_store_dwordx4 v[10:11], v[2:5], off sc0 sc1
	s_andn2_b64 exec, exec, s[10:11]
	s_cbranch_execnz .LBB0_12

; __device__ __forceinline__ void tr_tile(const float* W, int K, int N, int kt, int nt, LAS float* tile, const float* kscale, h16* dst, int mode, h16* dstG) {
;     ...
;     {
;         const int n = tid >> 3, kc = (tid & 7) * 8, gn = n0 + n;
;         if (gn < N) {
;             h16x8 o;
; #pragma unroll
;             for (int j = 0; j < 8; ++j) o[j] = (h16)tile[(kc + j) * 65 + n];
;             h16* d;
;             if (mode == 0) d = dst + (size_t)gn * K;
;             else d = (gn < 2048) ? dst + (size_t)gn * K : (gn < 2064 ? dstG + (size_t)(gn - 2048) * K : dst + (size_t)(gn - 16) * K);
;             *(h16x8*)(d + k0 + kc) = o;
;         }
.LBB0_22:
	s_or_b64 exec, exec, s[30:31]
	v_lshlrev_b64 v[2:3], 11, v[2:3]
	v_lshl_add_u64 v[2:3], v[30:31], 0, v[2:3]
	s_ashr_i32 s11, s10, 31
	v_lshl_add_u64 v[2:3], s[10:11], 1, v[2:3]
	s_waitcnt lgkmcnt(0)
	v_cvt_pk_f16_f32 v43, v28, v29
	v_cvt_pk_f16_f32 v42, v8, v9
	v_cvt_pk_f16_f32 v41, v6, v7
	v_cvt_pk_f16_f32 v40, v4, v5
	v_lshl_add_u64 v[2:3], v[2:3], 0, v[10:11]
	global_store_dwordx4 v[2:3], v[40:43], off sc0 sc1

; __device__ __forceinline__ void tr_tile(const float* W, int K, int N, int kt, int nt, LAS float* tile, const float* kscale, h16* dst, int mode, h16* dstG) {
;     const int tid = threadIdx.x, k0 = kt * 64, n0 = nt * 64;
;     {
;         const int kr = tid >> 4, nc = (tid & 15) * 4;
; #pragma unroll
;         for (int i = 0; i < 2; ++i) {
;             const int k = kr + 32 * i;
;             f32x4 v = {0.f, 0.f, 0.f, 0.f};
;             if (n0 + nc < N) v = *(const f32x4*)(W + (size_t)(k0 + k) * N + n0 + nc);
;             const float s = kscale ? kscale[k0 + k] : 1.f;
;             tile[k * 65 + nc] = v[0] * s; tile[k * 65 + nc + 1] = v[1] * s; tile[k * 65 + nc + 2] = v[2] * s; tile[k * 65 + nc + 3] = v[3] * s;
;         }
;     }
;     __syncthreads();
;     {
;         const int n = tid >> 3, kc = (tid & 7) * 8, gn = n0 + n;
;         if (gn < N) {
;             h16x8 o;
; #pragma unroll
;             for (int j = 0; j < 8; ++j) o[j] = (h16)tile[(kc + j) * 65 + n];
;             h16* d;
;             if (mode == 0) d = dst + (size_t)gn * K;
;             else d = (gn < 2048) ? dst + (size_t)gn * K : (gn < 2064 ? dstG + (size_t)(gn - 2048) * K : dst + (size_t)(gn - 16) * K);
;             *(h16x8*)(d + k0 + kc) = o;
;         }
.LBB0_25:
	s_cmpk_gt_i32 s55, 0x3cf
	s_mov_b64 s[10:11], -1
	s_cbranch_scc0 .LBB0_40
	s_cmpk_gt_u32 s55, 0x3d7
	s_cbranch_scc0 .LBB0_35
	s_cmpk_gt_u32 s55, 0x3df
	s_cbranch_scc0 .LBB0_31
	s_and_b32 s0, s54, 0x7fffffc0
	s_add_i32 s10, s0, 0xffffe100
	s_and_b32 s11, s3, 0x1c0
	s_lshl_b32 s0, s11, 2
	v_or_b32_e32 v4, s10, v146
	v_mov_b32_e32 v5, v11
	v_lshl_add_u64 v[2:3], v[16:17], 0, s[0:1]
	v_lshlrev_b64 v[4:5], 11, v[4:5]
	v_lshl_add_u64 v[4:5], v[2:3], 0, v[4:5]
	v_add_u32_e32 v8, s10, v32
	v_mov_b32_e32 v9, v11
	global_load_dwordx4 v[4:7], v[4:5], off
	v_lshlrev_b64 v[8:9], 11, v[8:9]
	v_lshl_add_u64 v[2:3], v[2:3], 0, v[8:9]
	global_load_dwordx4 v[28:31], v[2:3], off
	v_add_u32_e32 v2, s11, v147
	v_cmp_gt_u32_e32 vcc, s43, v2
	s_waitcnt vmcnt(1)
	ds_write2_b32 v34, v4, v5 offset1:1
	ds_write2_b32 v34, v6, v7 offset0:2 offset1:3
	s_waitcnt vmcnt(0)
	ds_write2_b32 v35, v28, v29 offset1:1
	ds_write2_b32 v36, v30, v31 offset1:1
	s_waitcnt lgkmcnt(0)
	s_barrier
	s_and_saveexec_b64 s[28:29], vcc
	s_cbranch_execz .LBB0_30
	ds_read2_b32 v[4:5], v38 offset0:134 offset1:199
	ds_read2_b32 v[8:9], v38 offset0:4 offset1:69
	ds_read2_b32 v[28:29], v37 offset0:130 offset1:195
	ds_read2_b32 v[30:31], v37 offset1:65
	v_lshlrev_b32_e32 v2, 8, v2
	v_mov_b32_e32 v3, v11
	v_lshl_add_u64 v[2:3], s[6:7], 0, v[2:3]
	s_mov_b32 s11, s1
	v_lshl_add_u64 v[2:3], s[10:11], 1, v[2:3]
	s_waitcnt lgkmcnt(3)
	v_cvt_pk_f16_f32 v7, v4, v5
	s_waitcnt lgkmcnt(2)
	v_cvt_pk_f16_f32 v6, v8, v9
	s_waitcnt lgkmcnt(1)
	v_cvt_pk_f16_f32 v5, v28, v29
	s_waitcnt lgkmcnt(0)
	v_cvt_pk_f16_f32 v4, v30, v31
	v_lshl_add_u64 v[2:3], v[2:3], 0, v[10:11]
	global_store_dwordx4 v[2:3], v[4:7], off sc0 sc1

; __device__ __forceinline__ void tr_tile(const float* W, int K, int N, int kt, int nt, LAS float* tile, const float* kscale, h16* dst, int mode, h16* dstG) {
;     const int tid = threadIdx.x, k0 = kt * 64, n0 = nt * 64;
;     {
;         const int kr = tid >> 4, nc = (tid & 15) * 4;
; #pragma unroll
;         for (int i = 0; i < 2; ++i) {
;             const int k = kr + 32 * i;
;             f32x4 v = {0.f, 0.f, 0.f, 0.f};
;             if (n0 + nc < N) v = *(const f32x4*)(W + (size_t)(k0 + k) * N + n0 + nc);
;             const float s = kscale ? kscale[k0 + k] : 1.f;
;             tile[k * 65 + nc] = v[0] * s; tile[k * 65 + nc + 1] = v[1] * s; tile[k * 65 + nc + 2] = v[2] * s; tile[k * 65 + nc + 3] = v[3] * s;
;         }
;     }
;     __syncthreads();
;     {
;         const int n = tid >> 3, kc = (tid & 7) * 8, gn = n0 + n;
;         if (gn < N) {
;             h16x8 o;
; #pragma unroll
;             for (int j = 0; j < 8; ++j) o[j] = (h16)tile[(kc + j) * 65 + n];
;             h16* d;
;             if (mode == 0) d = dst + (size_t)gn * K;
;             else d = (gn < 2048) ? dst + (size_t)gn * K : (gn < 2064 ? dstG + (size_t)(gn - 2048) * K : dst + (size_t)(gn - 16) * K);
;             *(h16x8*)(d + k0 + kc) = o;
;         }
.LBB0_31:
	s_and_b64 vcc, exec, s[10:11]
	s_cbranch_vccz .LBB0_52
	s_add_i32 s0, s3, 0xffff0a00
	v_lshl_add_u64 v[6:7], s[0:1], 2, v[18:19]
	v_mov_b32_e32 v25, v11
	v_lshl_add_u64 v[2:3], v[6:7], 0, v[24:25]
	global_load_dwordx4 v[2:5], v[2:3], off
	v_mov_b32_e32 v27, v11
	v_lshl_add_u64 v[6:7], v[6:7], 0, v[26:27]
	global_load_dwordx4 v[6:9], v[6:7], off
	v_add_u32_e32 v25, s0, v147
	v_cmp_gt_u32_e32 vcc, s43, v25
	s_waitcnt vmcnt(1)
	ds_write2_b32 v34, v2, v3 offset1:1
	ds_write2_b32 v34, v4, v5 offset0:2 offset1:3
	s_waitcnt vmcnt(0)
	ds_write2_b32 v35, v6, v7 offset1:1
	ds_write2_b32 v36, v8, v9 offset1:1
	s_waitcnt lgkmcnt(0)
	s_barrier
	s_and_saveexec_b64 s[10:11], vcc
	s_cbranch_execz .LBB0_34
	ds_read2_b32 v[2:3], v38 offset0:134 offset1:199
	ds_read2_b32 v[6:7], v38 offset0:4 offset1:69
	ds_read2_b32 v[8:9], v37 offset0:130 offset1:195
	ds_read2_b32 v[28:29], v37 offset1:65
	s_waitcnt lgkmcnt(3)
	v_cvt_pk_f16_f32 v5, v2, v3
	s_waitcnt lgkmcnt(2)
	v_cvt_pk_f16_f32 v4, v6, v7
	v_add_u32_e32 v6, 0xffc28000, v33
	v_mov_b32_e32 v7, v11
	s_waitcnt lgkmcnt(1)
	v_cvt_pk_f16_f32 v3, v8, v9
	s_waitcnt lgkmcnt(0)
	v_cvt_pk_f16_f32 v2, v28, v29
	v_lshl_add_u64 v[6:7], v[6:7], 1, v[12:13]
	global_store_dwordx4 v[6:7], v[2:5], off sc0 sc1

; __device__ __forceinline__ void tr_tile(const float* W, int K, int N, int kt, int nt, LAS float* tile, const float* kscale, h16* dst, int mode, h16* dstG) {
;     const int tid = threadIdx.x, k0 = kt * 64, n0 = nt * 64;
;     {
;         const int kr = tid >> 4, nc = (tid & 15) * 4;
; #pragma unroll
;         for (int i = 0; i < 2; ++i) {
;             const int k = kr + 32 * i;
;             f32x4 v = {0.f, 0.f, 0.f, 0.f};
;             if (n0 + nc < N) v = *(const f32x4*)(W + (size_t)(k0 + k) * N + n0 + nc);
;             const float s = kscale ? kscale[k0 + k] : 1.f;
;             tile[k * 65 + nc] = v[0] * s; tile[k * 65 + nc + 1] = v[1] * s; tile[k * 65 + nc + 2] = v[2] * s; tile[k * 65 + nc + 3] = v[3] * s;
;         }
;     }
;     __syncthreads();
;     {
;         const int n = tid >> 3, kc = (tid & 7) * 8, gn = n0 + n;
;         if (gn < N) {
;             h16x8 o;
; #pragma unroll
;             for (int j = 0; j < 8; ++j) o[j] = (h16)tile[(kc + j) * 65 + n];
;             h16* d;
;             if (mode == 0) d = dst + (size_t)gn * K;
;             else d = (gn < 2048) ? dst + (size_t)gn * K : (gn < 2064 ? dstG + (size_t)(gn - 2048) * K : dst + (size_t)(gn - 16) * K);
;             *(h16x8*)(d + k0 + kc) = o;
;         }
.LBB0_36:
	s_add_i32 s0, s3, 0xffff0c00
	v_lshl_add_u64 v[6:7], s[0:1], 2, v[20:21]
	v_mov_b32_e32 v25, v11
	v_lshl_add_u64 v[2:3], v[6:7], 0, v[24:25]
	global_load_dwordx4 v[2:5], v[2:3], off
	v_mov_b32_e32 v27, v11
	v_lshl_add_u64 v[6:7], v[6:7], 0, v[26:27]
	global_load_dwordx4 v[6:9], v[6:7], off
	v_add_u32_e32 v25, s0, v147
	v_cmp_gt_u32_e32 vcc, s43, v25
	s_waitcnt vmcnt(1)
	ds_write2_b32 v34, v2, v3 offset1:1
	ds_write2_b32 v34, v4, v5 offset0:2 offset1:3
	s_waitcnt vmcnt(0)
	ds_write2_b32 v35, v6, v7 offset1:1
	ds_write2_b32 v36, v8, v9 offset1:1
	s_waitcnt lgkmcnt(0)
	s_barrier
	s_and_saveexec_b64 s[10:11], vcc
	s_cbranch_execz .LBB0_38
	ds_read2_b32 v[2:3], v38 offset0:134 offset1:199
	ds_read2_b32 v[6:7], v38 offset0:4 offset1:69
	ds_read2_b32 v[8:9], v37 offset0:130 offset1:195
	ds_read2_b32 v[28:29], v37 offset1:65
	s_waitcnt lgkmcnt(3)
	v_cvt_pk_f16_f32 v5, v2, v3
	s_waitcnt lgkmcnt(2)
	v_cvt_pk_f16_f32 v4, v6, v7
	v_add_u32_e32 v6, 0xffc30000, v33
	v_mov_b32_e32 v7, v11
	s_waitcnt lgkmcnt(1)
	v_cvt_pk_f16_f32 v3, v8, v9
	s_waitcnt lgkmcnt(0)
	v_cvt_pk_f16_f32 v2, v28, v29
	v_lshl_add_u64 v[6:7], v[6:7], 1, v[14:15]
	global_store_dwordx4 v[6:7], v[2:5], off sc0 sc1

; __device__ __forceinline__ void rwkv_scan_prompt(const Params& p, LAS unsigned char* lds, int bh, int rq) {
;     ...
;     if (wave < 4) *(f32x4*)(p.out + O_PS + ((size_t)bh * 64 + rq * 16 + rloc) * 64 + cg_ * 4) = S;
.LBB0_358:
	s_and_saveexec_b64 s[58:59], vcc
	s_cbranch_execz .LBB0_310
	s_ashr_i32 s73, s72, 31
	s_lshl_b64 s[60:61], s[72:73], 6
	s_waitcnt vmcnt(5)
	v_mov_b32_e32 v0, s94
	v_or3_b32 v1, s61, 0, 0
	v_or3_b32 v0, s60, v146, v0
	v_lshlrev_b64 v[0:1], 8, v[0:1]
	v_lshl_add_u64 v[0:1], v[82:83], 0, v[0:1]
	global_store_dwordx4 v[0:1], v[24:27], off sc0 sc1
	s_branch .LBB0_310

; __device__ __forceinline__ float row_sum16(float x) { x = dpp_add<0xB1>(x); x = dpp_add<0x4E>(x); x = dpp_add<0x124>(x); x = dpp_add<0x128>(x); return x; }
; __device__ __forceinline__ void rwkv_sample_task(const Params& p, int s, int h) {
;     ...
;     const h16* ob = (const h16*)(ws + OFF_OPS16) + ((size_t)row * 8 + h) * 6 * 64;
;     f32x4 r4, d4, k4, a4, b4;
;     {
;         const h16x4 hr = *(const h16x4*)(ob + cg_ * 4), hw = *(const h16x4*)(ob + 64 + cg_ * 4), hk = *(const h16x4*)(ob + 128 + cg_ * 4),
;                     ha = *(const h16x4*)(ob + 256 + cg_ * 4), hb = *(const h16x4*)(ob + 320 + cg_ * 4);
; #pragma unroll
;         for (int j = 0; j < 4; ++j) { r4[j] = (float)hr[j]; d4[j] = __expf((float)hw[j]); k4[j] = (float)hk[j]; a4[j] = (float)ha[j]; b4[j] = (float)hb[j]; }
;     }
;     const float rk = ((const float*)(ws + OFF_RKS))[(size_t)row * 8 + h];
;     const float* S0 = p.in[6] + ((size_t)s * 8 + h) * 4096;
;     float* So = p.out + O_SS + ((size_t)s * 8 + h) * 4096;
;     float ysel = 0.f;
; #pragma unroll
;     for (int g = 0; g < 16; ++g) {
;         const int vrow = g * 4 + rr;
;         const float vv = (float)ob[192 + vrow];
;         f32x4 S = *(const f32x4*)(S0 + (size_t)vrow * 64 + cg_ * 4);
;         float sa = S[0] * a4[0] + S[1] * a4[1] + S[2] * a4[2] + S[3] * a4[3];
;         sa = row_sum16(sa);
;         S = S * d4 + sa * b4 + vv * k4;
;         float y = S[0] * r4[0] + S[1] * r4[1] + S[2] * r4[2] + S[3] * r4[3];
;         y = row_sum16(y) + rk * vv;
;         *(f32x4*)(So + (size_t)vrow * 64 + cg_ * 4) = S;
.LBB0_362:
	v_ashrrev_i32_e32 v0, 3, v143
	v_add_u32_e32 v106, 0x4000, v0
	v_ashrrev_i32_e32 v1, 31, v0
	v_ashrrev_i32_e32 v107, 31, v106
	v_lshlrev_b64 v[0:1], 17, v[0:1]
	v_lshlrev_b64 v[4:5], 3, v[106:107]
	v_mov_b64_e32 v[2:3], s[86:87]
	v_lshl_or_b32 v0, v56, 2, v0
	v_or_b32_e32 v4, v4, v54
	v_mov_b32_e32 v73, v53
	v_lshl_add_u64 v[146:147], v[58:59], 0, v[0:1]
	v_mad_u64_u32 v[150:151], s[0:1], v4, s3, v[2:3]
	v_lshl_add_u64 v[148:149], v[60:61], 0, v[0:1]
	v_lshl_add_u64 v[0:1], v[146:147], 0, v[72:73]
	v_mad_i32_i24 v151, v107, s3, v151
	v_mov_b32_e32 v71, v53
	global_load_dwordx4 v[0:3], v[0:1], off
	v_lshl_add_u64 v[10:11], v[150:151], 0, v[52:53]
	v_lshl_add_u64 v[4:5], v[4:5], 2, s[40:41]
	v_lshl_add_u64 v[6:7], v[148:149], 0, v[72:73]
	v_lshl_add_u64 v[126:127], v[150:151], 0, v[70:71]
	global_load_dwordx2 v[16:17], v[10:11], off offset:512
	global_load_dwordx2 v[18:19], v[10:11], off offset:128
	global_load_dwordx2 v[32:33], v[10:11], off offset:256
	global_load_dwordx2 v[34:35], v[10:11], off offset:640
	global_load_ushort v73, v[126:127], off offset:384
	global_load_dword v71, v[4:5], off
	global_load_dwordx2 v[108:109], v[10:11], off
	v_mov_b32_e32 v75, v53
	v_mov_b32_e32 v79, v53
	v_lshl_add_u64 v[8:9], v[146:147], 0, v[74:75]
	v_lshl_add_u64 v[22:23], v[146:147], 0, v[78:79]
	v_lshl_add_u64 v[24:25], v[148:149], 0, v[78:79]
	v_lshl_add_u64 v[12:13], v[148:149], 0, v[74:75]
	v_mov_b32_e32 v77, v53
	v_lshl_add_u64 v[14:15], v[146:147], 0, v[76:77]
	v_lshl_add_u64 v[20:21], v[148:149], 0, v[76:77]
	v_mov_b32_e32 v81, v53
	v_lshl_add_u64 v[26:27], v[146:147], 0, v[80:81]
	v_lshl_add_u64 v[28:29], v[148:149], 0, v[80:81]
	v_mov_b32_e32 v83, v53
	v_lshl_add_u64 v[30:31], v[146:147], 0, v[82:83]
	v_mov_b32_e32 v85, v53
	v_mov_b32_e32 v87, v53
	v_mov_b32_e32 v89, v53
	v_mov_b32_e32 v91, v53
	v_mov_b32_e32 v93, v53
	v_mov_b32_e32 v95, v53
	v_mov_b32_e32 v97, v53
	v_mov_b32_e32 v99, v53
	v_mov_b32_e32 v101, v53
	v_mov_b32_e32 v105, v53
	v_lshl_add_u64 v[162:163], v[148:149], 0, v[100:101]
	v_mov_b32_e32 v103, v53
	v_lshl_add_u64 v[150:151], v[150:151], 0, v[102:103]
	v_add_u32_e32 v143, s88, v143
	v_cmp_lt_i32_e64 s[0:1], s45, v143
	s_or_b64 s[42:43], s[0:1], s[42:43]
	s_waitcnt vmcnt(6)
	v_cvt_f32_f16_e32 v122, v16
	s_waitcnt vmcnt(5)
	v_cvt_f32_f16_e32 v5, v18
	v_cvt_f32_f16_sdwa v10, v18 dst_sel:DWORD dst_unused:UNUSED_PAD src0_sel:WORD_1
	v_cvt_f32_f16_e32 v11, v19
	v_cvt_f32_f16_sdwa v123, v16 dst_sel:DWORD dst_unused:UNUSED_PAD src0_sel:WORD_1
	v_cvt_f32_f16_e32 v124, v17
	v_cvt_f32_f16_sdwa v125, v17 dst_sel:DWORD dst_unused:UNUSED_PAD src0_sel:WORD_1
	s_waitcnt vmcnt(4)
	v_cvt_f32_f16_e32 v110, v32
	v_cvt_f32_f16_sdwa v111, v32 dst_sel:DWORD dst_unused:UNUSED_PAD src0_sel:WORD_1
	v_cvt_f32_f16_sdwa v18, v19 dst_sel:DWORD dst_unused:UNUSED_PAD src0_sel:WORD_1
	v_mul_f32_e32 v5, 0x3fb8aa3b, v5
	v_mul_f32_e32 v19, 0x3fb8aa3b, v10
	v_mul_f32_e32 v32, 0x3fb8aa3b, v11
	v_pk_mul_f32 v[10:11], v[0:1], v[122:123]
	v_pk_mul_f32 v[16:17], v[2:3], v[124:125]
	v_exp_f32_e32 v118, v5
	v_add_f32_e32 v5, v10, v11
	v_add_f32_e32 v5, v16, v5
	v_add_f32_e32 v5, v17, v5
	s_waitcnt vmcnt(3)
	v_cvt_f32_f16_e32 v112, v34
	v_cvt_f32_f16_sdwa v113, v34 dst_sel:DWORD dst_unused:UNUSED_PAD src0_sel:WORD_1
	v_cvt_f32_f16_e32 v116, v35
	v_cvt_f32_f16_sdwa v117, v35 dst_sel:DWORD dst_unused:UNUSED_PAD src0_sel:WORD_1
	v_mul_f32_e32 v18, 0x3fb8aa3b, v18
	v_add_f32_dpp v5, v5, v5 quad_perm:[1,0,3,2] row_mask:0xf bank_mask:0xf bound_ctrl:1
	v_exp_f32_e32 v119, v19
	v_exp_f32_e32 v120, v32
	v_exp_f32_e32 v121, v18
	v_add_f32_dpp v5, v5, v5 quad_perm:[2,3,0,1] row_mask:0xf bank_mask:0xf bound_ctrl:1
	v_cvt_f32_f16_e32 v114, v33
	v_cvt_f32_f16_sdwa v115, v33 dst_sel:DWORD dst_unused:UNUSED_PAD src0_sel:WORD_1
	s_waitcnt vmcnt(2)
	v_cvt_f32_f16_e32 v4, v73
	v_add_f32_dpp v5, v5, v5 row_ror:4 row_mask:0xf bank_mask:0xf bound_ctrl:1
	s_nop 1
	v_add_f32_dpp v10, v5, v5 row_ror:8 row_mask:0xf bank_mask:0xf bound_ctrl:1
	v_pk_mul_f32 v[16:17], v[116:117], v[10:11] op_sel_hi:[1,0]
	v_pk_mul_f32 v[10:11], v[112:113], v[10:11] op_sel_hi:[1,0]
	v_pk_fma_f32 v[2:3], v[2:3], v[120:121], v[16:17]
	v_pk_fma_f32 v[0:1], v[0:1], v[118:119], v[10:11]
	v_pk_fma_f32 v[2:3], v[114:115], v[4:5], v[2:3] op_sel_hi:[1,0,1]
	v_pk_fma_f32 v[0:1], v[110:111], v[4:5], v[0:1] op_sel_hi:[1,0,1]
	global_store_dwordx4 v[6:7], v[0:3], off sc0 sc1
	global_load_ushort v79, v[126:127], off offset:392
	s_nop 0
	global_load_dwordx4 v[4:7], v[8:9], off
	s_waitcnt vmcnt(1)
	v_cvt_f32_f16_e32 v8, v79
	s_waitcnt vmcnt(0)
	v_pk_mul_f32 v[10:11], v[4:5], v[122:123]
	v_pk_mul_f32 v[16:17], v[6:7], v[124:125]
	v_add_f32_e32 v9, v10, v11
	v_add_f32_e32 v9, v16, v9
	v_add_f32_e32 v9, v17, v9
	s_nop 1
	v_add_f32_dpp v9, v9, v9 quad_perm:[1,0,3,2] row_mask:0xf bank_mask:0xf bound_ctrl:1
	s_nop 1
	v_add_f32_dpp v9, v9, v9 quad_perm:[2,3,0,1] row_mask:0xf bank_mask:0xf bound_ctrl:1
	s_nop 1
	v_add_f32_dpp v9, v9, v9 row_ror:4 row_mask:0xf bank_mask:0xf bound_ctrl:1
	s_nop 1
	v_add_f32_dpp v10, v9, v9 row_ror:8 row_mask:0xf bank_mask:0xf bound_ctrl:1
	v_pk_mul_f32 v[16:17], v[116:117], v[10:11] op_sel_hi:[1,0]
	v_pk_mul_f32 v[10:11], v[112:113], v[10:11] op_sel_hi:[1,0]
	v_pk_fma_f32 v[6:7], v[120:121], v[6:7], v[16:17]
	v_pk_fma_f32 v[4:5], v[118:119], v[4:5], v[10:11]
	v_pk_fma_f32 v[10:11], v[114:115], v[8:9], v[6:7] op_sel_hi:[1,0,1]
	v_pk_fma_f32 v[8:9], v[110:111], v[8:9], v[4:5] op_sel_hi:[1,0,1]
	global_store_dwordx4 v[12:13], v[8:11], off sc0 sc1
	global_load_ushort v75, v[126:127], off offset:400
	global_load_dwordx4 v[4:7], v[14:15], off
	s_waitcnt vmcnt(1)
	v_cvt_f32_f16_e32 v12, v75
	s_waitcnt vmcnt(0)
; __device__ __forceinline__ float row_sum16(float x) { x = dpp_add<0xB1>(x); x = dpp_add<0x4E>(x); x = dpp_add<0x124>(x); x = dpp_add<0x128>(x); return x; }
; __device__ __forceinline__ void rwkv_sample_task(const Params& p, int s, int h) {
;     ...
; #pragma unroll
;     for (int g = 0; g < 16; ++g) {
;         const int vrow = g * 4 + rr;
;         const float vv = (float)ob[192 + vrow];
;         f32x4 S = *(const f32x4*)(S0 + (size_t)vrow * 64 + cg_ * 4);
;         float sa = S[0] * a4[0] + S[1] * a4[1] + S[2] * a4[2] + S[3] * a4[3];
;         sa = row_sum16(sa);
;         S = S * d4 + sa * b4 + vv * k4;
;         float y = S[0] * r4[0] + S[1] * r4[1] + S[2] * r4[2] + S[3] * r4[3];
;         y = row_sum16(y) + rk * vv;
;         *(f32x4*)(So + (size_t)vrow * 64 + cg_ * 4) = S;
;         ysel = (cg_ == g) ? y : ysel;
;     }
	v_pk_mul_f32 v[14:15], v[4:5], v[122:123]
	v_pk_mul_f32 v[16:17], v[6:7], v[124:125]
	v_add_f32_e32 v13, v14, v15
	v_add_f32_e32 v13, v16, v13
	v_add_f32_e32 v13, v17, v13
	s_nop 1
	v_add_f32_dpp v13, v13, v13 quad_perm:[1,0,3,2] row_mask:0xf bank_mask:0xf bound_ctrl:1
	s_nop 1
	v_add_f32_dpp v13, v13, v13 quad_perm:[2,3,0,1] row_mask:0xf bank_mask:0xf bound_ctrl:1
	s_nop 1
	v_add_f32_dpp v13, v13, v13 row_ror:4 row_mask:0xf bank_mask:0xf bound_ctrl:1
	s_nop 1
	v_add_f32_dpp v14, v13, v13 row_ror:8 row_mask:0xf bank_mask:0xf bound_ctrl:1
	v_pk_mul_f32 v[16:17], v[116:117], v[14:15] op_sel_hi:[1,0]
	v_pk_mul_f32 v[14:15], v[112:113], v[14:15] op_sel_hi:[1,0]
	v_pk_fma_f32 v[6:7], v[120:121], v[6:7], v[16:17]
	v_pk_fma_f32 v[4:5], v[118:119], v[4:5], v[14:15]
	v_pk_fma_f32 v[18:19], v[114:115], v[12:13], v[6:7] op_sel_hi:[1,0,1]
	v_pk_fma_f32 v[16:17], v[110:111], v[12:13], v[4:5] op_sel_hi:[1,0,1]
	global_store_dwordx4 v[20:21], v[16:19], off sc0 sc1
	global_load_ushort v77, v[126:127], off offset:408
	global_load_dwordx4 v[4:7], v[22:23], off
	s_waitcnt vmcnt(1)
	v_cvt_f32_f16_e32 v12, v77
	s_waitcnt vmcnt(0)
	v_pk_mul_f32 v[14:15], v[4:5], v[122:123]
	v_pk_mul_f32 v[20:21], v[6:7], v[124:125]
	v_add_f32_e32 v13, v14, v15
	v_add_f32_e32 v13, v20, v13
	v_add_f32_e32 v13, v21, v13
	s_nop 1
	v_add_f32_dpp v13, v13, v13 quad_perm:[1,0,3,2] row_mask:0xf bank_mask:0xf bound_ctrl:1
	s_nop 1
	v_add_f32_dpp v13, v13, v13 quad_perm:[2,3,0,1] row_mask:0xf bank_mask:0xf bound_ctrl:1
	s_nop 1
	v_add_f32_dpp v13, v13, v13 row_ror:4 row_mask:0xf bank_mask:0xf bound_ctrl:1
	s_nop 1
	v_add_f32_dpp v14, v13, v13 row_ror:8 row_mask:0xf bank_mask:0xf bound_ctrl:1
	v_pk_mul_f32 v[20:21], v[116:117], v[14:15] op_sel_hi:[1,0]
	v_pk_mul_f32 v[14:15], v[112:113], v[14:15] op_sel_hi:[1,0]
	v_pk_fma_f32 v[6:7], v[120:121], v[6:7], v[20:21]
	v_pk_fma_f32 v[4:5], v[118:119], v[4:5], v[14:15]
	v_pk_fma_f32 v[6:7], v[114:115], v[12:13], v[6:7] op_sel_hi:[1,0,1]
	v_pk_fma_f32 v[4:5], v[110:111], v[12:13], v[4:5] op_sel_hi:[1,0,1]
	global_store_dwordx4 v[24:25], v[4:7], off sc0 sc1
	global_load_dwordx4 v[12:15], v[26:27], off
	global_load_ushort v81, v[126:127], off offset:416
	v_lshl_add_u64 v[26:27], v[146:147], 0, v[84:85]
	s_waitcnt vmcnt(1)
	v_pk_mul_f32 v[22:23], v[12:13], v[122:123]
	v_pk_mul_f32 v[24:25], v[14:15], v[124:125]
	v_add_f32_e32 v21, v22, v23
	v_add_f32_e32 v21, v24, v21
	v_add_f32_e32 v21, v25, v21
	s_waitcnt vmcnt(0)
	v_cvt_f32_f16_e32 v20, v81
	v_add_f32_dpp v21, v21, v21 quad_perm:[1,0,3,2] row_mask:0xf bank_mask:0xf bound_ctrl:1
	s_nop 1
	v_add_f32_dpp v21, v21, v21 quad_perm:[2,3,0,1] row_mask:0xf bank_mask:0xf bound_ctrl:1
	s_nop 1
	v_add_f32_dpp v21, v21, v21 row_ror:4 row_mask:0xf bank_mask:0xf bound_ctrl:1
	s_nop 1
	v_add_f32_dpp v22, v21, v21 row_ror:8 row_mask:0xf bank_mask:0xf bound_ctrl:1
	v_pk_mul_f32 v[24:25], v[116:117], v[22:23] op_sel_hi:[1,0]
	v_pk_mul_f32 v[22:23], v[112:113], v[22:23] op_sel_hi:[1,0]
	v_pk_fma_f32 v[14:15], v[120:121], v[14:15], v[24:25]
	v_pk_fma_f32 v[12:13], v[118:119], v[12:13], v[22:23]
	v_pk_fma_f32 v[14:15], v[114:115], v[20:21], v[14:15] op_sel_hi:[1,0,1]
	v_pk_fma_f32 v[12:13], v[110:111], v[20:21], v[12:13] op_sel_hi:[1,0,1]
	global_store_dwordx4 v[28:29], v[12:15], off sc0 sc1
	global_load_dwordx4 v[20:23], v[30:31], off
	global_load_ushort v145, v[126:127], off offset:424
	v_lshl_add_u64 v[24:25], v[148:149], 0, v[82:83]
	s_waitcnt vmcnt(1)
	v_pk_mul_f32 v[30:31], v[20:21], v[122:123]
	v_pk_mul_f32 v[32:33], v[22:23], v[124:125]
	v_add_f32_e32 v29, v30, v31
	v_add_f32_e32 v29, v32, v29
	v_add_f32_e32 v29, v33, v29
	s_waitcnt vmcnt(0)
	v_cvt_f32_f16_e32 v28, v145
	v_add_f32_dpp v29, v29, v29 quad_perm:[1,0,3,2] row_mask:0xf bank_mask:0xf bound_ctrl:1
	s_nop 1
	v_add_f32_dpp v29, v29, v29 quad_perm:[2,3,0,1] row_mask:0xf bank_mask:0xf bound_ctrl:1
	s_nop 1
	v_add_f32_dpp v29, v29, v29 row_ror:4 row_mask:0xf bank_mask:0xf bound_ctrl:1
	s_nop 1
	v_add_f32_dpp v30, v29, v29 row_ror:8 row_mask:0xf bank_mask:0xf bound_ctrl:1
	v_pk_mul_f32 v[32:33], v[116:117], v[30:31] op_sel_hi:[1,0]
	v_pk_mul_f32 v[30:31], v[112:113], v[30:31] op_sel_hi:[1,0]
	v_pk_fma_f32 v[22:23], v[120:121], v[22:23], v[32:33]
	v_pk_fma_f32 v[20:21], v[118:119], v[20:21], v[30:31]
	v_pk_fma_f32 v[22:23], v[114:115], v[28:29], v[22:23] op_sel_hi:[1,0,1]
	v_pk_fma_f32 v[20:21], v[110:111], v[28:29], v[20:21] op_sel_hi:[1,0,1]
	global_store_dwordx4 v[24:25], v[20:23], off sc0 sc1
	global_load_dwordx4 v[24:27], v[26:27], off
	s_nop 0
	global_load_ushort v83, v[126:127], off offset:432
	v_lshl_add_u64 v[28:29], v[148:149], 0, v[84:85]
	v_lshl_add_u64 v[30:31], v[146:147], 0, v[86:87]
	s_waitcnt vmcnt(1)
	v_pk_mul_f32 v[34:35], v[24:25], v[122:123]
	v_pk_mul_f32 v[36:37], v[26:27], v[124:125]
	v_add_f32_e32 v33, v34, v35
	v_add_f32_e32 v33, v36, v33
	v_add_f32_e32 v33, v37, v33
	s_waitcnt vmcnt(0)
	v_cvt_f32_f16_e32 v32, v83
	v_add_f32_dpp v33, v33, v33 quad_perm:[1,0,3,2] row_mask:0xf bank_mask:0xf bound_ctrl:1
	s_nop 1
	v_add_f32_dpp v33, v33, v33 quad_perm:[2,3,0,1] row_mask:0xf bank_mask:0xf bound_ctrl:1
	s_nop 1
	v_add_f32_dpp v33, v33, v33 row_ror:4 row_mask:0xf bank_mask:0xf bound_ctrl:1
	s_nop 1
	v_add_f32_dpp v34, v33, v33 row_ror:8 row_mask:0xf bank_mask:0xf bound_ctrl:1
	v_pk_mul_f32 v[36:37], v[116:117], v[34:35] op_sel_hi:[1,0]
	v_pk_mul_f32 v[34:35], v[112:113], v[34:35] op_sel_hi:[1,0]
	v_pk_fma_f32 v[26:27], v[120:121], v[26:27], v[36:37]
	v_pk_fma_f32 v[24:25], v[118:119], v[24:25], v[34:35]
	v_pk_fma_f32 v[26:27], v[114:115], v[32:33], v[26:27] op_sel_hi:[1,0,1]
	v_pk_fma_f32 v[24:25], v[110:111], v[32:33], v[24:25] op_sel_hi:[1,0,1]
	global_store_dwordx4 v[28:29], v[24:27], off sc0 sc1
	global_load_dwordx4 v[28:31], v[30:31], off
	s_nop 0
	global_load_ushort v85, v[126:127], off offset:440
	v_lshl_add_u64 v[32:33], v[148:149], 0, v[86:87]
	v_lshl_add_u64 v[34:35], v[146:147], 0, v[88:89]
	s_waitcnt vmcnt(1)
; __device__ __forceinline__ float row_sum16(float x) { x = dpp_add<0xB1>(x); x = dpp_add<0x4E>(x); x = dpp_add<0x124>(x); x = dpp_add<0x128>(x); return x; }
; __device__ __forceinline__ void rwkv_sample_task(const Params& p, int s, int h) {
;     ...
; #pragma unroll
;     for (int g = 0; g < 16; ++g) {
;         const int vrow = g * 4 + rr;
;         const float vv = (float)ob[192 + vrow];
;         f32x4 S = *(const f32x4*)(S0 + (size_t)vrow * 64 + cg_ * 4);
;         float sa = S[0] * a4[0] + S[1] * a4[1] + S[2] * a4[2] + S[3] * a4[3];
;         sa = row_sum16(sa);
;         S = S * d4 + sa * b4 + vv * k4;
;         float y = S[0] * r4[0] + S[1] * r4[1] + S[2] * r4[2] + S[3] * r4[3];
;         y = row_sum16(y) + rk * vv;
;         *(f32x4*)(So + (size_t)vrow * 64 + cg_ * 4) = S;
;         ysel = (cg_ == g) ? y : ysel;
;     }
	v_pk_mul_f32 v[38:39], v[28:29], v[122:123]
	v_pk_mul_f32 v[40:41], v[30:31], v[124:125]
	v_add_f32_e32 v37, v38, v39
	v_add_f32_e32 v37, v40, v37
	v_add_f32_e32 v37, v41, v37
	s_waitcnt vmcnt(0)
	v_cvt_f32_f16_e32 v36, v85
	v_add_f32_dpp v37, v37, v37 quad_perm:[1,0,3,2] row_mask:0xf bank_mask:0xf bound_ctrl:1
	s_nop 1
	v_add_f32_dpp v37, v37, v37 quad_perm:[2,3,0,1] row_mask:0xf bank_mask:0xf bound_ctrl:1
	s_nop 1
	v_add_f32_dpp v37, v37, v37 row_ror:4 row_mask:0xf bank_mask:0xf bound_ctrl:1
	s_nop 1
	v_add_f32_dpp v38, v37, v37 row_ror:8 row_mask:0xf bank_mask:0xf bound_ctrl:1
	v_pk_mul_f32 v[40:41], v[116:117], v[38:39] op_sel_hi:[1,0]
	v_pk_mul_f32 v[38:39], v[112:113], v[38:39] op_sel_hi:[1,0]
	v_pk_fma_f32 v[30:31], v[120:121], v[30:31], v[40:41]
	v_pk_fma_f32 v[28:29], v[118:119], v[28:29], v[38:39]
	v_pk_fma_f32 v[30:31], v[114:115], v[36:37], v[30:31] op_sel_hi:[1,0,1]
	v_pk_fma_f32 v[28:29], v[110:111], v[36:37], v[28:29] op_sel_hi:[1,0,1]
	global_store_dwordx4 v[32:33], v[28:31], off sc0 sc1
	global_load_dwordx4 v[32:35], v[34:35], off
	s_nop 0
	global_load_ushort v87, v[126:127], off offset:448
	v_lshl_add_u64 v[36:37], v[148:149], 0, v[88:89]
	v_lshl_add_u64 v[38:39], v[146:147], 0, v[90:91]
	s_waitcnt vmcnt(1)
	v_pk_mul_f32 v[42:43], v[32:33], v[122:123]
	v_pk_mul_f32 v[44:45], v[34:35], v[124:125]
	v_add_f32_e32 v41, v42, v43
	v_add_f32_e32 v41, v44, v41
	v_add_f32_e32 v41, v45, v41
	s_waitcnt vmcnt(0)
	v_cvt_f32_f16_e32 v40, v87
	v_add_f32_dpp v41, v41, v41 quad_perm:[1,0,3,2] row_mask:0xf bank_mask:0xf bound_ctrl:1
	s_nop 1
	v_add_f32_dpp v41, v41, v41 quad_perm:[2,3,0,1] row_mask:0xf bank_mask:0xf bound_ctrl:1
	s_nop 1
	v_add_f32_dpp v41, v41, v41 row_ror:4 row_mask:0xf bank_mask:0xf bound_ctrl:1
	s_nop 1
	v_add_f32_dpp v42, v41, v41 row_ror:8 row_mask:0xf bank_mask:0xf bound_ctrl:1
	v_pk_mul_f32 v[44:45], v[116:117], v[42:43] op_sel_hi:[1,0]
	v_pk_mul_f32 v[42:43], v[112:113], v[42:43] op_sel_hi:[1,0]
	v_pk_fma_f32 v[34:35], v[120:121], v[34:35], v[44:45]
	v_pk_fma_f32 v[32:33], v[118:119], v[32:33], v[42:43]
	v_pk_fma_f32 v[34:35], v[114:115], v[40:41], v[34:35] op_sel_hi:[1,0,1]
	v_pk_fma_f32 v[32:33], v[110:111], v[40:41], v[32:33] op_sel_hi:[1,0,1]
	global_store_dwordx4 v[36:37], v[32:35], off sc0 sc1
	global_load_dwordx4 v[36:39], v[38:39], off
	s_nop 0
	global_load_ushort v89, v[126:127], off offset:456
	v_lshl_add_u64 v[40:41], v[148:149], 0, v[90:91]
	v_lshl_add_u64 v[42:43], v[146:147], 0, v[92:93]
	s_waitcnt vmcnt(1)
	v_pk_mul_f32 v[46:47], v[36:37], v[122:123]
	v_pk_mul_f32 v[48:49], v[38:39], v[124:125]
	v_add_f32_e32 v45, v46, v47
	v_add_f32_e32 v45, v48, v45
	v_add_f32_e32 v45, v49, v45
	s_waitcnt vmcnt(0)
	v_cvt_f32_f16_e32 v44, v89
	v_add_f32_dpp v45, v45, v45 quad_perm:[1,0,3,2] row_mask:0xf bank_mask:0xf bound_ctrl:1
	s_nop 1
	v_add_f32_dpp v45, v45, v45 quad_perm:[2,3,0,1] row_mask:0xf bank_mask:0xf bound_ctrl:1
	s_nop 1
	v_add_f32_dpp v45, v45, v45 row_ror:4 row_mask:0xf bank_mask:0xf bound_ctrl:1
	s_nop 1
	v_add_f32_dpp v46, v45, v45 row_ror:8 row_mask:0xf bank_mask:0xf bound_ctrl:1
	v_pk_mul_f32 v[48:49], v[116:117], v[46:47] op_sel_hi:[1,0]
	v_pk_mul_f32 v[46:47], v[112:113], v[46:47] op_sel_hi:[1,0]
	v_pk_fma_f32 v[38:39], v[120:121], v[38:39], v[48:49]
	v_pk_fma_f32 v[36:37], v[118:119], v[36:37], v[46:47]
	v_pk_fma_f32 v[38:39], v[114:115], v[44:45], v[38:39] op_sel_hi:[1,0,1]
	v_pk_fma_f32 v[36:37], v[110:111], v[44:45], v[36:37] op_sel_hi:[1,0,1]
	global_store_dwordx4 v[40:41], v[36:39], off sc0 sc1
	global_load_dwordx4 v[40:43], v[42:43], off
	s_nop 0
	global_load_ushort v91, v[126:127], off offset:464
	v_lshl_add_u64 v[44:45], v[148:149], 0, v[92:93]
	v_lshl_add_u64 v[46:47], v[146:147], 0, v[94:95]
	s_waitcnt vmcnt(1)
	v_pk_mul_f32 v[50:51], v[40:41], v[122:123]
	v_pk_mul_f32 v[152:153], v[42:43], v[124:125]
	v_add_f32_e32 v49, v50, v51
	v_add_f32_e32 v49, v152, v49
	v_add_f32_e32 v49, v153, v49
	s_waitcnt vmcnt(0)
	v_cvt_f32_f16_e32 v48, v91
	v_add_f32_dpp v49, v49, v49 quad_perm:[1,0,3,2] row_mask:0xf bank_mask:0xf bound_ctrl:1
	s_nop 1
	v_add_f32_dpp v49, v49, v49 quad_perm:[2,3,0,1] row_mask:0xf bank_mask:0xf bound_ctrl:1
	s_nop 1
	v_add_f32_dpp v49, v49, v49 row_ror:4 row_mask:0xf bank_mask:0xf bound_ctrl:1
	s_nop 1
	v_add_f32_dpp v50, v49, v49 row_ror:8 row_mask:0xf bank_mask:0xf bound_ctrl:1
	v_pk_mul_f32 v[152:153], v[116:117], v[50:51] op_sel_hi:[1,0]
	v_pk_mul_f32 v[50:51], v[112:113], v[50:51] op_sel_hi:[1,0]
	v_pk_fma_f32 v[42:43], v[120:121], v[42:43], v[152:153]
	v_pk_fma_f32 v[40:41], v[118:119], v[40:41], v[50:51]
	v_pk_fma_f32 v[42:43], v[114:115], v[48:49], v[42:43] op_sel_hi:[1,0,1]
	v_pk_fma_f32 v[40:41], v[110:111], v[48:49], v[40:41] op_sel_hi:[1,0,1]
	global_store_dwordx4 v[44:45], v[40:43], off sc0 sc1
	global_load_dwordx4 v[44:47], v[46:47], off
	s_nop 0
	global_load_ushort v93, v[126:127], off offset:472
	v_lshl_add_u64 v[48:49], v[148:149], 0, v[94:95]
	v_lshl_add_u64 v[50:51], v[146:147], 0, v[96:97]
	s_waitcnt vmcnt(1)
	v_pk_mul_f32 v[154:155], v[44:45], v[122:123]
	v_pk_mul_f32 v[156:157], v[46:47], v[124:125]
	v_add_f32_e32 v95, v154, v155
	v_add_f32_e32 v95, v156, v95
	v_add_f32_e32 v95, v157, v95
	s_waitcnt vmcnt(0)
; __device__ __forceinline__ float row_sum16(float x) { x = dpp_add<0xB1>(x); x = dpp_add<0x4E>(x); x = dpp_add<0x124>(x); x = dpp_add<0x128>(x); return x; }
; __device__ __forceinline__ void rwkv_sample_task(const Params& p, int s, int h) {
;     ...
; #pragma unroll
;     for (int g = 0; g < 16; ++g) {
;         const int vrow = g * 4 + rr;
;         const float vv = (float)ob[192 + vrow];
;         f32x4 S = *(const f32x4*)(S0 + (size_t)vrow * 64 + cg_ * 4);
;         float sa = S[0] * a4[0] + S[1] * a4[1] + S[2] * a4[2] + S[3] * a4[3];
;         sa = row_sum16(sa);
;         S = S * d4 + sa * b4 + vv * k4;
;         float y = S[0] * r4[0] + S[1] * r4[1] + S[2] * r4[2] + S[3] * r4[3];
;         y = row_sum16(y) + rk * vv;
;         *(f32x4*)(So + (size_t)vrow * 64 + cg_ * 4) = S;
;         ysel = (cg_ == g) ? y : ysel;
;     }
	v_cvt_f32_f16_e32 v152, v93
	v_add_f32_dpp v95, v95, v95 quad_perm:[1,0,3,2] row_mask:0xf bank_mask:0xf bound_ctrl:1
	s_nop 1
	v_add_f32_dpp v95, v95, v95 quad_perm:[2,3,0,1] row_mask:0xf bank_mask:0xf bound_ctrl:1
	s_nop 1
	v_add_f32_dpp v95, v95, v95 row_ror:4 row_mask:0xf bank_mask:0xf bound_ctrl:1
	s_nop 1
	v_add_f32_dpp v154, v95, v95 row_ror:8 row_mask:0xf bank_mask:0xf bound_ctrl:1
	v_pk_mul_f32 v[156:157], v[116:117], v[154:155] op_sel_hi:[1,0]
	v_pk_mul_f32 v[154:155], v[112:113], v[154:155] op_sel_hi:[1,0]
	v_pk_fma_f32 v[46:47], v[120:121], v[46:47], v[156:157]
	v_pk_fma_f32 v[44:45], v[118:119], v[44:45], v[154:155]
	v_pk_fma_f32 v[46:47], v[114:115], v[152:153], v[46:47] op_sel_hi:[1,0,1]
	v_pk_fma_f32 v[44:45], v[110:111], v[152:153], v[44:45] op_sel_hi:[1,0,1]
	global_store_dwordx4 v[48:49], v[44:47], off sc0 sc1
	global_load_dwordx4 v[48:51], v[50:51], off
	s_nop 0
	global_load_ushort v95, v[126:127], off offset:480
	v_lshl_add_u64 v[152:153], v[148:149], 0, v[96:97]
	v_lshl_add_u64 v[154:155], v[146:147], 0, v[98:99]
	s_waitcnt vmcnt(1)
	v_pk_mul_f32 v[158:159], v[48:49], v[122:123]
	v_pk_mul_f32 v[160:161], v[50:51], v[124:125]
	v_add_f32_e32 v97, v158, v159
	v_add_f32_e32 v97, v160, v97
	v_add_f32_e32 v97, v161, v97
	s_waitcnt vmcnt(0)
	v_cvt_f32_f16_e32 v156, v95
	v_add_f32_dpp v97, v97, v97 quad_perm:[1,0,3,2] row_mask:0xf bank_mask:0xf bound_ctrl:1
	s_nop 1
	v_add_f32_dpp v97, v97, v97 quad_perm:[2,3,0,1] row_mask:0xf bank_mask:0xf bound_ctrl:1
	s_nop 1
	v_add_f32_dpp v97, v97, v97 row_ror:4 row_mask:0xf bank_mask:0xf bound_ctrl:1
	s_nop 1
	v_add_f32_dpp v158, v97, v97 row_ror:8 row_mask:0xf bank_mask:0xf bound_ctrl:1
	v_pk_mul_f32 v[160:161], v[116:117], v[158:159] op_sel_hi:[1,0]
	v_pk_mul_f32 v[158:159], v[112:113], v[158:159] op_sel_hi:[1,0]
	v_pk_fma_f32 v[50:51], v[120:121], v[50:51], v[160:161]
	v_pk_fma_f32 v[48:49], v[118:119], v[48:49], v[158:159]
	v_pk_fma_f32 v[50:51], v[114:115], v[156:157], v[50:51] op_sel_hi:[1,0,1]
	v_pk_fma_f32 v[48:49], v[110:111], v[156:157], v[48:49] op_sel_hi:[1,0,1]
	global_store_dwordx4 v[152:153], v[48:51], off sc0 sc1
	global_load_dwordx4 v[152:155], v[154:155], off
	s_nop 0
	global_load_ushort v97, v[126:127], off offset:488
	v_lshl_add_u64 v[158:159], v[148:149], 0, v[98:99]
	v_cvt_f32_f16_sdwa v99, v108 dst_sel:DWORD dst_unused:UNUSED_PAD src0_sel:WORD_1
	v_lshl_add_u64 v[160:161], v[146:147], 0, v[100:101]
	v_lshl_add_u64 v[146:147], v[146:147], 0, v[104:105]
	v_lshl_add_u64 v[148:149], v[148:149], 0, v[104:105]
	v_mul_f32_e32 v1, v1, v99
	v_fma_mix_f32 v0, v0, v108, v1 op_sel_hi:[0,1,0]
	v_mul_f32_e32 v1, v9, v99
	v_fma_mix_f32 v0, v2, v109, v0 op_sel_hi:[0,1,0]
	v_fma_mix_f32 v1, v8, v108, v1 op_sel_hi:[0,1,0]
	v_fma_mix_f32 v0, v3, v109, v0 op_sel:[0,1,0] op_sel_hi:[0,1,0]
	v_fma_mix_f32 v1, v10, v109, v1 op_sel_hi:[0,1,0]
	v_fma_mix_f32 v1, v11, v109, v1 op_sel:[0,1,0] op_sel_hi:[0,1,0]
	v_add_f32_dpp v0, v0, v0 quad_perm:[1,0,3,2] row_mask:0xf bank_mask:0xf bound_ctrl:1
	v_mul_f32_e32 v5, v5, v99
	v_add_f32_dpp v1, v1, v1 quad_perm:[1,0,3,2] row_mask:0xf bank_mask:0xf bound_ctrl:1
	v_add_f32_dpp v0, v0, v0 quad_perm:[2,3,0,1] row_mask:0xf bank_mask:0xf bound_ctrl:1
	v_fma_mix_f32 v4, v4, v108, v5 op_sel_hi:[0,1,0]
	v_add_f32_dpp v1, v1, v1 quad_perm:[2,3,0,1] row_mask:0xf bank_mask:0xf bound_ctrl:1
	v_add_f32_dpp v0, v0, v0 row_ror:4 row_mask:0xf bank_mask:0xf bound_ctrl:1
	v_mul_f32_e32 v5, v13, v99
	v_add_f32_dpp v1, v1, v1 row_ror:4 row_mask:0xf bank_mask:0xf bound_ctrl:1
	v_add_f32_dpp v0, v0, v0 row_ror:8 row_mask:0xf bank_mask:0xf bound_ctrl:1
	v_fma_mix_f32 v0, v71, v73, v0 op_sel_hi:[0,1,0]
	v_add_f32_dpp v1, v1, v1 row_ror:8 row_mask:0xf bank_mask:0xf bound_ctrl:1
	v_cndmask_b32_e32 v0, 0, v0, vcc
	v_fma_mix_f32 v1, v71, v79, v1 op_sel_hi:[0,1,0]
	v_cndmask_b32_e64 v73, v0, v1, s[4:5]
	v_mul_f32_e32 v0, v17, v99
	v_fma_mix_f32 v0, v16, v108, v0 op_sel_hi:[0,1,0]
	v_fma_mix_f32 v0, v18, v109, v0 op_sel_hi:[0,1,0]
	v_fma_mix_f32 v16, v19, v109, v0 op_sel:[0,1,0] op_sel_hi:[0,1,0]
	v_fma_mix_f32 v4, v6, v109, v4 op_sel_hi:[0,1,0]
	v_fma_mix_f32 v5, v12, v108, v5 op_sel_hi:[0,1,0]
	v_add_f32_dpp v16, v16, v16 quad_perm:[1,0,3,2] row_mask:0xf bank_mask:0xf bound_ctrl:1
	v_fma_mix_f32 v4, v7, v109, v4 op_sel:[0,1,0] op_sel_hi:[0,1,0]
	v_fma_mix_f32 v5, v14, v109, v5 op_sel_hi:[0,1,0]
	v_add_f32_dpp v16, v16, v16 quad_perm:[2,3,0,1] row_mask:0xf bank_mask:0xf bound_ctrl:1
	v_add_f32_dpp v4, v4, v4 quad_perm:[1,0,3,2] row_mask:0xf bank_mask:0xf bound_ctrl:1
	v_fma_mix_f32 v5, v15, v109, v5 op_sel:[0,1,0] op_sel_hi:[0,1,0]
	v_add_f32_dpp v16, v16, v16 row_ror:4 row_mask:0xf bank_mask:0xf bound_ctrl:1
	v_add_f32_dpp v4, v4, v4 quad_perm:[2,3,0,1] row_mask:0xf bank_mask:0xf bound_ctrl:1
	v_add_f32_dpp v5, v5, v5 quad_perm:[1,0,3,2] row_mask:0xf bank_mask:0xf bound_ctrl:1
	v_add_f32_dpp v16, v16, v16 row_ror:8 row_mask:0xf bank_mask:0xf bound_ctrl:1
	v_add_f32_dpp v4, v4, v4 row_ror:4 row_mask:0xf bank_mask:0xf bound_ctrl:1
	v_add_f32_dpp v5, v5, v5 quad_perm:[2,3,0,1] row_mask:0xf bank_mask:0xf bound_ctrl:1
	v_fma_mix_f32 v16, v71, v75, v16 op_sel_hi:[0,1,0]
	v_add_f32_dpp v4, v4, v4 row_ror:8 row_mask:0xf bank_mask:0xf bound_ctrl:1
	v_add_f32_dpp v5, v5, v5 row_ror:4 row_mask:0xf bank_mask:0xf bound_ctrl:1
	v_cndmask_b32_e64 v16, v73, v16, s[6:7]
	v_fma_mix_f32 v4, v71, v77, v4 op_sel_hi:[0,1,0]
	v_add_f32_dpp v5, v5, v5 row_ror:8 row_mask:0xf bank_mask:0xf bound_ctrl:1
	v_cndmask_b32_e64 v4, v16, v4, s[8:9]
	v_fma_mix_f32 v5, v71, v81, v5 op_sel_hi:[0,1,0]
	v_cndmask_b32_e64 v4, v4, v5, s[10:11]
	v_mul_f32_e32 v5, v21, v99
	v_fma_mix_f32 v5, v20, v108, v5 op_sel_hi:[0,1,0]
	v_fma_mix_f32 v5, v22, v109, v5 op_sel_hi:[0,1,0]
	v_fma_mix_f32 v5, v23, v109, v5 op_sel:[0,1,0] op_sel_hi:[0,1,0]
	v_lshlrev_b64 v[156:157], 10, v[106:107]
	v_lshl_add_u64 v[156:157], v[64:65], 0, v[156:157]
	v_add_f32_dpp v5, v5, v5 quad_perm:[1,0,3,2] row_mask:0xf bank_mask:0xf bound_ctrl:1
	s_waitcnt vmcnt(1)
; __device__ __forceinline__ float row_sum16(float x) { x = dpp_add<0xB1>(x); x = dpp_add<0x4E>(x); x = dpp_add<0x124>(x); x = dpp_add<0x128>(x); return x; }
; __device__ __forceinline__ void rwkv_sample_task(const Params& p, int s, int h) {
;     ...
; #pragma unroll
;     for (int g = 0; g < 16; ++g) {
;         const int vrow = g * 4 + rr;
;         const float vv = (float)ob[192 + vrow];
;         f32x4 S = *(const f32x4*)(S0 + (size_t)vrow * 64 + cg_ * 4);
;         float sa = S[0] * a4[0] + S[1] * a4[1] + S[2] * a4[2] + S[3] * a4[3];
;         sa = row_sum16(sa);
;         S = S * d4 + sa * b4 + vv * k4;
;         float y = S[0] * r4[0] + S[1] * r4[1] + S[2] * r4[2] + S[3] * r4[3];
;         y = row_sum16(y) + rk * vv;
;         *(f32x4*)(So + (size_t)vrow * 64 + cg_ * 4) = S;
;         ysel = (cg_ == g) ? y : ysel;
;     }
	v_pk_mul_f32 v[2:3], v[152:153], v[122:123]
	v_pk_mul_f32 v[8:9], v[154:155], v[124:125]
	v_add_f32_e32 v1, v2, v3
	v_add_f32_e32 v1, v8, v1
	v_add_f32_e32 v1, v9, v1
	s_waitcnt vmcnt(0)
	v_cvt_f32_f16_e32 v0, v97
	v_add_f32_dpp v5, v5, v5 quad_perm:[2,3,0,1] row_mask:0xf bank_mask:0xf bound_ctrl:1
	v_add_f32_dpp v1, v1, v1 quad_perm:[1,0,3,2] row_mask:0xf bank_mask:0xf bound_ctrl:1
	s_nop 0
	v_add_f32_dpp v5, v5, v5 row_ror:4 row_mask:0xf bank_mask:0xf bound_ctrl:1
	v_add_f32_dpp v1, v1, v1 quad_perm:[2,3,0,1] row_mask:0xf bank_mask:0xf bound_ctrl:1
	s_nop 0
	v_add_f32_dpp v5, v5, v5 row_ror:8 row_mask:0xf bank_mask:0xf bound_ctrl:1
	v_add_f32_dpp v1, v1, v1 row_ror:4 row_mask:0xf bank_mask:0xf bound_ctrl:1
	v_fma_mix_f32 v5, v71, v145, v5 op_sel_hi:[0,1,0]
	v_cndmask_b32_e64 v4, v4, v5, s[12:13]
	v_add_f32_dpp v2, v1, v1 row_ror:8 row_mask:0xf bank_mask:0xf bound_ctrl:1
	v_pk_mul_f32 v[8:9], v[116:117], v[2:3] op_sel_hi:[1,0]
	v_pk_mul_f32 v[2:3], v[112:113], v[2:3] op_sel_hi:[1,0]
	v_mul_f32_e32 v5, v25, v99
	v_pk_fma_f32 v[10:11], v[118:119], v[152:153], v[2:3]
	v_pk_fma_f32 v[2:3], v[120:121], v[154:155], v[8:9]
	v_fma_mix_f32 v5, v24, v108, v5 op_sel_hi:[0,1,0]
	v_pk_fma_f32 v[2:3], v[114:115], v[0:1], v[2:3] op_sel_hi:[1,0,1]
	v_pk_fma_f32 v[0:1], v[110:111], v[0:1], v[10:11] op_sel_hi:[1,0,1]
	global_store_dwordx4 v[158:159], v[0:3], off sc0 sc1
	global_load_dwordx4 v[8:11], v[160:161], off
	global_load_ushort v17, v[126:127], off offset:496
	v_fma_mix_f32 v5, v26, v109, v5 op_sel_hi:[0,1,0]
	v_fma_mix_f32 v5, v27, v109, v5 op_sel:[0,1,0] op_sel_hi:[0,1,0]
	v_mul_f32_e32 v1, v1, v99
	v_fma_mix_f32 v0, v0, v108, v1 op_sel_hi:[0,1,0]
	v_add_f32_dpp v5, v5, v5 quad_perm:[1,0,3,2] row_mask:0xf bank_mask:0xf bound_ctrl:1
	v_fma_mix_f32 v0, v2, v109, v0 op_sel_hi:[0,1,0]
	v_fma_mix_f32 v0, v3, v109, v0 op_sel:[0,1,0] op_sel_hi:[0,1,0]
	v_add_f32_dpp v5, v5, v5 quad_perm:[2,3,0,1] row_mask:0xf bank_mask:0xf bound_ctrl:1
	s_waitcnt vmcnt(1)
	v_pk_mul_f32 v[6:7], v[8:9], v[122:123]
	v_add_f32_dpp v5, v5, v5 row_ror:4 row_mask:0xf bank_mask:0xf bound_ctrl:1
	v_pk_mul_f32 v[12:13], v[10:11], v[124:125]
	v_add_f32_dpp v0, v0, v0 quad_perm:[1,0,3,2] row_mask:0xf bank_mask:0xf bound_ctrl:1
	v_add_f32_dpp v5, v5, v5 row_ror:8 row_mask:0xf bank_mask:0xf bound_ctrl:1
	v_fma_mix_f32 v5, v71, v83, v5 op_sel_hi:[0,1,0]
	v_cndmask_b32_e64 v4, v4, v5, s[14:15]
	v_mul_f32_e32 v5, v29, v99
	v_fma_mix_f32 v5, v28, v108, v5 op_sel_hi:[0,1,0]
	v_fma_mix_f32 v5, v30, v109, v5 op_sel_hi:[0,1,0]
	v_fma_mix_f32 v5, v31, v109, v5 op_sel:[0,1,0] op_sel_hi:[0,1,0]
	v_add_f32_dpp v0, v0, v0 quad_perm:[2,3,0,1] row_mask:0xf bank_mask:0xf bound_ctrl:1
	s_nop 0
	v_add_f32_dpp v5, v5, v5 quad_perm:[1,0,3,2] row_mask:0xf bank_mask:0xf bound_ctrl:1
	v_add_f32_dpp v0, v0, v0 row_ror:4 row_mask:0xf bank_mask:0xf bound_ctrl:1
	s_nop 0
	v_add_f32_dpp v5, v5, v5 quad_perm:[2,3,0,1] row_mask:0xf bank_mask:0xf bound_ctrl:1
	v_add_f32_dpp v0, v0, v0 row_ror:8 row_mask:0xf bank_mask:0xf bound_ctrl:1
	v_fma_mix_f32 v0, v71, v97, v0 op_sel_hi:[0,1,0]
	v_add_f32_dpp v5, v5, v5 row_ror:4 row_mask:0xf bank_mask:0xf bound_ctrl:1
	s_nop 1
	v_add_f32_dpp v5, v5, v5 row_ror:8 row_mask:0xf bank_mask:0xf bound_ctrl:1
	v_fma_mix_f32 v5, v71, v85, v5 op_sel_hi:[0,1,0]
	v_cndmask_b32_e64 v14, v4, v5, s[16:17]
	v_add_f32_e32 v5, v6, v7
	v_add_f32_e32 v5, v12, v5
	v_mul_f32_e32 v4, v33, v99
	v_add_f32_e32 v5, v13, v5
	v_fma_mix_f32 v4, v32, v108, v4 op_sel_hi:[0,1,0]
	v_fma_mix_f32 v4, v34, v109, v4 op_sel_hi:[0,1,0]
	v_add_f32_dpp v5, v5, v5 quad_perm:[1,0,3,2] row_mask:0xf bank_mask:0xf bound_ctrl:1
	v_fma_mix_f32 v15, v35, v109, v4 op_sel:[0,1,0] op_sel_hi:[0,1,0]
	s_waitcnt vmcnt(0)
	v_cvt_f32_f16_e32 v4, v17
	v_add_f32_dpp v5, v5, v5 quad_perm:[2,3,0,1] row_mask:0xf bank_mask:0xf bound_ctrl:1
	s_nop 1
	v_add_f32_dpp v5, v5, v5 row_ror:4 row_mask:0xf bank_mask:0xf bound_ctrl:1
	s_nop 1
	v_add_f32_dpp v6, v5, v5 row_ror:8 row_mask:0xf bank_mask:0xf bound_ctrl:1
	v_pk_mul_f32 v[12:13], v[116:117], v[6:7] op_sel_hi:[1,0]
	v_pk_mul_f32 v[6:7], v[112:113], v[6:7] op_sel_hi:[1,0]
	s_nop 0
	v_pk_fma_f32 v[8:9], v[118:119], v[8:9], v[6:7]
	v_pk_fma_f32 v[6:7], v[120:121], v[10:11], v[12:13]
	v_add_f32_dpp v13, v15, v15 quad_perm:[1,0,3,2] row_mask:0xf bank_mask:0xf bound_ctrl:1
	v_pk_fma_f32 v[6:7], v[114:115], v[4:5], v[6:7] op_sel_hi:[1,0,1]
	v_pk_fma_f32 v[4:5], v[110:111], v[4:5], v[8:9] op_sel_hi:[1,0,1]
	global_store_dwordx4 v[162:163], v[4:7], off sc0 sc1
	global_load_dwordx4 v[8:11], v[146:147], off
	global_load_ushort v12, v[150:151], off offset:384
	v_add_f32_dpp v13, v13, v13 quad_perm:[2,3,0,1] row_mask:0xf bank_mask:0xf bound_ctrl:1
	v_mul_f32_e32 v1, v5, v99
	v_fma_mix_f32 v1, v4, v108, v1 op_sel_hi:[0,1,0]
	v_add_f32_dpp v13, v13, v13 row_ror:4 row_mask:0xf bank_mask:0xf bound_ctrl:1
	v_fma_mix_f32 v1, v6, v109, v1 op_sel_hi:[0,1,0]
	v_fma_mix_f32 v1, v7, v109, v1 op_sel:[0,1,0] op_sel_hi:[0,1,0]
	v_add_f32_dpp v13, v13, v13 row_ror:8 row_mask:0xf bank_mask:0xf bound_ctrl:1
	v_fma_mix_f32 v13, v71, v87, v13 op_sel_hi:[0,1,0]
	v_cndmask_b32_e64 v13, v14, v13, s[18:19]
	v_mul_f32_e32 v14, v37, v99
	v_fma_mix_f32 v14, v36, v108, v14 op_sel_hi:[0,1,0]
	v_fma_mix_f32 v14, v38, v109, v14 op_sel_hi:[0,1,0]
	v_fma_mix_f32 v14, v39, v109, v14 op_sel:[0,1,0] op_sel_hi:[0,1,0]
	v_add_f32_dpp v1, v1, v1 quad_perm:[1,0,3,2] row_mask:0xf bank_mask:0xf bound_ctrl:1
	s_waitcnt vmcnt(1)
; __device__ __forceinline__ float row_sum16(float x) { x = dpp_add<0xB1>(x); x = dpp_add<0x4E>(x); x = dpp_add<0x124>(x); x = dpp_add<0x128>(x); return x; }
; __device__ __forceinline__ void rwkv_sample_task(const Params& p, int s, int h) {
;     ...
; #pragma unroll
;     for (int g = 0; g < 16; ++g) {
;         const int vrow = g * 4 + rr;
;         const float vv = (float)ob[192 + vrow];
;         f32x4 S = *(const f32x4*)(S0 + (size_t)vrow * 64 + cg_ * 4);
;         float sa = S[0] * a4[0] + S[1] * a4[1] + S[2] * a4[2] + S[3] * a4[3];
;         sa = row_sum16(sa);
;         S = S * d4 + sa * b4 + vv * k4;
;         float y = S[0] * r4[0] + S[1] * r4[1] + S[2] * r4[2] + S[3] * r4[3];
;         y = row_sum16(y) + rk * vv;
;         *(f32x4*)(So + (size_t)vrow * 64 + cg_ * 4) = S;
;         ysel = (cg_ == g) ? y : ysel;
;     }
;     const int vr = cg_ * 4 + rr, col = h * 64 + vr;
;     const float mu = wave_sum(ysel) * (1.f / 64.f);
;     const float dlt = ysel - mu;
;     const float rstd = rsqrtf(wave_sum(dlt * dlt) * (1.f / 64.f) + GN_EPS);
;     const float gte = (float)((const h16*)((unsigned char*)p.out + OUTB_G16))[(size_t)row * 512 + col];
;     ((h16*)((unsigned char*)p.out + OUTB_MIX16))[(size_t)row * D + 512 + col] = (h16)((dlt * rstd * p.in[24][col] + p.in[25][col]) * gte);
	v_pk_mul_f32 v[2:3], v[8:9], v[122:123]
	v_add_f32_dpp v14, v14, v14 quad_perm:[1,0,3,2] row_mask:0xf bank_mask:0xf bound_ctrl:1
	v_add_f32_dpp v1, v1, v1 quad_perm:[2,3,0,1] row_mask:0xf bank_mask:0xf bound_ctrl:1
	v_pk_mul_f32 v[4:5], v[10:11], v[124:125]
	v_add_f32_dpp v14, v14, v14 quad_perm:[2,3,0,1] row_mask:0xf bank_mask:0xf bound_ctrl:1
	v_add_f32_dpp v1, v1, v1 row_ror:4 row_mask:0xf bank_mask:0xf bound_ctrl:1
	s_nop 0
	v_add_f32_dpp v14, v14, v14 row_ror:4 row_mask:0xf bank_mask:0xf bound_ctrl:1
	v_add_f32_dpp v1, v1, v1 row_ror:8 row_mask:0xf bank_mask:0xf bound_ctrl:1
	v_fma_mix_f32 v1, v71, v17, v1 op_sel_hi:[0,1,0]
	v_add_f32_dpp v14, v14, v14 row_ror:8 row_mask:0xf bank_mask:0xf bound_ctrl:1
	v_fma_mix_f32 v14, v71, v89, v14 op_sel_hi:[0,1,0]
	v_cndmask_b32_e64 v13, v13, v14, s[20:21]
	v_mul_f32_e32 v14, v41, v99
	v_fma_mix_f32 v14, v40, v108, v14 op_sel_hi:[0,1,0]
	v_fma_mix_f32 v14, v42, v109, v14 op_sel_hi:[0,1,0]
	v_fma_mix_f32 v14, v43, v109, v14 op_sel:[0,1,0] op_sel_hi:[0,1,0]
	s_nop 1
	v_add_f32_dpp v14, v14, v14 quad_perm:[1,0,3,2] row_mask:0xf bank_mask:0xf bound_ctrl:1
	s_nop 1
	v_add_f32_dpp v14, v14, v14 quad_perm:[2,3,0,1] row_mask:0xf bank_mask:0xf bound_ctrl:1
	s_nop 1
	v_add_f32_dpp v14, v14, v14 row_ror:4 row_mask:0xf bank_mask:0xf bound_ctrl:1
	s_nop 1
	v_add_f32_dpp v14, v14, v14 row_ror:8 row_mask:0xf bank_mask:0xf bound_ctrl:1
	v_fma_mix_f32 v14, v71, v91, v14 op_sel_hi:[0,1,0]
	v_cndmask_b32_e64 v13, v13, v14, s[22:23]
	v_mul_f32_e32 v14, v45, v99
	v_fma_mix_f32 v14, v44, v108, v14 op_sel_hi:[0,1,0]
	v_fma_mix_f32 v14, v46, v109, v14 op_sel_hi:[0,1,0]
	v_fma_mix_f32 v14, v47, v109, v14 op_sel:[0,1,0] op_sel_hi:[0,1,0]
	s_nop 1
	v_add_f32_dpp v14, v14, v14 quad_perm:[1,0,3,2] row_mask:0xf bank_mask:0xf bound_ctrl:1
	s_nop 1
	v_add_f32_dpp v14, v14, v14 quad_perm:[2,3,0,1] row_mask:0xf bank_mask:0xf bound_ctrl:1
	s_nop 1
	v_add_f32_dpp v14, v14, v14 row_ror:4 row_mask:0xf bank_mask:0xf bound_ctrl:1
	s_nop 1
	v_add_f32_dpp v14, v14, v14 row_ror:8 row_mask:0xf bank_mask:0xf bound_ctrl:1
	v_fma_mix_f32 v14, v71, v93, v14 op_sel_hi:[0,1,0]
	v_cndmask_b32_e64 v13, v13, v14, s[24:25]
	v_mul_f32_e32 v14, v49, v99
	v_fma_mix_f32 v14, v48, v108, v14 op_sel_hi:[0,1,0]
	v_fma_mix_f32 v14, v50, v109, v14 op_sel_hi:[0,1,0]
	v_fma_mix_f32 v14, v51, v109, v14 op_sel:[0,1,0] op_sel_hi:[0,1,0]
	s_nop 1
	v_add_f32_dpp v14, v14, v14 quad_perm:[1,0,3,2] row_mask:0xf bank_mask:0xf bound_ctrl:1
	s_nop 1
	v_add_f32_dpp v14, v14, v14 quad_perm:[2,3,0,1] row_mask:0xf bank_mask:0xf bound_ctrl:1
	s_nop 1
	v_add_f32_dpp v14, v14, v14 row_ror:4 row_mask:0xf bank_mask:0xf bound_ctrl:1
	s_nop 1
	v_add_f32_dpp v14, v14, v14 row_ror:8 row_mask:0xf bank_mask:0xf bound_ctrl:1
	v_fma_mix_f32 v14, v71, v95, v14 op_sel_hi:[0,1,0]
	v_cndmask_b32_e64 v13, v13, v14, s[26:27]
	v_cndmask_b32_e64 v0, v13, v0, s[28:29]
	v_cndmask_b32_e64 v13, v0, v1, s[30:31]
	v_add_f32_e32 v1, v2, v3
	v_add_f32_e32 v1, v4, v1
	v_add_f32_e32 v1, v5, v1
	s_waitcnt vmcnt(0)
	v_cvt_f32_f16_e32 v0, v12
	v_add_f32_dpp v1, v1, v1 quad_perm:[1,0,3,2] row_mask:0xf bank_mask:0xf bound_ctrl:1
	s_nop 1
	v_add_f32_dpp v1, v1, v1 quad_perm:[2,3,0,1] row_mask:0xf bank_mask:0xf bound_ctrl:1
	s_nop 1
	v_add_f32_dpp v1, v1, v1 row_ror:4 row_mask:0xf bank_mask:0xf bound_ctrl:1
	s_nop 1
	v_add_f32_dpp v2, v1, v1 row_ror:8 row_mask:0xf bank_mask:0xf bound_ctrl:1
	v_pk_mul_f32 v[4:5], v[116:117], v[2:3] op_sel_hi:[1,0]
	v_pk_mul_f32 v[2:3], v[112:113], v[2:3] op_sel_hi:[1,0]
	s_nop 0
	v_pk_fma_f32 v[6:7], v[118:119], v[8:9], v[2:3]
	v_pk_fma_f32 v[2:3], v[120:121], v[10:11], v[4:5]
	s_nop 0
	v_pk_fma_f32 v[2:3], v[114:115], v[0:1], v[2:3] op_sel_hi:[1,0,1]
	v_pk_fma_f32 v[0:1], v[110:111], v[0:1], v[6:7] op_sel_hi:[1,0,1]
	global_store_dwordx4 v[148:149], v[0:3], off sc0 sc1
	v_mul_f32_e32 v4, v1, v99
	s_nop 0
	v_fma_mix_f32 v0, v0, v108, v4 op_sel_hi:[0,1,0]
	v_fma_mix_f32 v0, v2, v109, v0 op_sel_hi:[0,1,0]
	v_fma_mix_f32 v0, v3, v109, v0 op_sel:[0,1,0] op_sel_hi:[0,1,0]
	global_load_ushort v3, v[156:157], off
	global_load_dword v4, v[66:67], off
	global_load_dword v5, v[68:69], off
	v_add_f32_dpp v0, v0, v0 quad_perm:[1,0,3,2] row_mask:0xf bank_mask:0xf bound_ctrl:1
	s_nop 1
	v_add_f32_dpp v0, v0, v0 quad_perm:[2,3,0,1] row_mask:0xf bank_mask:0xf bound_ctrl:1
	s_nop 1
	v_add_f32_dpp v0, v0, v0 row_ror:4 row_mask:0xf bank_mask:0xf bound_ctrl:1
	s_nop 1
	v_add_f32_dpp v0, v0, v0 row_ror:8 row_mask:0xf bank_mask:0xf bound_ctrl:1
	v_fma_mix_f32 v0, v71, v12, v0 op_sel_hi:[0,1,0]
	v_cndmask_b32_e64 v2, v13, v0, s[34:35]
	ds_bpermute_b32 v0, v55, v2
	s_waitcnt lgkmcnt(0)
	v_add_f32_e32 v0, v2, v0
	ds_bpermute_b32 v1, v57, v0
	s_waitcnt lgkmcnt(0)
	v_add_f32_e32 v0, v0, v1
	ds_bpermute_b32 v1, v129, v0
	s_waitcnt lgkmcnt(0)
	v_add_f32_e32 v0, v0, v1
	ds_bpermute_b32 v1, v135, v0
	s_waitcnt lgkmcnt(0)
	v_add_f32_e32 v0, v0, v1
	ds_bpermute_b32 v1, v137, v0
	s_waitcnt lgkmcnt(0)
	v_add_f32_e32 v0, v0, v1
	ds_bpermute_b32 v1, v139, v0
	s_waitcnt lgkmcnt(0)
	v_add_f32_e32 v0, v0, v1
	v_fmac_f32_e32 v2, 0xbc800000, v0
	v_mul_f32_e32 v0, v2, v2
	ds_bpermute_b32 v0, v55, v0
	s_waitcnt lgkmcnt(0)
	v_fmac_f32_e32 v0, v2, v2
	ds_bpermute_b32 v1, v57, v0
	s_waitcnt lgkmcnt(0)
	v_add_f32_e32 v0, v0, v1
	ds_bpermute_b32 v1, v129, v0
	s_waitcnt lgkmcnt(0)
	v_add_f32_e32 v0, v0, v1
	ds_bpermute_b32 v1, v135, v0
	s_waitcnt lgkmcnt(0)
	v_add_f32_e32 v0, v0, v1
	ds_bpermute_b32 v1, v137, v0
	s_waitcnt lgkmcnt(0)
	v_add_f32_e32 v0, v0, v1
	ds_bpermute_b32 v1, v139, v0
	s_waitcnt lgkmcnt(0)
	v_add_f32_e32 v0, v0, v1
	v_fmamk_f32 v0, v0, 0x3c800000, v141
	v_mul_f32_e32 v1, 0x4b800000, v0
	v_cmp_gt_f32_e64 s[36:37], s44, v0
	s_nop 1
	v_cndmask_b32_e64 v0, v0, v1, s[36:37]
	v_rsq_f32_e32 v6, v0
	v_lshlrev_b64 v[0:1], 11, v[106:107]
	v_lshl_add_u64 v[0:1], v[62:63], 0, v[0:1]
	v_mul_f32_e32 v7, 0x45800000, v6
	v_cndmask_b32_e64 v6, v6, v7, s[36:37]
	v_mul_f32_e32 v2, v2, v6
	s_waitcnt vmcnt(0)
	v_fmac_f32_e32 v5, v4, v2
	v_fma_mixlo_f16 v2, v5, v3, 0 op_sel_hi:[0,1,0]
	global_store_short v[0:1], v2, off offset:1024
	s_andn2_b64 exec, exec, s[42:43]
	s_cbranch_execnz .LBB0_362

; #define PG8_STAGE(bufoff, gbase, voff) do { _Pragma("unroll") for (int _i = 0; _i < 2; ++_i) \
;         __builtin_amdgcn_global_load_lds((const unsigned*)((const char*)(gbase) + (voff)[_i]), (LAS unsigned*)(lds + (bufoff) + ldsw + _i * 8192), 16, 0, 0); } while (0)
; #define PG8_LDA(dst, b, h) do { _Pragma("unroll") for (int m = 0; m < 4; ++m) _Pragma("unroll") for (int k = 0; k < 2; ++k) dst[m][k] = *(const LAS h16x8*)(lds + PG8_SA(b, h) + aoff + m * 2048 + k * 1024); } while (0)
; #define PG8_LDB(dst, b, h) do { _Pragma("unroll") for (int n = 0; n < 2; ++n) _Pragma("unroll") for (int k = 0; k < 2; ++k) dst[n][k] = *(const LAS h16x8*)(lds + PG8_SB(b, h) + boff + n * 2048 + k * 1024); } while (0)
; #define PG8_MMA(ai, bj, At, Bt) do { __builtin_amdgcn_s_setprio(1); _Pragma("unroll") for (int m = 0; m < 4; ++m) _Pragma("unroll") for (int n = 0; n < 2; ++n) _Pragma("unroll") for (int k = 0; k < 2; ++k) \
;         acc[ai][bj][m][n] = __builtin_amdgcn_mfma_f32_16x16x32_f16(Bt[n][k], At[m][k], acc[ai][bj][m][n], 0, 0, 0); __builtin_amdgcn_s_setprio(0); } while (0)
; #define PG8_WAIT_L(n) asm volatile("s_waitcnt lgkmcnt(" #n ")" ::: "memory")
; #define PG8_BAR __builtin_amdgcn_s_barrier()
; #define PG8_SCHED __builtin_amdgcn_sched_barrier(0)
; template <class Epi>
; __device__ __forceinline__ void gemm_phase(LAS unsigned char* lds, const Gemm g, const StaticOrder& S, const Epi& E) {
;     ...
;             PG8_LDB(B0, 0, 0); PG8_SCHED; PG8_LDA(At, 0, 0); PG8_STAGE(PG8_SA(1, 1), a1 + hstep, voffA);
;             PG8_WAIT_L(8); PG8_BAR; PG8_WAIT_L(0); PG8_MMA(0, 0, At, B0); PG8_BAR; PG8_SCHED;
;             PG8_LDB(B1, 0, 1); PG8_STAGE(PG8_SB(0, 0), b2, voffB);
;             PG8_BAR; PG8_WAIT_L(0); PG8_MMA(0, 1, At, B1); PG8_BAR;
;             PG8_LDA(At, 0, 1); PG8_STAGE(PG8_SA(0, 0), a2, voffA);
;             PG8_BAR; PG8_WAIT_L(0); PG8_MMA(1, 0, At, B0); PG8_BAR; PG8_SCHED;
.LBB0_422:
	ds_read_b128 v[162:165], v145
	ds_read_b128 v[168:171], v145 offset:1024
	ds_read_b128 v[172:175], v145 offset:2048
	ds_read_b128 v[176:179], v145 offset:3072
	s_add_u32 s28, s26, 0xfffc0080
	s_addc_u32 s29, s27, -1
	s_cmp_eq_u32 s50, 12
	s_cselect_b32 s31, s17, s29
	s_cselect_b32 s30, s23, s28
	s_cselect_b32 s29, s13, s49
	s_cselect_b32 s28, s47, s48
	v_lshl_add_u64 v[212:213], s[26:27], 0, v[154:155]
	s_add_i32 m0, s25, 0xc000
	ds_read_b128 v[180:183], v147
	ds_read_b128 v[184:187], v147 offset:1024
	ds_read_b128 v[188:191], v147 offset:2048
	ds_read_b128 v[192:195], v147 offset:3072
	ds_read_b128 v[196:199], v147 offset:4096
	ds_read_b128 v[200:203], v147 offset:5120
	ds_read_b128 v[204:207], v147 offset:6144
	ds_read_b128 v[208:211], v147 offset:7168
	global_load_lds_dwordx4 v[212:213], off
	v_lshl_add_u64 v[212:213], s[26:27], 0, v[156:157]
	s_add_i32 m0, s25, 0xe000
	s_nop 0
	global_load_lds_dwordx4 v[212:213], off
	s_waitcnt lgkmcnt(8)
	s_barrier
	s_waitcnt lgkmcnt(0)
	s_setprio 1
	s_waitcnt lgkmcnt(0)
	v_mfma_f32_16x16x32_f16 v[124:127], v[162:165], v[180:183], v[124:127]
	v_mfma_f32_16x16x32_f16 v[120:123], v[172:175], v[180:183], v[120:123]
	v_mfma_f32_16x16x32_f16 v[108:111], v[162:165], v[188:191], v[108:111]
	v_mfma_f32_16x16x32_f16 v[104:107], v[172:175], v[188:191], v[104:107]
	v_mfma_f32_16x16x32_f16 v[92:95], v[162:165], v[196:199], v[92:95]
	v_mfma_f32_16x16x32_f16 v[88:91], v[172:175], v[196:199], v[88:91]
	v_mfma_f32_16x16x32_f16 v[76:79], v[162:165], v[204:207], v[76:79]
	v_mfma_f32_16x16x32_f16 v[72:75], v[172:175], v[204:207], v[72:75]
	v_mfma_f32_16x16x32_f16 v[124:127], v[168:171], v[184:187], v[124:127]
	v_mfma_f32_16x16x32_f16 v[120:123], v[176:179], v[184:187], v[120:123]
	v_mfma_f32_16x16x32_f16 v[108:111], v[168:171], v[192:195], v[108:111]
	v_mfma_f32_16x16x32_f16 v[104:107], v[176:179], v[192:195], v[104:107]
	v_mfma_f32_16x16x32_f16 v[92:95], v[168:171], v[200:203], v[92:95]
	v_mfma_f32_16x16x32_f16 v[88:91], v[176:179], v[200:203], v[88:91]
	v_mfma_f32_16x16x32_f16 v[76:79], v[168:171], v[208:211], v[76:79]
	v_mfma_f32_16x16x32_f16 v[72:75], v[176:179], v[208:211], v[72:75]
	s_setprio 0
	s_barrier
	s_add_i32 s51, s45, s37
	v_lshl_add_u64 v[228:229], s[28:29], 0, v[148:149]
	s_mov_b32 m0, s51
	ds_read_b128 v[212:215], v166
	ds_read_b128 v[216:219], v166 offset:1024
	ds_read_b128 v[220:223], v166 offset:2048
	ds_read_b128 v[224:227], v166 offset:3072
	global_load_lds_dwordx4 v[228:229], off
	v_lshl_add_u64 v[230:231], s[28:29], 0, v[152:153]
	s_add_i32 m0, s51, 0x2000
	s_nop 0
	global_load_lds_dwordx4 v[230:231], off
	s_barrier
	s_waitcnt lgkmcnt(0)
	s_setprio 1
	s_waitcnt lgkmcnt(0)
	v_mfma_f32_16x16x32_f16 v[116:119], v[212:215], v[180:183], v[116:119]
	v_mfma_f32_16x16x32_f16 v[112:115], v[220:223], v[180:183], v[112:115]
	v_mfma_f32_16x16x32_f16 v[100:103], v[212:215], v[188:191], v[100:103]
	v_mfma_f32_16x16x32_f16 v[96:99], v[220:223], v[188:191], v[96:99]
	v_mfma_f32_16x16x32_f16 v[84:87], v[212:215], v[196:199], v[84:87]
	v_mfma_f32_16x16x32_f16 v[80:83], v[220:223], v[196:199], v[80:83]
	v_mfma_f32_16x16x32_f16 v[68:71], v[212:215], v[204:207], v[68:71]
	v_mfma_f32_16x16x32_f16 v[64:67], v[220:223], v[204:207], v[64:67]
	v_mfma_f32_16x16x32_f16 v[116:119], v[216:219], v[184:187], v[116:119]
	v_mfma_f32_16x16x32_f16 v[112:115], v[224:227], v[184:187], v[112:115]
	v_mfma_f32_16x16x32_f16 v[100:103], v[216:219], v[192:195], v[100:103]
	v_mfma_f32_16x16x32_f16 v[96:99], v[224:227], v[192:195], v[96:99]
	v_mfma_f32_16x16x32_f16 v[84:87], v[216:219], v[200:203], v[84:87]
	v_mfma_f32_16x16x32_f16 v[80:83], v[224:227], v[200:203], v[80:83]
	v_mfma_f32_16x16x32_f16 v[68:71], v[216:219], v[208:211], v[68:71]
	v_mfma_f32_16x16x32_f16 v[64:67], v[224:227], v[208:211], v[64:67]
	s_setprio 0
	s_mov_b32 m0, s25
	v_lshl_add_u64 v[232:233], s[30:31], 0, v[142:143]
	s_barrier
	ds_read_b128 v[180:183], v147 offset:16384
	ds_read_b128 v[184:187], v147 offset:17408
	ds_read_b128 v[188:191], v147 offset:18432
	ds_read_b128 v[192:195], v147 offset:19456
	ds_read_b128 v[196:199], v147 offset:20480
	ds_read_b128 v[200:203], v147 offset:21504
	ds_read_b128 v[204:207], v147 offset:22528
	ds_read_b128 v[208:211], v147 offset:23552
	global_load_lds_dwordx4 v[232:233], off
	v_lshl_add_u64 v[234:235], s[30:31], 0, v[150:151]
	s_mov_b32 m0, s38
	s_nop 0
	global_load_lds_dwordx4 v[234:235], off
	s_barrier
	s_waitcnt lgkmcnt(0)
	s_setprio 1
	s_waitcnt lgkmcnt(0)
	v_mfma_f32_16x16x32_f16 v[60:63], v[162:165], v[180:183], v[60:63]
	v_mfma_f32_16x16x32_f16 v[56:59], v[172:175], v[180:183], v[56:59]
	v_mfma_f32_16x16x32_f16 v[44:47], v[162:165], v[188:191], v[44:47]
	v_mfma_f32_16x16x32_f16 v[40:43], v[172:175], v[188:191], v[40:43]
	v_mfma_f32_16x16x32_f16 v[28:31], v[162:165], v[196:199], v[28:31]
	v_mfma_f32_16x16x32_f16 v[24:27], v[172:175], v[196:199], v[24:27]
	v_mfma_f32_16x16x32_f16 v[12:15], v[162:165], v[204:207], v[12:15]
	v_mfma_f32_16x16x32_f16 v[8:11], v[172:175], v[204:207], v[8:11]
	v_mfma_f32_16x16x32_f16 v[60:63], v[168:171], v[184:187], v[60:63]
	v_mfma_f32_16x16x32_f16 v[56:59], v[176:179], v[184:187], v[56:59]
	v_mfma_f32_16x16x32_f16 v[44:47], v[168:171], v[192:195], v[44:47]
	v_mfma_f32_16x16x32_f16 v[40:43], v[176:179], v[192:195], v[40:43]
	v_mfma_f32_16x16x32_f16 v[28:31], v[168:171], v[200:203], v[28:31]
	v_mfma_f32_16x16x32_f16 v[24:27], v[176:179], v[200:203], v[24:27]
	v_mfma_f32_16x16x32_f16 v[12:15], v[168:171], v[208:211], v[12:15]
	v_mfma_f32_16x16x32_f16 v[8:11], v[176:179], v[208:211], v[8:11]
	s_setprio 0
	s_barrier
; #define PG8_STAGE(bufoff, gbase, voff) do { _Pragma("unroll") for (int _i = 0; _i < 2; ++_i) \
;         __builtin_amdgcn_global_load_lds((const unsigned*)((const char*)(gbase) + (voff)[_i]), (LAS unsigned*)(lds + (bufoff) + ldsw + _i * 8192), 16, 0, 0); } while (0)
; #define PG8_LDA(dst, b, h) do { _Pragma("unroll") for (int m = 0; m < 4; ++m) _Pragma("unroll") for (int k = 0; k < 2; ++k) dst[m][k] = *(const LAS h16x8*)(lds + PG8_SA(b, h) + aoff + m * 2048 + k * 1024); } while (0)
; #define PG8_LDB(dst, b, h) do { _Pragma("unroll") for (int n = 0; n < 2; ++n) _Pragma("unroll") for (int k = 0; k < 2; ++k) dst[n][k] = *(const LAS h16x8*)(lds + PG8_SB(b, h) + boff + n * 2048 + k * 1024); } while (0)
; #define PG8_MMA(ai, bj, At, Bt) do { __builtin_amdgcn_s_setprio(1); _Pragma("unroll") for (int m = 0; m < 4; ++m) _Pragma("unroll") for (int n = 0; n < 2; ++n) _Pragma("unroll") for (int k = 0; k < 2; ++k) \
;         acc[ai][bj][m][n] = __builtin_amdgcn_mfma_f32_16x16x32_f16(Bt[n][k], At[m][k], acc[ai][bj][m][n], 0, 0, 0); __builtin_amdgcn_s_setprio(0); } while (0)
; #define PG8_WAIT_V(n) asm volatile("s_waitcnt vmcnt(" #n ")" ::: "memory")
; #define PG8_WAIT_L(n) asm volatile("s_waitcnt lgkmcnt(" #n ")" ::: "memory")
; #define PG8_BAR __builtin_amdgcn_s_barrier()
; #define PG8_SCHED __builtin_amdgcn_sched_barrier(0)
; template <class Epi>
; __device__ __forceinline__ void gemm_phase(LAS unsigned char* lds, const Gemm g, const StaticOrder& S, const Epi& E) {
;     ...
;             PG8_STAGE(PG8_SB(0, 1), b2 + hstep, voffB);
;             PG8_WAIT_V(6); PG8_BAR; PG8_MMA(1, 1, At, B1); PG8_BAR;
;             PG8_LDB(B0, 1, 0); PG8_SCHED; PG8_LDA(At, 1, 0); PG8_STAGE(PG8_SA(0, 1), a2 + hstep, voffA);
;             PG8_WAIT_L(8); PG8_BAR; PG8_WAIT_L(0); PG8_MMA(0, 0, At, B0); PG8_BAR; PG8_SCHED;
;             PG8_LDB(B1, 1, 1); PG8_STAGE(PG8_SB(1, 0), b3, voffB);
;             PG8_BAR; PG8_WAIT_L(0); PG8_MMA(0, 1, At, B1); PG8_BAR;
;             PG8_LDA(At, 1, 1); PG8_STAGE(PG8_SA(1, 0), a3, voffA);
	s_add_u32 s52, s28, 0x40000
	s_addc_u32 s53, s29, 0
	s_add_i32 s51, s46, s37
	v_lshl_add_u64 v[162:163], s[52:53], 0, v[148:149]
	s_mov_b32 m0, s51
	s_nop 0
	global_load_lds_dwordx4 v[162:163], off
	v_lshl_add_u64 v[162:163], s[52:53], 0, v[152:153]
	s_add_i32 m0, s51, 0x2000
	s_nop 0
	global_load_lds_dwordx4 v[162:163], off
	s_waitcnt vmcnt(6)
	s_barrier
	s_setprio 1
	v_mfma_f32_16x16x32_f16 v[52:55], v[212:215], v[180:183], v[52:55]
	v_mfma_f32_16x16x32_f16 v[48:51], v[220:223], v[180:183], v[48:51]
	v_mfma_f32_16x16x32_f16 v[36:39], v[212:215], v[188:191], v[36:39]
	v_mfma_f32_16x16x32_f16 v[32:35], v[220:223], v[188:191], v[32:35]
	v_mfma_f32_16x16x32_f16 v[20:23], v[212:215], v[196:199], v[20:23]
	v_mfma_f32_16x16x32_f16 v[16:19], v[220:223], v[196:199], v[16:19]
	v_mfma_f32_16x16x32_f16 v[4:7], v[212:215], v[204:207], v[4:7]
	v_mfma_f32_16x16x32_f16 v[0:3], v[220:223], v[204:207], v[0:3]
	v_mfma_f32_16x16x32_f16 v[52:55], v[216:219], v[184:187], v[52:55]
	v_mfma_f32_16x16x32_f16 v[48:51], v[224:227], v[184:187], v[48:51]
	v_mfma_f32_16x16x32_f16 v[36:39], v[216:219], v[192:195], v[36:39]
	v_mfma_f32_16x16x32_f16 v[32:35], v[224:227], v[192:195], v[32:35]
	v_mfma_f32_16x16x32_f16 v[20:23], v[216:219], v[200:203], v[20:23]
	v_mfma_f32_16x16x32_f16 v[16:19], v[224:227], v[200:203], v[16:19]
	v_mfma_f32_16x16x32_f16 v[4:7], v[216:219], v[208:211], v[4:7]
	v_mfma_f32_16x16x32_f16 v[0:3], v[224:227], v[208:211], v[0:3]
	s_setprio 0
	s_add_i32 s51, 0, 0x18000
	v_add_u32_e32 v167, s51, v139
	s_barrier
	ds_read_b128 v[162:165], v167
	ds_read_b128 v[168:171], v167 offset:1024
	ds_read_b128 v[172:175], v167 offset:2048
	ds_read_b128 v[176:179], v167 offset:3072
	s_add_u32 s30, s30, 0x40000
	s_addc_u32 s31, s31, 0
	s_mov_b32 m0, s39
	v_lshl_add_u64 v[212:213], s[30:31], 0, v[142:143]
	ds_read_b128 v[180:183], v147 offset:32768
	ds_read_b128 v[184:187], v147 offset:33792
	ds_read_b128 v[188:191], v147 offset:34816
	ds_read_b128 v[192:195], v147 offset:35840
	ds_read_b128 v[196:199], v147 offset:36864
	ds_read_b128 v[200:203], v147 offset:37888
	ds_read_b128 v[204:207], v147 offset:38912
	ds_read_b128 v[208:211], v147 offset:39936
	global_load_lds_dwordx4 v[212:213], off
	v_lshl_add_u64 v[212:213], s[30:31], 0, v[150:151]
	s_mov_b32 m0, s41
	s_nop 0
	global_load_lds_dwordx4 v[212:213], off
	s_waitcnt lgkmcnt(8)
	s_barrier
	s_waitcnt lgkmcnt(0)
	s_setprio 1
	s_waitcnt lgkmcnt(0)
	v_mfma_f32_16x16x32_f16 v[124:127], v[162:165], v[180:183], v[124:127]
	v_mfma_f32_16x16x32_f16 v[120:123], v[172:175], v[180:183], v[120:123]
	v_mfma_f32_16x16x32_f16 v[108:111], v[162:165], v[188:191], v[108:111]
	v_mfma_f32_16x16x32_f16 v[104:107], v[172:175], v[188:191], v[104:107]
	v_mfma_f32_16x16x32_f16 v[92:95], v[162:165], v[196:199], v[92:95]
	v_mfma_f32_16x16x32_f16 v[88:91], v[172:175], v[196:199], v[88:91]
	v_mfma_f32_16x16x32_f16 v[76:79], v[162:165], v[204:207], v[76:79]
	v_mfma_f32_16x16x32_f16 v[72:75], v[172:175], v[204:207], v[72:75]
	v_mfma_f32_16x16x32_f16 v[124:127], v[168:171], v[184:187], v[124:127]
	v_mfma_f32_16x16x32_f16 v[120:123], v[176:179], v[184:187], v[120:123]
	v_mfma_f32_16x16x32_f16 v[108:111], v[168:171], v[192:195], v[108:111]
	v_mfma_f32_16x16x32_f16 v[104:107], v[176:179], v[192:195], v[104:107]
	v_mfma_f32_16x16x32_f16 v[92:95], v[168:171], v[200:203], v[92:95]
	v_mfma_f32_16x16x32_f16 v[88:91], v[176:179], v[200:203], v[88:91]
	v_mfma_f32_16x16x32_f16 v[76:79], v[168:171], v[208:211], v[76:79]
	v_mfma_f32_16x16x32_f16 v[72:75], v[176:179], v[208:211], v[72:75]
	s_setprio 0
	s_barrier
	s_add_i32 s30, 0, 0x1c000
	s_add_i32 s31, s51, s37
	v_add_u32_e32 v167, s30, v139
	v_lshl_add_u64 v[228:229], v[228:229], 0, s[0:1]
	s_mov_b32 m0, s31
	ds_read_b128 v[212:215], v167
	ds_read_b128 v[216:219], v167 offset:1024
	ds_read_b128 v[220:223], v167 offset:2048
	ds_read_b128 v[224:227], v167 offset:3072
	global_load_lds_dwordx4 v[228:229], off
	v_lshl_add_u64 v[228:229], v[230:231], 0, s[0:1]
	s_add_i32 m0, s31, 0x2000
	s_nop 0
	global_load_lds_dwordx4 v[228:229], off
	s_barrier
	s_waitcnt lgkmcnt(0)
	s_setprio 1
	s_waitcnt lgkmcnt(0)
	v_mfma_f32_16x16x32_f16 v[116:119], v[212:215], v[180:183], v[116:119]
	v_mfma_f32_16x16x32_f16 v[112:115], v[220:223], v[180:183], v[112:115]
	v_mfma_f32_16x16x32_f16 v[100:103], v[212:215], v[188:191], v[100:103]
	v_mfma_f32_16x16x32_f16 v[96:99], v[220:223], v[188:191], v[96:99]
	v_mfma_f32_16x16x32_f16 v[84:87], v[212:215], v[196:199], v[84:87]
	v_mfma_f32_16x16x32_f16 v[80:83], v[220:223], v[196:199], v[80:83]
	v_mfma_f32_16x16x32_f16 v[68:71], v[212:215], v[204:207], v[68:71]
	v_mfma_f32_16x16x32_f16 v[64:67], v[220:223], v[204:207], v[64:67]
	v_mfma_f32_16x16x32_f16 v[116:119], v[216:219], v[184:187], v[116:119]
	v_mfma_f32_16x16x32_f16 v[112:115], v[224:227], v[184:187], v[112:115]
	v_mfma_f32_16x16x32_f16 v[100:103], v[216:219], v[192:195], v[100:103]
	v_mfma_f32_16x16x32_f16 v[96:99], v[224:227], v[192:195], v[96:99]
	v_mfma_f32_16x16x32_f16 v[84:87], v[216:219], v[200:203], v[84:87]
	v_mfma_f32_16x16x32_f16 v[80:83], v[224:227], v[200:203], v[80:83]
	v_mfma_f32_16x16x32_f16 v[68:71], v[216:219], v[208:211], v[68:71]
	v_mfma_f32_16x16x32_f16 v[64:67], v[224:227], v[208:211], v[64:67]
	s_setprio 0
	s_mov_b32 m0, s43
	v_lshl_add_u64 v[228:229], v[232:233], 0, s[0:1]
	s_barrier
	ds_read_b128 v[180:183], v147 offset:49152
	ds_read_b128 v[184:187], v147 offset:50176
	ds_read_b128 v[188:191], v147 offset:51200
	ds_read_b128 v[192:195], v147 offset:52224
	ds_read_b128 v[196:199], v147 offset:53248
	ds_read_b128 v[200:203], v147 offset:54272
	ds_read_b128 v[204:207], v147 offset:55296
	ds_read_b128 v[208:211], v147 offset:56320
	global_load_lds_dwordx4 v[228:229], off
	v_lshl_add_u64 v[228:229], v[234:235], 0, s[0:1]
	s_mov_b32 m0, s44
	s_nop 0
	global_load_lds_dwordx4 v[228:229], off
	s_barrier
; template <class Epi>
; __device__ __forceinline__ void gemm_phase(LAS unsigned char* lds, const Gemm g, const StaticOrder& S, const Epi& E) {
;     ...
;             PG8_BAR; PG8_WAIT_L(0); PG8_MMA(1, 0, At, B0); PG8_BAR; PG8_SCHED;
;             PG8_STAGE(PG8_SB(1, 1), b3 + hstep, voffB);
;             PG8_WAIT_V(6); PG8_BAR; PG8_MMA(1, 1, At, B1); PG8_BAR;
;     __device__ __forceinline__ void operator()(const f32x4 (&acc)[2][2][4][2], const pg8::Unit& u, int wr, int wc, int fr, int fq) const {
;         const int row0 = u.pm * 256 + wr * 64 + fr, col0 = u.pn * 256 + wc * 32 + 8 * fq;
; #pragma unroll
;         for (int ai = 0; ai < 2; ++ai)
; #pragma unroll
;             for (int m = 0; m < 4; ++m) {
;                 const int row = row0 + ai * 128 + m * 16;
;                 float ss = 0.f, rstd = 1.f;
;                 if (MODE == 2) rstd = rsqrtf(rowss[row] * (1.f / 1024.f) + EPS);
; #pragma unroll
;                 for (int bj = 0; bj < 2; ++bj) {
;                     const int c = col0 + bj * 128;
;                     f32x4 v0 = acc[ai][bj][m][0], v1 = acc[ai][bj][m][1];
;                     if (MODE == 1) {
;                         const float* rp = res + (size_t)row * ldres + c;
;                         v0 += *(const f32x4*)rp; v1 += *(const f32x4*)(rp + 4);
;                     }
;                     if (MODE == 3) {
;                         const h16x8 r8 = *(const h16x8*)(res16 + (size_t)row * ldres + c);
; #pragma unroll
;                         for (int j = 0; j < 4; ++j) { v0[j] += (float)r8[j]; v1[j] += (float)r8[4 + j]; }
;                     }
;                     if (MODE == 1 || MODE == 3) {
;                         ss += v0[0] * v0[0] + v0[1] * v0[1] + v0[2] * v0[2] + v0[3] * v0[3] + v1[0] * v1[0] + v1[1] * v1[1] + v1[2] * v1[2] + v1[3] * v1[3];
;                     }
;                     if (MODE == 2) {
; #pragma unroll
;                         for (int j = 0; j < 4; ++j) { float a = fmaxf(v0[j] * rstd, 0.f), b = fmaxf(v1[j] * rstd, 0.f); v0[j] = a * a; v1[j] = b * b; }
;                     }
;                     *(h16x8*)(o16 + (size_t)row * ld16 + c) = pack8(v0, v1);
;                 }
;                 if (MODE == 1 || MODE == 3) {
;                     ss += __shfl_xor(ss, 16); ss += __shfl_xor(ss, 32);
;                     if (fq == 0) atomicAdd(rowss + row, ss);
;                 }
;             }
	s_waitcnt lgkmcnt(0)
	s_setprio 1
	s_waitcnt lgkmcnt(0)
	v_mfma_f32_16x16x32_f16 v[60:63], v[162:165], v[180:183], v[60:63]
	v_mfma_f32_16x16x32_f16 v[56:59], v[172:175], v[180:183], v[56:59]
	v_mfma_f32_16x16x32_f16 v[44:47], v[162:165], v[188:191], v[44:47]
	v_mfma_f32_16x16x32_f16 v[40:43], v[172:175], v[188:191], v[40:43]
	v_mfma_f32_16x16x32_f16 v[28:31], v[162:165], v[196:199], v[28:31]
	v_mfma_f32_16x16x32_f16 v[24:27], v[172:175], v[196:199], v[24:27]
	v_mfma_f32_16x16x32_f16 v[12:15], v[162:165], v[204:207], v[12:15]
	v_mfma_f32_16x16x32_f16 v[8:11], v[172:175], v[204:207], v[8:11]
	v_mfma_f32_16x16x32_f16 v[60:63], v[168:171], v[184:187], v[60:63]
	v_mfma_f32_16x16x32_f16 v[56:59], v[176:179], v[184:187], v[56:59]
	v_mfma_f32_16x16x32_f16 v[44:47], v[168:171], v[192:195], v[44:47]
	v_mfma_f32_16x16x32_f16 v[40:43], v[176:179], v[192:195], v[40:43]
	v_mfma_f32_16x16x32_f16 v[28:31], v[168:171], v[200:203], v[28:31]
	v_mfma_f32_16x16x32_f16 v[24:27], v[176:179], v[200:203], v[24:27]
	v_mfma_f32_16x16x32_f16 v[12:15], v[168:171], v[208:211], v[12:15]
	v_mfma_f32_16x16x32_f16 v[8:11], v[176:179], v[208:211], v[8:11]
	s_setprio 0
	s_barrier
	s_add_u32 s28, s28, 0x40080
	s_addc_u32 s29, s29, 0
	s_add_i32 s30, s30, s37
	v_lshl_add_u64 v[162:163], s[28:29], 0, v[148:149]
	s_mov_b32 m0, s30
	s_nop 0
	global_load_lds_dwordx4 v[162:163], off
	v_lshl_add_u64 v[162:163], s[28:29], 0, v[152:153]
	s_add_i32 m0, s30, 0x2000
	s_nop 0
	global_load_lds_dwordx4 v[162:163], off
	s_waitcnt vmcnt(6)
	s_barrier
	s_setprio 1
	v_mfma_f32_16x16x32_f16 v[52:55], v[212:215], v[180:183], v[52:55]
	v_mfma_f32_16x16x32_f16 v[48:51], v[220:223], v[180:183], v[48:51]
	v_mfma_f32_16x16x32_f16 v[36:39], v[212:215], v[188:191], v[36:39]
	v_mfma_f32_16x16x32_f16 v[32:35], v[220:223], v[188:191], v[32:35]
	v_mfma_f32_16x16x32_f16 v[20:23], v[212:215], v[196:199], v[20:23]
	v_mfma_f32_16x16x32_f16 v[16:19], v[220:223], v[196:199], v[16:19]
	v_mfma_f32_16x16x32_f16 v[4:7], v[212:215], v[204:207], v[4:7]
	v_mfma_f32_16x16x32_f16 v[0:3], v[220:223], v[204:207], v[0:3]
	v_mfma_f32_16x16x32_f16 v[52:55], v[216:219], v[184:187], v[52:55]
	v_mfma_f32_16x16x32_f16 v[48:51], v[224:227], v[184:187], v[48:51]
	v_mfma_f32_16x16x32_f16 v[36:39], v[216:219], v[192:195], v[36:39]
	v_mfma_f32_16x16x32_f16 v[32:35], v[224:227], v[192:195], v[32:35]
	v_mfma_f32_16x16x32_f16 v[20:23], v[216:219], v[200:203], v[20:23]
	v_mfma_f32_16x16x32_f16 v[16:19], v[224:227], v[200:203], v[16:19]
	v_mfma_f32_16x16x32_f16 v[4:7], v[216:219], v[208:211], v[4:7]
	v_mfma_f32_16x16x32_f16 v[0:3], v[224:227], v[208:211], v[0:3]
	s_setprio 0
	s_add_i32 s50, s50, 2
	s_add_u32 s26, s26, 0x100
	s_addc_u32 s27, s27, 0
	s_add_u32 s48, s48, 0x100
	s_addc_u32 s49, s49, 0
	s_cmp_gt_u32 s50, 13
	s_barrier
	s_cbranch_scc0 .LBB0_422
	v_lshl_add_u32 v164, s22, 8, v137
	v_ashrrev_i32_e32 v165, 31, v164
	v_readlane_b32 s48, v253, 4
	v_lshl_or_b32 v162, s24, 8, v141
	v_lshlrev_b64 v[168:169], 12, v[164:165]
	v_readlane_b32 s49, v253, 5
	v_ashrrev_i32_e32 v163, 31, v162
	v_lshlrev_b64 v[178:179], 11, v[164:165]
	v_lshl_add_u64 v[168:169], s[48:49], 0, v[168:169]
	v_lshl_add_u64 v[176:177], v[162:163], 2, v[168:169]
	global_load_dwordx4 v[168:171], v[176:177], off
	global_load_dwordx4 v[172:175], v[176:177], off offset:16
	v_lshlrev_b32_e32 v182, 12, v164
	v_lshl_add_u32 v182, v162, 2, v182
	v_add_u32_e32 v183, 0x80000, v182
	global_load_dword v184, v182, s[48:49] offset:512
	v_add_u32_e32 v185, 0x10000, v182
	global_load_dword v186, v185, s[48:49]
	global_load_dword v187, v185, s[48:49] offset:512
	v_add_u32_e32 v188, 0x20000, v182
	global_load_dword v189, v188, s[48:49]
	global_load_dword v190, v188, s[48:49] offset:512
	v_add_u32_e32 v191, 0x30000, v182
	global_load_dword v192, v191, s[48:49]
	global_load_dword v193, v191, s[48:49] offset:512
	global_load_dword v194, v183, s[48:49]
	global_load_dword v195, v183, s[48:49] offset:512
	v_add_u32_e32 v196, 0x10000, v183
	global_load_dword v197, v196, s[48:49]
	global_load_dword v198, v196, s[48:49] offset:512
	v_add_u32_e32 v199, 0x20000, v183
	global_load_dword v200, v199, s[48:49]
	global_load_dword v201, v199, s[48:49] offset:512
	v_add_u32_e32 v202, 0x30000, v183
	global_load_dword v204, v202, s[48:49]
	global_load_dword v205, v202, s[48:49] offset:512
	v_lshl_add_u64 v[178:179], s[10:11], 0, v[178:179]
	v_lshl_add_u64 v[178:179], v[162:163], 1, v[178:179]
	v_readlane_b32 s50, v253, 6
	v_readlane_b32 s51, v253, 7
	v_readlane_b32 s52, v253, 8
	v_readlane_b32 s53, v253, 9
	v_readlane_b32 s54, v253, 10
	v_readlane_b32 s55, v253, 11
	v_readlane_b32 s56, v253, 12
	v_readlane_b32 s57, v253, 13
	v_readlane_b32 s58, v253, 14
	v_readlane_b32 s59, v253, 15
	v_readlane_b32 s60, v253, 16
	v_readlane_b32 s61, v253, 17
	v_readlane_b32 s62, v253, 18
	v_readlane_b32 s63, v253, 19
	s_waitcnt vmcnt(0)
	v_pk_add_f32 v[126:127], v[126:127], v[170:171]
	v_pk_add_f32 v[180:181], v[124:125], v[168:169]
	v_pk_add_f32 v[174:175], v[122:123], v[174:175]
	v_pk_add_f32 v[172:173], v[120:121], v[172:173]
	v_cvt_pk_f16_f32 v123, v174, v175
	v_cvt_pk_f16_f32 v121, v126, v127
	v_cvt_pk_f16_f32 v122, v172, v173
	v_cvt_pk_f16_f32 v120, v180, v181
	global_store_dwordx4 v[178:179], v[120:123], off sc0 sc1
	global_load_dwordx4 v[122:125], v[176:177], off offset:512
	s_nop 0
	global_load_dwordx4 v[168:171], v[176:177], off offset:528
	v_mul_f32_e32 v167, v181, v181
	v_fmac_f32_e32 v167, v180, v180
	v_fmac_f32_e32 v167, v126, v126
	v_fmac_f32_e32 v167, v127, v127
	v_fmac_f32_e32 v167, v172, v172
	v_xor_b32_e32 v120, 16, v129
	v_fmac_f32_e32 v167, v173, v173
	v_cmp_lt_i32_e32 vcc, v120, v135
	v_fmac_f32_e32 v167, v174, v174
	v_fmac_f32_e32 v167, v175, v175
	v_cndmask_b32_e32 v120, v129, v120, vcc
	v_lshlrev_b32_e32 v120, 2, v120
	v_xor_b32_e32 v121, 32, v129
	v_cmp_lt_i32_e32 vcc, v121, v135
	s_waitcnt vmcnt(0)
	v_pk_add_f32 v[122:123], v[116:117], v[122:123]
	v_pk_add_f32 v[126:127], v[112:113], v[168:169]
	v_mul_f32_e32 v112, v123, v123
	v_pk_add_f32 v[124:125], v[118:119], v[124:125]
	v_fmac_f32_e32 v112, v122, v122
	v_fmac_f32_e32 v112, v124, v124
	v_fmac_f32_e32 v112, v125, v125
	v_fmac_f32_e32 v112, v126, v126
	v_pk_add_f32 v[116:117], v[114:115], v[170:171]
	v_fmac_f32_e32 v112, v127, v127
	v_fmac_f32_e32 v112, v116, v116
	v_fmac_f32_e32 v112, v117, v117
	v_add_f32_e32 v112, v167, v112
	v_mov_b32_e32 v113, v112
	s_nop 1
	v_permlane16_swap_b32 v112, v113
	v_cndmask_b32_e32 v114, v129, v121, vcc
	v_lshlrev_b32_e32 v114, 2, v114
	v_cvt_pk_f16_f32 v119, v116, v117
	v_cvt_pk_f16_f32 v117, v124, v125
	s_waitcnt lgkmcnt(0)
	v_add_f32_e32 v112, v112, v113
	v_mov_b32_e32 v113, v112
	s_nop 1
	v_permlane32_swap_b32 v112, v113
	v_cvt_pk_f16_f32 v118, v126, v127
	v_cvt_pk_f16_f32 v116, v122, v123
	global_store_dwordx4 v[178:179], v[116:119], off offset:256 sc0 sc1
	s_and_saveexec_b64 s[22:23], s[6:7]
	s_cbranch_execz .LBB0_425
	v_lshl_add_u64 v[116:117], v[164:165], 2, s[14:15]
	s_waitcnt lgkmcnt(0)
	v_add_f32_e32 v112, v112, v113
	global_atomic_add_f32 v[116:117], v112, off
;     __device__ __forceinline__ void operator()(const f32x4 (&acc)[2][2][4][2], const pg8::Unit& u, int wr, int wc, int fr, int fq) const {
;         const int row0 = u.pm * 256 + wr * 64 + fr, col0 = u.pn * 256 + wc * 32 + 8 * fq;
; #pragma unroll
;         for (int ai = 0; ai < 2; ++ai)
; #pragma unroll
;             for (int m = 0; m < 4; ++m) {
;                 const int row = row0 + ai * 128 + m * 16;
;                 float ss = 0.f, rstd = 1.f;
;                 if (MODE == 2) rstd = rsqrtf(rowss[row] * (1.f / 1024.f) + EPS);
; #pragma unroll
;                 for (int bj = 0; bj < 2; ++bj) {
;                     const int c = col0 + bj * 128;
;                     f32x4 v0 = acc[ai][bj][m][0], v1 = acc[ai][bj][m][1];
;                     if (MODE == 1) {
;                         const float* rp = res + (size_t)row * ldres + c;
;                         v0 += *(const f32x4*)rp; v1 += *(const f32x4*)(rp + 4);
;                     }
;                     if (MODE == 3) {
;                         const h16x8 r8 = *(const h16x8*)(res16 + (size_t)row * ldres + c);
; #pragma unroll
;                         for (int j = 0; j < 4; ++j) { v0[j] += (float)r8[j]; v1[j] += (float)r8[4 + j]; }
;                     }
;                     if (MODE == 1 || MODE == 3) {
;                         ss += v0[0] * v0[0] + v0[1] * v0[1] + v0[2] * v0[2] + v0[3] * v0[3] + v1[0] * v1[0] + v1[1] * v1[1] + v1[2] * v1[2] + v1[3] * v1[3];
;                     }
;                     if (MODE == 2) {
; #pragma unroll
;                         for (int j = 0; j < 4; ++j) { float a = fmaxf(v0[j] * rstd, 0.f), b = fmaxf(v1[j] * rstd, 0.f); v0[j] = a * a; v1[j] = b * b; }
;                     }
;                     *(h16x8*)(o16 + (size_t)row * ld16 + c) = pack8(v0, v1);
;                 }
;                 if (MODE == 1 || MODE == 3) {
;                     ss += __shfl_xor(ss, 16); ss += __shfl_xor(ss, 32);
;                     if (fq == 0) atomicAdd(rowss + row, ss);
;                 }
;             }
.LBB0_425:
	s_or_b64 exec, exec, s[22:23]
	v_or_b32_e32 v112, 16, v164
	s_waitcnt lgkmcnt(0)
	v_ashrrev_i32_e32 v113, 31, v112
	v_readlane_b32 s48, v253, 4
	v_lshlrev_b64 v[116:117], 12, v[112:113]
	v_readlane_b32 s49, v253, 5
	v_lshlrev_b64 v[168:169], 11, v[112:113]
	v_lshl_add_u64 v[168:169], s[10:11], 0, v[168:169]
	v_lshl_add_u64 v[116:117], s[48:49], 0, v[116:117]
	v_lshl_add_u64 v[126:127], v[162:163], 2, v[116:117]
	global_load_dwordx4 v[116:119], v[126:127], off
	global_load_dwordx4 v[122:125], v[126:127], off offset:16
	v_lshl_add_u64 v[168:169], v[162:163], 1, v[168:169]
	v_readlane_b32 s60, v253, 16
	v_readlane_b32 s61, v253, 17
	v_readlane_b32 s62, v253, 18
	v_readlane_b32 s63, v253, 19
	v_readlane_b32 s50, v253, 6
	v_readlane_b32 s51, v253, 7
	v_readlane_b32 s52, v253, 8
	v_readlane_b32 s53, v253, 9
	v_readlane_b32 s54, v253, 10
	v_readlane_b32 s55, v253, 11
	v_readlane_b32 s56, v253, 12
	v_readlane_b32 s57, v253, 13
	v_readlane_b32 s58, v253, 14
	v_readlane_b32 s59, v253, 15
	s_waitcnt vmcnt(1)
	v_pk_add_f32 v[118:119], v[110:111], v[118:119]
	v_pk_add_f32 v[116:117], v[108:109], v[116:117]
	s_waitcnt vmcnt(0)
	v_pk_add_f32 v[124:125], v[106:107], v[124:125]
	v_pk_add_f32 v[122:123], v[104:105], v[122:123]
	v_cvt_pk_f16_f32 v107, v124, v125
	v_cvt_pk_f16_f32 v105, v118, v119
	v_cvt_pk_f16_f32 v106, v122, v123
	v_cvt_pk_f16_f32 v104, v116, v117
	global_store_dwordx4 v[168:169], v[104:107], off sc0 sc1
	global_load_dwordx4 v[104:107], v[126:127], off offset:512
	s_nop 0
	global_load_dwordx4 v[108:111], v[126:127], off offset:528
	v_mul_f32_e32 v115, v117, v117
	v_fmac_f32_e32 v115, v116, v116
	v_fmac_f32_e32 v115, v118, v118
	v_fmac_f32_e32 v115, v119, v119
	v_fmac_f32_e32 v115, v122, v122
	v_fmac_f32_e32 v115, v123, v123
	v_fmac_f32_e32 v115, v124, v124
	v_fmac_f32_e32 v115, v125, v125
	s_waitcnt vmcnt(1)
	v_pk_add_f32 v[104:105], v[100:101], v[104:105]
	v_pk_add_f32 v[102:103], v[102:103], v[106:107]
	s_waitcnt vmcnt(0)
	v_pk_add_f32 v[106:107], v[96:97], v[108:109]
	v_mul_f32_e32 v96, v105, v105
	v_fmac_f32_e32 v96, v104, v104
	v_fmac_f32_e32 v96, v102, v102
	v_fmac_f32_e32 v96, v103, v103
	v_fmac_f32_e32 v96, v106, v106
	v_pk_add_f32 v[98:99], v[98:99], v[110:111]
	v_fmac_f32_e32 v96, v107, v107
	v_fmac_f32_e32 v96, v98, v98
	v_fmac_f32_e32 v96, v99, v99
	v_add_f32_e32 v96, v115, v96
	v_mov_b32_e32 v97, v96
	s_nop 1
	v_permlane16_swap_b32 v96, v97
	v_cvt_pk_f16_f32 v101, v98, v99
	v_cvt_pk_f16_f32 v99, v102, v103
	v_cvt_pk_f16_f32 v100, v106, v107
	v_cvt_pk_f16_f32 v98, v104, v105
	s_waitcnt lgkmcnt(0)
	v_add_f32_e32 v96, v96, v97
	v_mov_b32_e32 v97, v96
	s_nop 1
	v_permlane32_swap_b32 v96, v97
	global_store_dwordx4 v[168:169], v[98:101], off offset:256 sc0 sc1
	s_and_saveexec_b64 s[22:23], s[6:7]
	v_readlane_b32 s48, v253, 20
	v_readlane_b32 s60, v253, 32
	v_readlane_b32 s61, v253, 33
	v_readlane_b32 s62, v253, 34
	v_readlane_b32 s63, v253, 35
	v_readlane_b32 s49, v253, 21
	v_readlane_b32 s50, v253, 22
	v_readlane_b32 s51, v253, 23
	v_readlane_b32 s52, v253, 24
	v_readlane_b32 s53, v253, 25
	v_readlane_b32 s54, v253, 26
	v_readlane_b32 s55, v253, 27
	v_readlane_b32 s56, v253, 28
	v_readlane_b32 s57, v253, 29
	v_readlane_b32 s58, v253, 30
	v_readlane_b32 s59, v253, 31
	s_cbranch_execz .LBB0_427
	v_lshl_add_u64 v[98:99], v[112:113], 2, s[14:15]
	s_waitcnt lgkmcnt(0)
	v_add_f32_e32 v96, v96, v97
	global_atomic_add_f32 v[98:99], v96, off
.LBB0_427:
	s_or_b64 exec, exec, s[22:23]
	v_or_b32_e32 v96, 32, v164
	s_waitcnt lgkmcnt(0)
	v_ashrrev_i32_e32 v97, 31, v96
	v_readlane_b32 s64, v253, 4
	v_lshlrev_b64 v[98:99], 12, v[96:97]
	v_readlane_b32 s65, v253, 5
	v_lshlrev_b64 v[108:109], 11, v[96:97]
	v_lshl_add_u64 v[108:109], s[10:11], 0, v[108:109]
	v_lshl_add_u64 v[98:99], s[64:65], 0, v[98:99]
	v_lshl_add_u64 v[106:107], v[162:163], 2, v[98:99]
	global_load_dwordx4 v[98:101], v[106:107], off
	global_load_dwordx4 v[102:105], v[106:107], off offset:16
	v_lshl_add_u64 v[108:109], v[162:163], 1, v[108:109]
	v_readlane_b32 s66, v253, 6
	v_readlane_b32 s67, v253, 7
	v_readlane_b32 s68, v253, 8
	v_readlane_b32 s69, v253, 9
	v_readlane_b32 s70, v253, 10
	v_readlane_b32 s71, v253, 11
	v_readlane_b32 s72, v253, 12
	v_readlane_b32 s73, v253, 13
	v_readlane_b32 s74, v253, 14
	v_readlane_b32 s75, v253, 15
	v_readlane_b32 s76, v253, 16
	v_readlane_b32 s77, v253, 17
	v_readlane_b32 s78, v253, 18
	v_readlane_b32 s79, v253, 19
	s_waitcnt vmcnt(1)
	v_pk_add_f32 v[100:101], v[94:95], v[100:101]
	v_pk_add_f32 v[98:99], v[92:93], v[98:99]
	s_waitcnt vmcnt(0)
	v_pk_add_f32 v[104:105], v[90:91], v[104:105]
	v_pk_add_f32 v[102:103], v[88:89], v[102:103]
	v_cvt_pk_f16_f32 v91, v104, v105
	v_cvt_pk_f16_f32 v89, v100, v101
	v_cvt_pk_f16_f32 v90, v102, v103
	v_cvt_pk_f16_f32 v88, v98, v99
	global_store_dwordx4 v[108:109], v[88:91], off sc0 sc1
	global_load_dwordx4 v[88:91], v[106:107], off offset:512
	s_nop 0
	global_load_dwordx4 v[92:95], v[106:107], off offset:528
	v_mul_f32_e32 v99, v99, v99
	v_fmac_f32_e32 v99, v98, v98
	v_fmac_f32_e32 v99, v100, v100
	v_fmac_f32_e32 v99, v101, v101
	v_fmac_f32_e32 v99, v102, v102
	v_fmac_f32_e32 v99, v103, v103
	v_fmac_f32_e32 v99, v104, v104
	v_fmac_f32_e32 v99, v105, v105
	s_waitcnt vmcnt(1)
	v_pk_add_f32 v[88:89], v[84:85], v[88:89]
	v_pk_add_f32 v[86:87], v[86:87], v[90:91]
	s_waitcnt vmcnt(0)
	v_pk_add_f32 v[90:91], v[80:81], v[92:93]
	v_mul_f32_e32 v80, v89, v89
	v_fmac_f32_e32 v80, v88, v88
	v_fmac_f32_e32 v80, v86, v86
	v_fmac_f32_e32 v80, v87, v87
	v_fmac_f32_e32 v80, v90, v90
	v_pk_add_f32 v[82:83], v[82:83], v[94:95]
	v_fmac_f32_e32 v80, v91, v91
	v_fmac_f32_e32 v80, v82, v82
	v_fmac_f32_e32 v80, v83, v83
	v_add_f32_e32 v80, v99, v80
	v_mov_b32_e32 v81, v80
	s_nop 1
	v_permlane16_swap_b32 v80, v81
	v_cvt_pk_f16_f32 v85, v82, v83
	v_cvt_pk_f16_f32 v83, v86, v87
	v_cvt_pk_f16_f32 v84, v90, v91
	v_cvt_pk_f16_f32 v82, v88, v89
	s_waitcnt lgkmcnt(0)
	v_add_f32_e32 v80, v80, v81
	v_mov_b32_e32 v81, v80
	s_nop 1
	v_permlane32_swap_b32 v80, v81
	global_store_dwordx4 v[108:109], v[82:85], off offset:256 sc0 sc1
	s_and_saveexec_b64 s[22:23], s[6:7]
	s_cbranch_execz .LBB0_429
	v_lshl_add_u64 v[82:83], v[96:97], 2, s[14:15]
	s_waitcnt lgkmcnt(0)
	v_add_f32_e32 v80, v80, v81
	global_atomic_add_f32 v[82:83], v80, off
;     __device__ __forceinline__ void operator()(const f32x4 (&acc)[2][2][4][2], const pg8::Unit& u, int wr, int wc, int fr, int fq) const {
;         const int row0 = u.pm * 256 + wr * 64 + fr, col0 = u.pn * 256 + wc * 32 + 8 * fq;
; #pragma unroll
;         for (int ai = 0; ai < 2; ++ai)
; #pragma unroll
;             for (int m = 0; m < 4; ++m) {
;                 const int row = row0 + ai * 128 + m * 16;
;                 float ss = 0.f, rstd = 1.f;
;                 if (MODE == 2) rstd = rsqrtf(rowss[row] * (1.f / 1024.f) + EPS);
; #pragma unroll
;                 for (int bj = 0; bj < 2; ++bj) {
;                     const int c = col0 + bj * 128;
;                     f32x4 v0 = acc[ai][bj][m][0], v1 = acc[ai][bj][m][1];
;                     if (MODE == 1) {
;                         const float* rp = res + (size_t)row * ldres + c;
;                         v0 += *(const f32x4*)rp; v1 += *(const f32x4*)(rp + 4);
;                     }
;                     if (MODE == 3) {
;                         const h16x8 r8 = *(const h16x8*)(res16 + (size_t)row * ldres + c);
; #pragma unroll
;                         for (int j = 0; j < 4; ++j) { v0[j] += (float)r8[j]; v1[j] += (float)r8[4 + j]; }
;                     }
;                     if (MODE == 1 || MODE == 3) {
;                         ss += v0[0] * v0[0] + v0[1] * v0[1] + v0[2] * v0[2] + v0[3] * v0[3] + v1[0] * v1[0] + v1[1] * v1[1] + v1[2] * v1[2] + v1[3] * v1[3];
;                     }
;                     if (MODE == 2) {
; #pragma unroll
;                         for (int j = 0; j < 4; ++j) { float a = fmaxf(v0[j] * rstd, 0.f), b = fmaxf(v1[j] * rstd, 0.f); v0[j] = a * a; v1[j] = b * b; }
;                     }
;                     *(h16x8*)(o16 + (size_t)row * ld16 + c) = pack8(v0, v1);
;                 }
;                 if (MODE == 1 || MODE == 3) {
;                     ss += __shfl_xor(ss, 16); ss += __shfl_xor(ss, 32);
;                     if (fq == 0) atomicAdd(rowss + row, ss);
;                 }
;             }
.LBB0_429:
	s_or_b64 exec, exec, s[22:23]
	v_or_b32_e32 v80, 48, v164
	s_waitcnt lgkmcnt(0)
	v_ashrrev_i32_e32 v81, 31, v80
	v_readlane_b32 s64, v253, 4
	v_lshlrev_b64 v[82:83], 12, v[80:81]
	v_readlane_b32 s65, v253, 5
	v_lshlrev_b64 v[92:93], 11, v[80:81]
	v_lshl_add_u64 v[92:93], s[10:11], 0, v[92:93]
	v_lshl_add_u64 v[82:83], s[64:65], 0, v[82:83]
	v_lshl_add_u64 v[90:91], v[162:163], 2, v[82:83]
	global_load_dwordx4 v[82:85], v[90:91], off
	global_load_dwordx4 v[86:89], v[90:91], off offset:16
	v_lshl_add_u64 v[92:93], v[162:163], 1, v[92:93]
	v_readlane_b32 s66, v253, 6
	v_readlane_b32 s67, v253, 7
	v_readlane_b32 s68, v253, 8
	v_readlane_b32 s69, v253, 9
	v_readlane_b32 s70, v253, 10
	v_readlane_b32 s71, v253, 11
	v_readlane_b32 s72, v253, 12
	v_readlane_b32 s73, v253, 13
	v_readlane_b32 s74, v253, 14
	v_readlane_b32 s75, v253, 15
	v_readlane_b32 s76, v253, 16
	v_readlane_b32 s77, v253, 17
	v_readlane_b32 s78, v253, 18
	v_readlane_b32 s79, v253, 19
	s_waitcnt vmcnt(1)
	v_pk_add_f32 v[84:85], v[78:79], v[84:85]
	v_pk_add_f32 v[82:83], v[76:77], v[82:83]
	s_waitcnt vmcnt(0)
	v_pk_add_f32 v[88:89], v[74:75], v[88:89]
	v_pk_add_f32 v[86:87], v[72:73], v[86:87]
	v_cvt_pk_f16_f32 v75, v88, v89
	v_cvt_pk_f16_f32 v73, v84, v85
	v_cvt_pk_f16_f32 v74, v86, v87
	v_cvt_pk_f16_f32 v72, v82, v83
	global_store_dwordx4 v[92:93], v[72:75], off sc0 sc1
	global_load_dwordx4 v[72:75], v[90:91], off offset:512
	s_nop 0
	global_load_dwordx4 v[76:79], v[90:91], off offset:528
	v_mul_f32_e32 v83, v83, v83
	v_fmac_f32_e32 v83, v82, v82
	v_fmac_f32_e32 v83, v84, v84
	v_fmac_f32_e32 v83, v85, v85
	v_fmac_f32_e32 v83, v86, v86
	v_fmac_f32_e32 v83, v87, v87
	v_fmac_f32_e32 v83, v88, v88
	v_fmac_f32_e32 v83, v89, v89
	s_waitcnt vmcnt(1)
	v_pk_add_f32 v[72:73], v[68:69], v[72:73]
	v_pk_add_f32 v[70:71], v[70:71], v[74:75]
	s_waitcnt vmcnt(0)
	v_pk_add_f32 v[74:75], v[64:65], v[76:77]
	v_mul_f32_e32 v64, v73, v73
	v_fmac_f32_e32 v64, v72, v72
	v_fmac_f32_e32 v64, v70, v70
	v_fmac_f32_e32 v64, v71, v71
	v_fmac_f32_e32 v64, v74, v74
	v_pk_add_f32 v[66:67], v[66:67], v[78:79]
	v_fmac_f32_e32 v64, v75, v75
	v_fmac_f32_e32 v64, v66, v66
	v_fmac_f32_e32 v64, v67, v67
	v_add_f32_e32 v64, v83, v64
	v_mov_b32_e32 v65, v64
	s_nop 1
	v_permlane16_swap_b32 v64, v65
	v_cvt_pk_f16_f32 v69, v66, v67
	v_cvt_pk_f16_f32 v67, v70, v71
	v_cvt_pk_f16_f32 v68, v74, v75
	v_cvt_pk_f16_f32 v66, v72, v73
	s_waitcnt lgkmcnt(0)
	v_add_f32_e32 v64, v64, v65
	v_mov_b32_e32 v65, v64
	s_nop 1
	v_permlane32_swap_b32 v64, v65
	global_store_dwordx4 v[92:93], v[66:69], off offset:256 sc0 sc1
	s_and_saveexec_b64 s[22:23], s[6:7]
	s_cbranch_execz .LBB0_431
	v_lshl_add_u64 v[66:67], v[80:81], 2, s[14:15]
	s_waitcnt lgkmcnt(0)
	v_add_f32_e32 v64, v64, v65
	global_atomic_add_f32 v[66:67], v64, off
.LBB0_431:
	s_or_b64 exec, exec, s[22:23]
	v_add_u32_e32 v64, 0x80, v164
	s_waitcnt lgkmcnt(0)
	v_ashrrev_i32_e32 v65, 31, v64
	v_readlane_b32 s64, v253, 4
	v_lshlrev_b64 v[66:67], 12, v[64:65]
	v_readlane_b32 s65, v253, 5
	v_lshlrev_b64 v[76:77], 11, v[64:65]
	v_lshl_add_u64 v[76:77], s[10:11], 0, v[76:77]
	v_lshl_add_u64 v[66:67], s[64:65], 0, v[66:67]
	v_lshl_add_u64 v[74:75], v[162:163], 2, v[66:67]
	global_load_dwordx4 v[66:69], v[74:75], off
	global_load_dwordx4 v[70:73], v[74:75], off offset:16
	v_lshl_add_u64 v[76:77], v[162:163], 1, v[76:77]
	v_readlane_b32 s66, v253, 6
	v_readlane_b32 s67, v253, 7
	v_readlane_b32 s68, v253, 8
	v_readlane_b32 s69, v253, 9
	v_readlane_b32 s70, v253, 10
	v_readlane_b32 s71, v253, 11
	v_readlane_b32 s72, v253, 12
	v_readlane_b32 s73, v253, 13
	v_readlane_b32 s74, v253, 14
	v_readlane_b32 s75, v253, 15
	v_readlane_b32 s76, v253, 16
	v_readlane_b32 s77, v253, 17
	v_readlane_b32 s78, v253, 18
	v_readlane_b32 s79, v253, 19
	s_waitcnt vmcnt(1)
	v_pk_add_f32 v[68:69], v[62:63], v[68:69]
	v_pk_add_f32 v[66:67], v[60:61], v[66:67]
	s_waitcnt vmcnt(0)
	v_pk_add_f32 v[72:73], v[58:59], v[72:73]
	v_pk_add_f32 v[70:71], v[56:57], v[70:71]
	v_cvt_pk_f16_f32 v59, v72, v73
	v_cvt_pk_f16_f32 v57, v68, v69
	v_cvt_pk_f16_f32 v58, v70, v71
	v_cvt_pk_f16_f32 v56, v66, v67
	global_store_dwordx4 v[76:77], v[56:59], off sc0 sc1
	global_load_dwordx4 v[56:59], v[74:75], off offset:512
	s_nop 0
	global_load_dwordx4 v[60:63], v[74:75], off offset:528
	v_mul_f32_e32 v67, v67, v67
	v_fmac_f32_e32 v67, v66, v66
	v_fmac_f32_e32 v67, v68, v68
	v_fmac_f32_e32 v67, v69, v69
	v_fmac_f32_e32 v67, v70, v70
	v_fmac_f32_e32 v67, v71, v71
	v_fmac_f32_e32 v67, v72, v72
	v_fmac_f32_e32 v67, v73, v73
	s_waitcnt vmcnt(1)
	v_pk_add_f32 v[56:57], v[52:53], v[56:57]
	v_pk_add_f32 v[54:55], v[54:55], v[58:59]
	s_waitcnt vmcnt(0)
	v_pk_add_f32 v[58:59], v[48:49], v[60:61]
	v_mul_f32_e32 v48, v57, v57
	v_fmac_f32_e32 v48, v56, v56
	v_fmac_f32_e32 v48, v54, v54
	v_fmac_f32_e32 v48, v55, v55
	v_fmac_f32_e32 v48, v58, v58
	v_pk_add_f32 v[50:51], v[50:51], v[62:63]
	v_fmac_f32_e32 v48, v59, v59
	v_fmac_f32_e32 v48, v50, v50
	v_fmac_f32_e32 v48, v51, v51
	v_add_f32_e32 v48, v67, v48
	v_mov_b32_e32 v49, v48
	s_nop 1
	v_permlane16_swap_b32 v48, v49
	v_cvt_pk_f16_f32 v53, v50, v51
	v_cvt_pk_f16_f32 v51, v54, v55
	v_cvt_pk_f16_f32 v52, v58, v59
	v_cvt_pk_f16_f32 v50, v56, v57
	s_waitcnt lgkmcnt(0)
	v_add_f32_e32 v48, v48, v49
	v_mov_b32_e32 v49, v48
	s_nop 1
	v_permlane32_swap_b32 v48, v49
	global_store_dwordx4 v[76:77], v[50:53], off offset:256 sc0 sc1
	s_and_saveexec_b64 s[22:23], s[6:7]
	s_cbranch_execz .LBB0_433
	v_lshl_add_u64 v[50:51], v[64:65], 2, s[14:15]
	s_waitcnt lgkmcnt(0)
	v_add_f32_e32 v48, v48, v49
	global_atomic_add_f32 v[50:51], v48, off
;     __device__ __forceinline__ void operator()(const f32x4 (&acc)[2][2][4][2], const pg8::Unit& u, int wr, int wc, int fr, int fq) const {
;         const int row0 = u.pm * 256 + wr * 64 + fr, col0 = u.pn * 256 + wc * 32 + 8 * fq;
; #pragma unroll
;         for (int ai = 0; ai < 2; ++ai)
; #pragma unroll
;             for (int m = 0; m < 4; ++m) {
;                 const int row = row0 + ai * 128 + m * 16;
;                 float ss = 0.f, rstd = 1.f;
;                 if (MODE == 2) rstd = rsqrtf(rowss[row] * (1.f / 1024.f) + EPS);
; #pragma unroll
;                 for (int bj = 0; bj < 2; ++bj) {
;                     const int c = col0 + bj * 128;
;                     f32x4 v0 = acc[ai][bj][m][0], v1 = acc[ai][bj][m][1];
;                     if (MODE == 1) {
;                         const float* rp = res + (size_t)row * ldres + c;
;                         v0 += *(const f32x4*)rp; v1 += *(const f32x4*)(rp + 4);
;                     }
;                     if (MODE == 3) {
;                         const h16x8 r8 = *(const h16x8*)(res16 + (size_t)row * ldres + c);
; #pragma unroll
;                         for (int j = 0; j < 4; ++j) { v0[j] += (float)r8[j]; v1[j] += (float)r8[4 + j]; }
;                     }
;                     if (MODE == 1 || MODE == 3) {
;                         ss += v0[0] * v0[0] + v0[1] * v0[1] + v0[2] * v0[2] + v0[3] * v0[3] + v1[0] * v1[0] + v1[1] * v1[1] + v1[2] * v1[2] + v1[3] * v1[3];
;                     }
;                     if (MODE == 2) {
; #pragma unroll
;                         for (int j = 0; j < 4; ++j) { float a = fmaxf(v0[j] * rstd, 0.f), b = fmaxf(v1[j] * rstd, 0.f); v0[j] = a * a; v1[j] = b * b; }
;                     }
;                     *(h16x8*)(o16 + (size_t)row * ld16 + c) = pack8(v0, v1);
;                 }
;                 if (MODE == 1 || MODE == 3) {
;                     ss += __shfl_xor(ss, 16); ss += __shfl_xor(ss, 32);
;                     if (fq == 0) atomicAdd(rowss + row, ss);
;                 }
;             }
.LBB0_433:
	s_or_b64 exec, exec, s[22:23]
	v_add_u32_e32 v48, 0x90, v164
	s_waitcnt lgkmcnt(0)
	v_ashrrev_i32_e32 v49, 31, v48
	v_readlane_b32 s64, v253, 4
	v_lshlrev_b64 v[50:51], 12, v[48:49]
	v_readlane_b32 s65, v253, 5
	v_lshlrev_b64 v[60:61], 11, v[48:49]
	v_lshl_add_u64 v[60:61], s[10:11], 0, v[60:61]
	v_lshl_add_u64 v[50:51], s[64:65], 0, v[50:51]
	v_lshl_add_u64 v[58:59], v[162:163], 2, v[50:51]
	global_load_dwordx4 v[50:53], v[58:59], off
	global_load_dwordx4 v[54:57], v[58:59], off offset:16
	v_lshl_add_u64 v[60:61], v[162:163], 1, v[60:61]
	v_readlane_b32 s66, v253, 6
	v_readlane_b32 s67, v253, 7
	v_readlane_b32 s68, v253, 8
	v_readlane_b32 s69, v253, 9
	v_readlane_b32 s70, v253, 10
	v_readlane_b32 s71, v253, 11
	v_readlane_b32 s72, v253, 12
	v_readlane_b32 s73, v253, 13
	v_readlane_b32 s74, v253, 14
	v_readlane_b32 s75, v253, 15
	v_readlane_b32 s76, v253, 16
	v_readlane_b32 s77, v253, 17
	v_readlane_b32 s78, v253, 18
	v_readlane_b32 s79, v253, 19
	s_waitcnt vmcnt(1)
	v_pk_add_f32 v[52:53], v[46:47], v[52:53]
	v_pk_add_f32 v[50:51], v[44:45], v[50:51]
	s_waitcnt vmcnt(0)
	v_pk_add_f32 v[56:57], v[42:43], v[56:57]
	v_pk_add_f32 v[54:55], v[40:41], v[54:55]
	v_cvt_pk_f16_f32 v43, v56, v57
	v_cvt_pk_f16_f32 v41, v52, v53
	v_cvt_pk_f16_f32 v42, v54, v55
	v_cvt_pk_f16_f32 v40, v50, v51
	global_store_dwordx4 v[60:61], v[40:43], off sc0 sc1
	global_load_dwordx4 v[40:43], v[58:59], off offset:512
	s_nop 0
	global_load_dwordx4 v[44:47], v[58:59], off offset:528
	v_mul_f32_e32 v51, v51, v51
	v_fmac_f32_e32 v51, v50, v50
	v_fmac_f32_e32 v51, v52, v52
	v_fmac_f32_e32 v51, v53, v53
	v_fmac_f32_e32 v51, v54, v54
	v_fmac_f32_e32 v51, v55, v55
	v_fmac_f32_e32 v51, v56, v56
	v_fmac_f32_e32 v51, v57, v57
	s_waitcnt vmcnt(1)
	v_pk_add_f32 v[40:41], v[36:37], v[40:41]
	v_pk_add_f32 v[38:39], v[38:39], v[42:43]
	s_waitcnt vmcnt(0)
	v_pk_add_f32 v[42:43], v[32:33], v[44:45]
	v_mul_f32_e32 v32, v41, v41
	v_fmac_f32_e32 v32, v40, v40
	v_fmac_f32_e32 v32, v38, v38
	v_fmac_f32_e32 v32, v39, v39
	v_fmac_f32_e32 v32, v42, v42
	v_pk_add_f32 v[34:35], v[34:35], v[46:47]
	v_fmac_f32_e32 v32, v43, v43
	v_fmac_f32_e32 v32, v34, v34
	v_fmac_f32_e32 v32, v35, v35
	v_add_f32_e32 v32, v51, v32
	v_mov_b32_e32 v33, v32
	s_nop 1
	v_permlane16_swap_b32 v32, v33
	v_cvt_pk_f16_f32 v37, v34, v35
	v_cvt_pk_f16_f32 v35, v38, v39
	v_cvt_pk_f16_f32 v36, v42, v43
	v_cvt_pk_f16_f32 v34, v40, v41
	s_waitcnt lgkmcnt(0)
	v_add_f32_e32 v32, v32, v33
	v_mov_b32_e32 v33, v32
	s_nop 1
	v_permlane32_swap_b32 v32, v33
	global_store_dwordx4 v[60:61], v[34:37], off offset:256 sc0 sc1
	s_and_saveexec_b64 s[22:23], s[6:7]
	s_cbranch_execz .LBB0_435
	v_lshl_add_u64 v[34:35], v[48:49], 2, s[14:15]
	s_waitcnt lgkmcnt(0)
	v_add_f32_e32 v32, v32, v33
	global_atomic_add_f32 v[34:35], v32, off
;     __device__ __forceinline__ void operator()(const f32x4 (&acc)[2][2][4][2], const pg8::Unit& u, int wr, int wc, int fr, int fq) const {
;         const int row0 = u.pm * 256 + wr * 64 + fr, col0 = u.pn * 256 + wc * 32 + 8 * fq;
; #pragma unroll
;         for (int ai = 0; ai < 2; ++ai)
; #pragma unroll
;             for (int m = 0; m < 4; ++m) {
;                 const int row = row0 + ai * 128 + m * 16;
;                 float ss = 0.f, rstd = 1.f;
;                 if (MODE == 2) rstd = rsqrtf(rowss[row] * (1.f / 1024.f) + EPS);
; #pragma unroll
;                 for (int bj = 0; bj < 2; ++bj) {
;                     const int c = col0 + bj * 128;
;                     f32x4 v0 = acc[ai][bj][m][0], v1 = acc[ai][bj][m][1];
;                     if (MODE == 1) {
;                         const float* rp = res + (size_t)row * ldres + c;
;                         v0 += *(const f32x4*)rp; v1 += *(const f32x4*)(rp + 4);
;                     }
;                     if (MODE == 3) {
;                         const h16x8 r8 = *(const h16x8*)(res16 + (size_t)row * ldres + c);
; #pragma unroll
;                         for (int j = 0; j < 4; ++j) { v0[j] += (float)r8[j]; v1[j] += (float)r8[4 + j]; }
;                     }
;                     if (MODE == 1 || MODE == 3) {
;                         ss += v0[0] * v0[0] + v0[1] * v0[1] + v0[2] * v0[2] + v0[3] * v0[3] + v1[0] * v1[0] + v1[1] * v1[1] + v1[2] * v1[2] + v1[3] * v1[3];
;                     }
;                     if (MODE == 2) {
; #pragma unroll
;                         for (int j = 0; j < 4; ++j) { float a = fmaxf(v0[j] * rstd, 0.f), b = fmaxf(v1[j] * rstd, 0.f); v0[j] = a * a; v1[j] = b * b; }
;                     }
;                     *(h16x8*)(o16 + (size_t)row * ld16 + c) = pack8(v0, v1);
;                 }
;                 if (MODE == 1 || MODE == 3) {
;                     ss += __shfl_xor(ss, 16); ss += __shfl_xor(ss, 32);
;                     if (fq == 0) atomicAdd(rowss + row, ss);
;                 }
;             }
.LBB0_435:
	s_or_b64 exec, exec, s[22:23]
	v_add_u32_e32 v32, 0xa0, v164
	s_waitcnt lgkmcnt(0)
	v_ashrrev_i32_e32 v33, 31, v32
	v_readlane_b32 s64, v253, 4
	v_lshlrev_b64 v[34:35], 12, v[32:33]
	v_readlane_b32 s65, v253, 5
	v_lshlrev_b64 v[44:45], 11, v[32:33]
	v_lshl_add_u64 v[44:45], s[10:11], 0, v[44:45]
	v_lshl_add_u64 v[34:35], s[64:65], 0, v[34:35]
	v_lshl_add_u64 v[42:43], v[162:163], 2, v[34:35]
	global_load_dwordx4 v[34:37], v[42:43], off
	global_load_dwordx4 v[38:41], v[42:43], off offset:16
	v_lshl_add_u64 v[44:45], v[162:163], 1, v[44:45]
	v_readlane_b32 s66, v253, 6
	v_readlane_b32 s67, v253, 7
	v_readlane_b32 s68, v253, 8
	v_readlane_b32 s69, v253, 9
	v_readlane_b32 s70, v253, 10
	v_readlane_b32 s71, v253, 11
	v_readlane_b32 s72, v253, 12
	v_readlane_b32 s73, v253, 13
	v_readlane_b32 s74, v253, 14
	v_readlane_b32 s75, v253, 15
	v_readlane_b32 s76, v253, 16
	v_readlane_b32 s77, v253, 17
	v_readlane_b32 s78, v253, 18
	v_readlane_b32 s79, v253, 19
	s_waitcnt vmcnt(1)
	v_pk_add_f32 v[36:37], v[30:31], v[36:37]
	v_pk_add_f32 v[34:35], v[28:29], v[34:35]
	s_waitcnt vmcnt(0)
	v_pk_add_f32 v[40:41], v[26:27], v[40:41]
	v_pk_add_f32 v[38:39], v[24:25], v[38:39]
	v_cvt_pk_f16_f32 v27, v40, v41
	v_cvt_pk_f16_f32 v25, v36, v37
	v_cvt_pk_f16_f32 v26, v38, v39
	v_cvt_pk_f16_f32 v24, v34, v35
	global_store_dwordx4 v[44:45], v[24:27], off sc0 sc1
	global_load_dwordx4 v[24:27], v[42:43], off offset:512
	s_nop 0
	global_load_dwordx4 v[28:31], v[42:43], off offset:528
	v_mul_f32_e32 v35, v35, v35
	v_fmac_f32_e32 v35, v34, v34
	v_fmac_f32_e32 v35, v36, v36
	v_fmac_f32_e32 v35, v37, v37
	v_fmac_f32_e32 v35, v38, v38
	v_fmac_f32_e32 v35, v39, v39
	v_fmac_f32_e32 v35, v40, v40
	v_fmac_f32_e32 v35, v41, v41
	s_waitcnt vmcnt(1)
	v_pk_add_f32 v[24:25], v[20:21], v[24:25]
	v_pk_add_f32 v[22:23], v[22:23], v[26:27]
	s_waitcnt vmcnt(0)
	v_pk_add_f32 v[26:27], v[16:17], v[28:29]
	v_mul_f32_e32 v16, v25, v25
	v_fmac_f32_e32 v16, v24, v24
	v_fmac_f32_e32 v16, v22, v22
	v_fmac_f32_e32 v16, v23, v23
	v_fmac_f32_e32 v16, v26, v26
	v_pk_add_f32 v[18:19], v[18:19], v[30:31]
	v_fmac_f32_e32 v16, v27, v27
	v_fmac_f32_e32 v16, v18, v18
	v_fmac_f32_e32 v16, v19, v19
	v_add_f32_e32 v16, v35, v16
	v_mov_b32_e32 v17, v16
	s_nop 1
	v_permlane16_swap_b32 v16, v17
	v_cvt_pk_f16_f32 v21, v18, v19
	v_cvt_pk_f16_f32 v19, v22, v23
	v_cvt_pk_f16_f32 v20, v26, v27
	v_cvt_pk_f16_f32 v18, v24, v25
	s_waitcnt lgkmcnt(0)
	v_add_f32_e32 v16, v16, v17
	v_mov_b32_e32 v17, v16
	s_nop 1
	v_permlane32_swap_b32 v16, v17
	global_store_dwordx4 v[44:45], v[18:21], off offset:256 sc0 sc1
	s_and_saveexec_b64 s[22:23], s[6:7]
	s_cbranch_execz .LBB0_437
	v_lshl_add_u64 v[18:19], v[32:33], 2, s[14:15]
	s_waitcnt lgkmcnt(0)
	v_add_f32_e32 v16, v16, v17
	global_atomic_add_f32 v[18:19], v16, off
.LBB0_437:
	s_or_b64 exec, exec, s[22:23]
	v_add_u32_e32 v16, 0xb0, v164
	s_waitcnt lgkmcnt(0)
	v_ashrrev_i32_e32 v17, 31, v16
	v_readlane_b32 s64, v253, 4
	v_lshlrev_b64 v[18:19], 12, v[16:17]
	v_readlane_b32 s65, v253, 5
	v_lshlrev_b64 v[28:29], 11, v[16:17]
	v_lshl_add_u64 v[28:29], s[10:11], 0, v[28:29]
	v_lshl_add_u64 v[18:19], s[64:65], 0, v[18:19]
	v_lshl_add_u64 v[26:27], v[162:163], 2, v[18:19]
	global_load_dwordx4 v[18:21], v[26:27], off
	global_load_dwordx4 v[22:25], v[26:27], off offset:16
	v_lshl_add_u64 v[28:29], v[162:163], 1, v[28:29]
	v_readlane_b32 s66, v253, 6
	v_readlane_b32 s67, v253, 7
	v_readlane_b32 s68, v253, 8
	v_readlane_b32 s69, v253, 9
	v_readlane_b32 s70, v253, 10
	v_readlane_b32 s71, v253, 11
	v_readlane_b32 s72, v253, 12
	v_readlane_b32 s73, v253, 13
	v_readlane_b32 s74, v253, 14
	v_readlane_b32 s75, v253, 15
	v_readlane_b32 s76, v253, 16
	v_readlane_b32 s77, v253, 17
	v_readlane_b32 s78, v253, 18
	v_readlane_b32 s79, v253, 19
	s_waitcnt vmcnt(1)
	v_pk_add_f32 v[20:21], v[14:15], v[20:21]
	v_pk_add_f32 v[18:19], v[12:13], v[18:19]
	s_waitcnt vmcnt(0)
	v_pk_add_f32 v[24:25], v[10:11], v[24:25]
	v_pk_add_f32 v[22:23], v[8:9], v[22:23]
	v_cvt_pk_f16_f32 v11, v24, v25
	v_cvt_pk_f16_f32 v9, v20, v21
	v_cvt_pk_f16_f32 v10, v22, v23
	v_cvt_pk_f16_f32 v8, v18, v19
	global_store_dwordx4 v[28:29], v[8:11], off sc0 sc1
	global_load_dwordx4 v[8:11], v[26:27], off offset:512
	s_nop 0
	global_load_dwordx4 v[12:15], v[26:27], off offset:528
	v_mul_f32_e32 v19, v19, v19
	v_fmac_f32_e32 v19, v18, v18
	v_fmac_f32_e32 v19, v20, v20
	v_fmac_f32_e32 v19, v21, v21
	v_fmac_f32_e32 v19, v22, v22
	v_fmac_f32_e32 v19, v23, v23
	v_fmac_f32_e32 v19, v24, v24
	v_fmac_f32_e32 v19, v25, v25
	s_waitcnt vmcnt(1)
	v_pk_add_f32 v[8:9], v[4:5], v[8:9]
	v_pk_add_f32 v[6:7], v[6:7], v[10:11]
	s_waitcnt vmcnt(0)
	v_pk_add_f32 v[10:11], v[0:1], v[12:13]
	v_mul_f32_e32 v0, v9, v9
	v_fmac_f32_e32 v0, v8, v8
	v_fmac_f32_e32 v0, v6, v6
	v_fmac_f32_e32 v0, v7, v7
	v_fmac_f32_e32 v0, v10, v10
	v_pk_add_f32 v[2:3], v[2:3], v[14:15]
	v_fmac_f32_e32 v0, v11, v11
	v_fmac_f32_e32 v0, v2, v2
	v_fmac_f32_e32 v0, v3, v3
	v_add_f32_e32 v0, v19, v0
	v_mov_b32_e32 v1, v0
	s_nop 1
	v_permlane16_swap_b32 v0, v1
	v_cvt_pk_f16_f32 v5, v2, v3
	v_cvt_pk_f16_f32 v3, v6, v7
	v_cvt_pk_f16_f32 v4, v10, v11
	v_cvt_pk_f16_f32 v2, v8, v9
	s_waitcnt lgkmcnt(0)
	v_add_f32_e32 v0, v0, v1
	v_mov_b32_e32 v1, v0
	s_nop 1
	v_permlane32_swap_b32 v0, v1
	global_store_dwordx4 v[28:29], v[2:5], off offset:256 sc0 sc1
	s_and_saveexec_b64 s[22:23], s[6:7]
	s_cbranch_execz .LBB0_414
	v_lshl_add_u64 v[2:3], v[16:17], 2, s[14:15]
	s_waitcnt lgkmcnt(0)
	v_add_f32_e32 v0, v0, v1
	global_atomic_add_f32 v[2:3], v0, off
	s_branch .LBB0_414

;     __device__ __forceinline__ void operator()(f32x4 (&acc)[2][2][4][2], const pg8::Unit& u, int wr, int wc, int fr, int fq) const {
;     ...
; #pragma unroll
;         for (int ai = 0; ai < 2; ++ai)
; #pragma unroll
;             for (int m = 0; m < 4; ++m) {
;                 const int row = row0 + ai * 128 + m * 16;
;                 const float rstd = rsqrtf(__hip_atomic_load(rowss + row, __ATOMIC_RELAXED, __HIP_MEMORY_SCOPE_AGENT) * (1.f / 1024.f) + EPS);
; #pragma unroll
;                 for (int bj = 0; bj < 2; ++bj) {
;                     const int c = col0 + bj * 128;
;                     const f32x4 w0 = *(const f32x4*)(nw + c), w1 = *(const f32x4*)(nw + c + 4);
;                     float* op = out + (size_t)row * D + c;
;                     *(f32x4*)op = acc[ai][bj][m][0] * rstd * w0; *(f32x4*)(op + 4) = acc[ai][bj][m][1] * rstd * w1;
;                 }
;             }
.LBB0_605:
	s_or_b64 exec, exec, s[4:5]
	s_barrier
	v_cmp_gt_u32_e64 s[98:99], 8, v131
	v_mov_b32_e32 v240, 0xffff8010
	v_cndmask_b32_e64 v236, v240, 0, s[98:99]
	v_cndmask_b32_e64 v237, -1, 0, s[98:99]
	v_mov_b32_e32 v240, 0x8010
	v_cndmask_b32_e64 v238, 0, v240, s[98:99]
	v_mov_b32_e32 v239, 0
	global_load_dword v147, v[112:113], off sc1
	v_lshlrev_b64 v[166:167], 2, v[140:141]
	v_lshl_add_u64 v[140:141], s[60:61], 0, v[166:167]
	global_load_dwordx4 v[168:171], v[140:141], off
	global_load_dwordx4 v[172:175], v[140:141], off offset:16
	v_mov_b32_e32 v137, 0x358637bd
	s_mov_b32 s0, 0x800000
	v_lshlrev_b64 v[138:139], 12, v[138:139]
	v_lshl_add_u64 v[138:139], s[62:63], 0, v[138:139]
	v_lshl_add_u64 v[138:139], v[138:139], 0, v[166:167]
	v_lshlrev_b64 v[104:105], 12, v[104:105]
	v_lshl_add_u64 v[104:105], s[62:63], 0, v[104:105]
	v_lshl_add_u64 v[104:105], v[104:105], 0, v[166:167]
	v_lshlrev_b64 v[88:89], 12, v[88:89]
	v_lshl_add_u64 v[88:89], s[62:63], 0, v[88:89]
	v_lshl_add_u64 v[88:89], v[88:89], 0, v[166:167]
	v_lshlrev_b64 v[72:73], 12, v[72:73]
	v_lshl_add_u64 v[72:73], s[62:63], 0, v[72:73]
	v_lshl_add_u64 v[72:73], v[72:73], 0, v[166:167]
	v_lshlrev_b64 v[56:57], 12, v[56:57]
	v_lshl_add_u64 v[56:57], s[62:63], 0, v[56:57]
	v_lshl_add_u64 v[56:57], v[56:57], 0, v[166:167]
	v_lshlrev_b64 v[40:41], 12, v[40:41]
	v_lshl_add_u64 v[40:41], s[62:63], 0, v[40:41]
	v_lshl_add_u64 v[40:41], v[40:41], 0, v[166:167]
	v_lshlrev_b64 v[24:25], 12, v[24:25]
	v_lshl_add_u64 v[24:25], s[62:63], 0, v[24:25]
	v_lshl_add_u64 v[24:25], v[24:25], 0, v[166:167]
	s_waitcnt vmcnt(2)
	v_fmamk_f32 v147, v147, 0x3a800000, v137
	v_mul_f32_e32 v176, 0x4b800000, v147
	v_cmp_gt_f32_e32 vcc, s0, v147
	s_nop 1
	v_cndmask_b32_e32 v147, v147, v176, vcc
	v_rsq_f32_e32 v147, v147
	s_nop 0
	v_mul_f32_e32 v176, 0x45800000, v147
	v_cndmask_b32_e32 v176, v147, v176, vcc
	v_pk_mul_f32 v[142:143], v[142:143], v[176:177] op_sel_hi:[1,0]
	v_pk_mul_f32 v[126:127], v[126:127], v[176:177] op_sel_hi:[1,0]
	v_pk_mul_f32 v[178:179], v[124:125], v[176:177] op_sel_hi:[1,0]
	v_pk_mul_f32 v[180:181], v[122:123], v[176:177] op_sel_hi:[1,0]
	s_waitcnt vmcnt(1)
	v_pk_mul_f32 v[124:125], v[170:171], v[126:127]
	v_pk_mul_f32 v[122:123], v[168:169], v[142:143]
	s_waitcnt vmcnt(0)
	v_pk_mul_f32 v[170:171], v[174:175], v[180:181]
	v_pk_mul_f32 v[168:169], v[172:173], v[178:179]
	s_nop 1
	v_mov_b32_dpp v228, v168 row_ror:8 row_mask:0xf bank_mask:0xf
	v_mov_b32_dpp v229, v169 row_ror:8 row_mask:0xf bank_mask:0xf
	v_mov_b32_dpp v230, v170 row_ror:8 row_mask:0xf bank_mask:0xf
	v_mov_b32_dpp v231, v171 row_ror:8 row_mask:0xf bank_mask:0xf
	v_cndmask_b32_e64 v168, v228, v122, s[98:99]
	v_cndmask_b32_e64 v169, v229, v123, s[98:99]
	v_cndmask_b32_e64 v170, v230, v124, s[98:99]
	v_cndmask_b32_e64 v171, v231, v125, s[98:99]
	v_cndmask_b32_e64 v228, v122, v228, s[98:99]
	v_cndmask_b32_e64 v229, v123, v229, s[98:99]
	v_cndmask_b32_e64 v230, v124, v230, s[98:99]
	v_cndmask_b32_e64 v231, v125, v231, s[98:99]
	v_lshl_add_u64 v[232:233], v[138:139], 0, v[236:237]
	v_lshl_add_u64 v[234:235], v[138:139], 0, v[238:239]
	global_store_dwordx4 v[232:233], v[168:171], off sc0 sc1
	global_store_dwordx4 v[234:235], v[228:231], off sc0 sc1
	global_load_dwordx4 v[122:125], v[140:141], off offset:512
	s_nop 0
	global_load_dwordx4 v[168:171], v[140:141], off offset:528
	v_pk_mul_f32 v[118:119], v[118:119], v[176:177] op_sel_hi:[1,0]
	v_pk_mul_f32 v[120:121], v[120:121], v[176:177] op_sel_hi:[1,0]
	v_pk_mul_f32 v[126:127], v[114:115], v[176:177] op_sel_hi:[1,0]
	v_pk_mul_f32 v[142:143], v[116:117], v[176:177] op_sel_hi:[1,0]
	s_waitcnt vmcnt(1)
	v_pk_mul_f32 v[114:115], v[122:123], v[120:121]
	v_pk_mul_f32 v[116:117], v[124:125], v[118:119]
	s_waitcnt vmcnt(0)
	v_pk_mul_f32 v[118:119], v[168:169], v[142:143]
	v_pk_mul_f32 v[120:121], v[170:171], v[126:127]
	s_nop 1
	v_mov_b32_dpp v228, v118 row_ror:8 row_mask:0xf bank_mask:0xf
	v_mov_b32_dpp v229, v119 row_ror:8 row_mask:0xf bank_mask:0xf
	v_mov_b32_dpp v230, v120 row_ror:8 row_mask:0xf bank_mask:0xf
	v_mov_b32_dpp v231, v121 row_ror:8 row_mask:0xf bank_mask:0xf
	v_cndmask_b32_e64 v118, v228, v114, s[98:99]
	v_cndmask_b32_e64 v119, v229, v115, s[98:99]
	v_cndmask_b32_e64 v120, v230, v116, s[98:99]
	v_cndmask_b32_e64 v121, v231, v117, s[98:99]
	v_cndmask_b32_e64 v228, v114, v228, s[98:99]
	v_cndmask_b32_e64 v229, v115, v229, s[98:99]
	v_cndmask_b32_e64 v230, v116, v230, s[98:99]
	v_cndmask_b32_e64 v231, v117, v231, s[98:99]
	v_lshl_add_u64 v[232:233], v[138:139], 0, v[236:237]
	v_lshl_add_u64 v[234:235], v[138:139], 0, v[238:239]
	global_store_dwordx4 v[232:233], v[118:121], off offset:512 sc0 sc1
	global_store_dwordx4 v[234:235], v[228:231], off offset:512 sc0 sc1
	global_load_dword v122, v[152:153], off sc1
	s_nop 0
	global_load_dwordx4 v[114:117], v[140:141], off
	global_load_dwordx4 v[118:121], v[140:141], off offset:16
	s_waitcnt vmcnt(2)
	v_fmamk_f32 v122, v122, 0x3a800000, v137
	v_mul_f32_e32 v123, 0x4b800000, v122
	v_cmp_gt_f32_e32 vcc, s0, v122
	s_nop 1
	v_cndmask_b32_e32 v122, v122, v123, vcc
	v_rsq_f32_e32 v124, v122
	v_lshlrev_b64 v[122:123], 12, v[144:145]
	v_lshl_add_u64 v[122:123], s[62:63], 0, v[122:123]
	v_lshl_add_u64 v[122:123], v[122:123], 0, v[166:167]
	v_mul_f32_e32 v125, 0x45800000, v124
	v_cndmask_b32_e32 v124, v124, v125, vcc
	v_pk_mul_f32 v[126:127], v[148:149], v[124:125] op_sel_hi:[1,0]
	v_pk_mul_f32 v[110:111], v[110:111], v[124:125] op_sel_hi:[1,0]
	v_pk_mul_f32 v[138:139], v[108:109], v[124:125] op_sel_hi:[1,0]
	v_pk_mul_f32 v[142:143], v[106:107], v[124:125] op_sel_hi:[1,0]
	s_waitcnt vmcnt(1)
;     __device__ __forceinline__ void operator()(f32x4 (&acc)[2][2][4][2], const pg8::Unit& u, int wr, int wc, int fr, int fq) const {
;     ...
; #pragma unroll
;         for (int ai = 0; ai < 2; ++ai)
; #pragma unroll
;             for (int m = 0; m < 4; ++m) {
;                 const int row = row0 + ai * 128 + m * 16;
;                 const float rstd = rsqrtf(__hip_atomic_load(rowss + row, __ATOMIC_RELAXED, __HIP_MEMORY_SCOPE_AGENT) * (1.f / 1024.f) + EPS);
; #pragma unroll
;                 for (int bj = 0; bj < 2; ++bj) {
;                     const int c = col0 + bj * 128;
;                     const f32x4 w0 = *(const f32x4*)(nw + c), w1 = *(const f32x4*)(nw + c + 4);
;                     float* op = out + (size_t)row * D + c;
;                     *(f32x4*)op = acc[ai][bj][m][0] * rstd * w0; *(f32x4*)(op + 4) = acc[ai][bj][m][1] * rstd * w1;
;                 }
;             }
	v_pk_mul_f32 v[108:109], v[116:117], v[110:111]
	v_pk_mul_f32 v[106:107], v[114:115], v[126:127]
	s_waitcnt vmcnt(0)
	v_pk_mul_f32 v[116:117], v[120:121], v[142:143]
	v_pk_mul_f32 v[114:115], v[118:119], v[138:139]
	s_nop 1
	v_mov_b32_dpp v228, v114 row_ror:8 row_mask:0xf bank_mask:0xf
	v_mov_b32_dpp v229, v115 row_ror:8 row_mask:0xf bank_mask:0xf
	v_mov_b32_dpp v230, v116 row_ror:8 row_mask:0xf bank_mask:0xf
	v_mov_b32_dpp v231, v117 row_ror:8 row_mask:0xf bank_mask:0xf
	v_cndmask_b32_e64 v114, v228, v106, s[98:99]
	v_cndmask_b32_e64 v115, v229, v107, s[98:99]
	v_cndmask_b32_e64 v116, v230, v108, s[98:99]
	v_cndmask_b32_e64 v117, v231, v109, s[98:99]
	v_cndmask_b32_e64 v228, v106, v228, s[98:99]
	v_cndmask_b32_e64 v229, v107, v229, s[98:99]
	v_cndmask_b32_e64 v230, v108, v230, s[98:99]
	v_cndmask_b32_e64 v231, v109, v231, s[98:99]
	v_lshl_add_u64 v[232:233], v[122:123], 0, v[236:237]
	v_lshl_add_u64 v[234:235], v[122:123], 0, v[238:239]
	global_store_dwordx4 v[232:233], v[114:117], off sc0 sc1
	global_store_dwordx4 v[234:235], v[228:231], off sc0 sc1
	global_load_dwordx4 v[106:109], v[140:141], off offset:512
	s_nop 0
	global_load_dwordx4 v[114:117], v[140:141], off offset:528
	v_pk_mul_f32 v[102:103], v[102:103], v[124:125] op_sel_hi:[1,0]
	v_pk_mul_f32 v[100:101], v[100:101], v[124:125] op_sel_hi:[1,0]
	v_pk_mul_f32 v[110:111], v[98:99], v[124:125] op_sel_hi:[1,0]
	v_pk_mul_f32 v[118:119], v[96:97], v[124:125] op_sel_hi:[1,0]
	s_waitcnt vmcnt(1)
	v_pk_mul_f32 v[96:97], v[106:107], v[100:101]
	v_pk_mul_f32 v[98:99], v[108:109], v[102:103]
	s_waitcnt vmcnt(0)
	v_pk_mul_f32 v[100:101], v[114:115], v[118:119]
	v_pk_mul_f32 v[102:103], v[116:117], v[110:111]
	s_nop 1
	v_mov_b32_dpp v228, v100 row_ror:8 row_mask:0xf bank_mask:0xf
	v_mov_b32_dpp v229, v101 row_ror:8 row_mask:0xf bank_mask:0xf
	v_mov_b32_dpp v230, v102 row_ror:8 row_mask:0xf bank_mask:0xf
	v_mov_b32_dpp v231, v103 row_ror:8 row_mask:0xf bank_mask:0xf
	v_cndmask_b32_e64 v100, v228, v96, s[98:99]
	v_cndmask_b32_e64 v101, v229, v97, s[98:99]
	v_cndmask_b32_e64 v102, v230, v98, s[98:99]
	v_cndmask_b32_e64 v103, v231, v99, s[98:99]
	v_cndmask_b32_e64 v228, v96, v228, s[98:99]
	v_cndmask_b32_e64 v229, v97, v229, s[98:99]
	v_cndmask_b32_e64 v230, v98, v230, s[98:99]
	v_cndmask_b32_e64 v231, v99, v231, s[98:99]
	v_lshl_add_u64 v[232:233], v[122:123], 0, v[236:237]
	v_lshl_add_u64 v[234:235], v[122:123], 0, v[238:239]
	global_store_dwordx4 v[232:233], v[100:103], off offset:512 sc0 sc1
	global_store_dwordx4 v[234:235], v[228:231], off offset:512 sc0 sc1
	global_load_dword v106, v[156:157], off sc1
	s_nop 0
	global_load_dwordx4 v[96:99], v[140:141], off
	global_load_dwordx4 v[100:103], v[140:141], off offset:16
	s_waitcnt vmcnt(2)
	v_fmamk_f32 v106, v106, 0x3a800000, v137
	v_mul_f32_e32 v107, 0x4b800000, v106
	v_cmp_gt_f32_e32 vcc, s0, v106
	s_nop 1
	v_cndmask_b32_e32 v106, v106, v107, vcc
	v_rsq_f32_e32 v106, v106
	s_nop 0
	v_mul_f32_e32 v107, 0x45800000, v106
	v_cndmask_b32_e32 v106, v106, v107, vcc
	v_pk_mul_f32 v[108:109], v[150:151], v[106:107] op_sel_hi:[1,0]
	v_pk_mul_f32 v[94:95], v[94:95], v[106:107] op_sel_hi:[1,0]
	v_pk_mul_f32 v[110:111], v[92:93], v[106:107] op_sel_hi:[1,0]
	v_pk_mul_f32 v[114:115], v[90:91], v[106:107] op_sel_hi:[1,0]
	s_waitcnt vmcnt(1)
	v_pk_mul_f32 v[92:93], v[98:99], v[94:95]
	v_pk_mul_f32 v[90:91], v[96:97], v[108:109]
	s_waitcnt vmcnt(0)
	v_pk_mul_f32 v[96:97], v[102:103], v[114:115]
	v_pk_mul_f32 v[94:95], v[100:101], v[110:111]
	s_nop 1
	v_mov_b32_dpp v228, v94 row_ror:8 row_mask:0xf bank_mask:0xf
	v_mov_b32_dpp v229, v95 row_ror:8 row_mask:0xf bank_mask:0xf
	v_mov_b32_dpp v230, v96 row_ror:8 row_mask:0xf bank_mask:0xf
	v_mov_b32_dpp v231, v97 row_ror:8 row_mask:0xf bank_mask:0xf
	v_cndmask_b32_e64 v94, v228, v90, s[98:99]
	v_cndmask_b32_e64 v95, v229, v91, s[98:99]
	v_cndmask_b32_e64 v96, v230, v92, s[98:99]
	v_cndmask_b32_e64 v97, v231, v93, s[98:99]
	v_cndmask_b32_e64 v228, v90, v228, s[98:99]
	v_cndmask_b32_e64 v229, v91, v229, s[98:99]
	v_cndmask_b32_e64 v230, v92, v230, s[98:99]
	v_cndmask_b32_e64 v231, v93, v231, s[98:99]
	v_lshl_add_u64 v[232:233], v[104:105], 0, v[236:237]
	v_lshl_add_u64 v[234:235], v[104:105], 0, v[238:239]
	global_store_dwordx4 v[232:233], v[94:97], off sc0 sc1
	global_store_dwordx4 v[234:235], v[228:231], off sc0 sc1
	global_load_dwordx4 v[90:93], v[140:141], off offset:512
	s_nop 0
	global_load_dwordx4 v[94:97], v[140:141], off offset:528
	v_pk_mul_f32 v[86:87], v[86:87], v[106:107] op_sel_hi:[1,0]
	v_pk_mul_f32 v[84:85], v[84:85], v[106:107] op_sel_hi:[1,0]
	v_pk_mul_f32 v[98:99], v[82:83], v[106:107] op_sel_hi:[1,0]
	v_pk_mul_f32 v[100:101], v[80:81], v[106:107] op_sel_hi:[1,0]
	s_waitcnt vmcnt(1)
	v_pk_mul_f32 v[80:81], v[90:91], v[84:85]
	v_pk_mul_f32 v[82:83], v[92:93], v[86:87]
	s_waitcnt vmcnt(0)
	v_pk_mul_f32 v[84:85], v[94:95], v[100:101]
	v_pk_mul_f32 v[86:87], v[96:97], v[98:99]
	s_nop 1
	v_mov_b32_dpp v228, v84 row_ror:8 row_mask:0xf bank_mask:0xf
	v_mov_b32_dpp v229, v85 row_ror:8 row_mask:0xf bank_mask:0xf
	v_mov_b32_dpp v230, v86 row_ror:8 row_mask:0xf bank_mask:0xf
	v_mov_b32_dpp v231, v87 row_ror:8 row_mask:0xf bank_mask:0xf
	v_cndmask_b32_e64 v84, v228, v80, s[98:99]
	v_cndmask_b32_e64 v85, v229, v81, s[98:99]
	v_cndmask_b32_e64 v86, v230, v82, s[98:99]
	v_cndmask_b32_e64 v87, v231, v83, s[98:99]
	v_cndmask_b32_e64 v228, v80, v228, s[98:99]
	v_cndmask_b32_e64 v229, v81, v229, s[98:99]
	v_cndmask_b32_e64 v230, v82, v230, s[98:99]
	v_cndmask_b32_e64 v231, v83, v231, s[98:99]
	v_lshl_add_u64 v[232:233], v[104:105], 0, v[236:237]
	v_lshl_add_u64 v[234:235], v[104:105], 0, v[238:239]
	global_store_dwordx4 v[232:233], v[84:87], off offset:512 sc0 sc1
	global_store_dwordx4 v[234:235], v[228:231], off offset:512 sc0 sc1
	global_load_dword v90, v[160:161], off sc1
	s_nop 0
	global_load_dwordx4 v[80:83], v[140:141], off
	global_load_dwordx4 v[84:87], v[140:141], off offset:16
	s_waitcnt vmcnt(2)
;     __device__ __forceinline__ void operator()(f32x4 (&acc)[2][2][4][2], const pg8::Unit& u, int wr, int wc, int fr, int fq) const {
;     ...
; #pragma unroll
;         for (int ai = 0; ai < 2; ++ai)
; #pragma unroll
;             for (int m = 0; m < 4; ++m) {
;                 const int row = row0 + ai * 128 + m * 16;
;                 const float rstd = rsqrtf(__hip_atomic_load(rowss + row, __ATOMIC_RELAXED, __HIP_MEMORY_SCOPE_AGENT) * (1.f / 1024.f) + EPS);
; #pragma unroll
;                 for (int bj = 0; bj < 2; ++bj) {
;                     const int c = col0 + bj * 128;
;                     const f32x4 w0 = *(const f32x4*)(nw + c), w1 = *(const f32x4*)(nw + c + 4);
;                     float* op = out + (size_t)row * D + c;
;                     *(f32x4*)op = acc[ai][bj][m][0] * rstd * w0; *(f32x4*)(op + 4) = acc[ai][bj][m][1] * rstd * w1;
;                 }
;             }
	v_fmamk_f32 v90, v90, 0x3a800000, v137
	v_mul_f32_e32 v91, 0x4b800000, v90
	v_cmp_gt_f32_e32 vcc, s0, v90
	s_nop 1
	v_cndmask_b32_e32 v90, v90, v91, vcc
	v_rsq_f32_e32 v90, v90
	s_nop 0
	v_mul_f32_e32 v91, 0x45800000, v90
	v_cndmask_b32_e32 v90, v90, v91, vcc
	v_pk_mul_f32 v[92:93], v[154:155], v[90:91] op_sel_hi:[1,0]
	v_pk_mul_f32 v[78:79], v[78:79], v[90:91] op_sel_hi:[1,0]
	v_pk_mul_f32 v[94:95], v[76:77], v[90:91] op_sel_hi:[1,0]
	v_pk_mul_f32 v[96:97], v[74:75], v[90:91] op_sel_hi:[1,0]
	s_waitcnt vmcnt(1)
	v_pk_mul_f32 v[76:77], v[82:83], v[78:79]
	v_pk_mul_f32 v[74:75], v[80:81], v[92:93]
	s_waitcnt vmcnt(0)
	v_pk_mul_f32 v[80:81], v[86:87], v[96:97]
	v_pk_mul_f32 v[78:79], v[84:85], v[94:95]
	s_nop 1
	v_mov_b32_dpp v228, v78 row_ror:8 row_mask:0xf bank_mask:0xf
	v_mov_b32_dpp v229, v79 row_ror:8 row_mask:0xf bank_mask:0xf
	v_mov_b32_dpp v230, v80 row_ror:8 row_mask:0xf bank_mask:0xf
	v_mov_b32_dpp v231, v81 row_ror:8 row_mask:0xf bank_mask:0xf
	v_cndmask_b32_e64 v78, v228, v74, s[98:99]
	v_cndmask_b32_e64 v79, v229, v75, s[98:99]
	v_cndmask_b32_e64 v80, v230, v76, s[98:99]
	v_cndmask_b32_e64 v81, v231, v77, s[98:99]
	v_cndmask_b32_e64 v228, v74, v228, s[98:99]
	v_cndmask_b32_e64 v229, v75, v229, s[98:99]
	v_cndmask_b32_e64 v230, v76, v230, s[98:99]
	v_cndmask_b32_e64 v231, v77, v231, s[98:99]
	v_lshl_add_u64 v[232:233], v[88:89], 0, v[236:237]
	v_lshl_add_u64 v[234:235], v[88:89], 0, v[238:239]
	global_store_dwordx4 v[232:233], v[78:81], off sc0 sc1
	global_store_dwordx4 v[234:235], v[228:231], off sc0 sc1
	global_load_dwordx4 v[74:77], v[140:141], off offset:512
	s_nop 0
	global_load_dwordx4 v[78:81], v[140:141], off offset:528
	v_pk_mul_f32 v[70:71], v[70:71], v[90:91] op_sel_hi:[1,0]
	v_pk_mul_f32 v[68:69], v[68:69], v[90:91] op_sel_hi:[1,0]
	v_pk_mul_f32 v[82:83], v[66:67], v[90:91] op_sel_hi:[1,0]
	v_pk_mul_f32 v[84:85], v[64:65], v[90:91] op_sel_hi:[1,0]
	s_waitcnt vmcnt(1)
	v_pk_mul_f32 v[64:65], v[74:75], v[68:69]
	v_pk_mul_f32 v[66:67], v[76:77], v[70:71]
	s_waitcnt vmcnt(0)
	v_pk_mul_f32 v[68:69], v[78:79], v[84:85]
	v_pk_mul_f32 v[70:71], v[80:81], v[82:83]
	s_nop 1
	v_mov_b32_dpp v228, v68 row_ror:8 row_mask:0xf bank_mask:0xf
	v_mov_b32_dpp v229, v69 row_ror:8 row_mask:0xf bank_mask:0xf
	v_mov_b32_dpp v230, v70 row_ror:8 row_mask:0xf bank_mask:0xf
	v_mov_b32_dpp v231, v71 row_ror:8 row_mask:0xf bank_mask:0xf
	v_cndmask_b32_e64 v68, v228, v64, s[98:99]
	v_cndmask_b32_e64 v69, v229, v65, s[98:99]
	v_cndmask_b32_e64 v70, v230, v66, s[98:99]
	v_cndmask_b32_e64 v71, v231, v67, s[98:99]
	v_cndmask_b32_e64 v228, v64, v228, s[98:99]
	v_cndmask_b32_e64 v229, v65, v229, s[98:99]
	v_cndmask_b32_e64 v230, v66, v230, s[98:99]
	v_cndmask_b32_e64 v231, v67, v231, s[98:99]
	v_lshl_add_u64 v[232:233], v[88:89], 0, v[236:237]
	v_lshl_add_u64 v[234:235], v[88:89], 0, v[238:239]
	global_store_dwordx4 v[232:233], v[68:71], off offset:512 sc0 sc1
	global_store_dwordx4 v[234:235], v[228:231], off offset:512 sc0 sc1
	global_load_dword v74, v[112:113], off offset:512 sc1
	s_nop 0
	global_load_dwordx4 v[64:67], v[140:141], off
	global_load_dwordx4 v[68:71], v[140:141], off offset:16
	s_waitcnt vmcnt(2)
	v_fmamk_f32 v74, v74, 0x3a800000, v137
	v_mul_f32_e32 v75, 0x4b800000, v74
	v_cmp_gt_f32_e32 vcc, s0, v74
	s_nop 1
	v_cndmask_b32_e32 v74, v74, v75, vcc
	v_rsq_f32_e32 v74, v74
	s_nop 0
	v_mul_f32_e32 v75, 0x45800000, v74
	v_cndmask_b32_e32 v74, v74, v75, vcc
	v_pk_mul_f32 v[76:77], v[158:159], v[74:75] op_sel_hi:[1,0]
	v_pk_mul_f32 v[62:63], v[62:63], v[74:75] op_sel_hi:[1,0]
	v_pk_mul_f32 v[78:79], v[60:61], v[74:75] op_sel_hi:[1,0]
	v_pk_mul_f32 v[80:81], v[58:59], v[74:75] op_sel_hi:[1,0]
	s_waitcnt vmcnt(1)
	v_pk_mul_f32 v[60:61], v[66:67], v[62:63]
	v_pk_mul_f32 v[58:59], v[64:65], v[76:77]
	s_waitcnt vmcnt(0)
	v_pk_mul_f32 v[64:65], v[70:71], v[80:81]
	v_pk_mul_f32 v[62:63], v[68:69], v[78:79]
	s_nop 1
	v_mov_b32_dpp v228, v62 row_ror:8 row_mask:0xf bank_mask:0xf
	v_mov_b32_dpp v229, v63 row_ror:8 row_mask:0xf bank_mask:0xf
	v_mov_b32_dpp v230, v64 row_ror:8 row_mask:0xf bank_mask:0xf
	v_mov_b32_dpp v231, v65 row_ror:8 row_mask:0xf bank_mask:0xf
	v_cndmask_b32_e64 v62, v228, v58, s[98:99]
	v_cndmask_b32_e64 v63, v229, v59, s[98:99]
	v_cndmask_b32_e64 v64, v230, v60, s[98:99]
	v_cndmask_b32_e64 v65, v231, v61, s[98:99]
	v_cndmask_b32_e64 v228, v58, v228, s[98:99]
	v_cndmask_b32_e64 v229, v59, v229, s[98:99]
	v_cndmask_b32_e64 v230, v60, v230, s[98:99]
	v_cndmask_b32_e64 v231, v61, v231, s[98:99]
	v_lshl_add_u64 v[232:233], v[72:73], 0, v[236:237]
	v_lshl_add_u64 v[234:235], v[72:73], 0, v[238:239]
	global_store_dwordx4 v[232:233], v[62:65], off sc0 sc1
	global_store_dwordx4 v[234:235], v[228:231], off sc0 sc1
	global_load_dwordx4 v[58:61], v[140:141], off offset:512
	s_nop 0
	global_load_dwordx4 v[62:65], v[140:141], off offset:528
	v_pk_mul_f32 v[54:55], v[54:55], v[74:75] op_sel_hi:[1,0]
	v_pk_mul_f32 v[52:53], v[52:53], v[74:75] op_sel_hi:[1,0]
	v_pk_mul_f32 v[66:67], v[50:51], v[74:75] op_sel_hi:[1,0]
	v_pk_mul_f32 v[68:69], v[48:49], v[74:75] op_sel_hi:[1,0]
	s_waitcnt vmcnt(1)
	v_pk_mul_f32 v[48:49], v[58:59], v[52:53]
	v_pk_mul_f32 v[50:51], v[60:61], v[54:55]
	s_waitcnt vmcnt(0)
;     __device__ __forceinline__ void operator()(f32x4 (&acc)[2][2][4][2], const pg8::Unit& u, int wr, int wc, int fr, int fq) const {
;     ...
; #pragma unroll
;         for (int ai = 0; ai < 2; ++ai)
; #pragma unroll
;             for (int m = 0; m < 4; ++m) {
;                 const int row = row0 + ai * 128 + m * 16;
;                 const float rstd = rsqrtf(__hip_atomic_load(rowss + row, __ATOMIC_RELAXED, __HIP_MEMORY_SCOPE_AGENT) * (1.f / 1024.f) + EPS);
; #pragma unroll
;                 for (int bj = 0; bj < 2; ++bj) {
;                     const int c = col0 + bj * 128;
;                     const f32x4 w0 = *(const f32x4*)(nw + c), w1 = *(const f32x4*)(nw + c + 4);
;                     float* op = out + (size_t)row * D + c;
;                     *(f32x4*)op = acc[ai][bj][m][0] * rstd * w0; *(f32x4*)(op + 4) = acc[ai][bj][m][1] * rstd * w1;
;                 }
;             }
	v_pk_mul_f32 v[52:53], v[62:63], v[68:69]
	v_pk_mul_f32 v[54:55], v[64:65], v[66:67]
	s_nop 1
	v_mov_b32_dpp v228, v52 row_ror:8 row_mask:0xf bank_mask:0xf
	v_mov_b32_dpp v229, v53 row_ror:8 row_mask:0xf bank_mask:0xf
	v_mov_b32_dpp v230, v54 row_ror:8 row_mask:0xf bank_mask:0xf
	v_mov_b32_dpp v231, v55 row_ror:8 row_mask:0xf bank_mask:0xf
	v_cndmask_b32_e64 v52, v228, v48, s[98:99]
	v_cndmask_b32_e64 v53, v229, v49, s[98:99]
	v_cndmask_b32_e64 v54, v230, v50, s[98:99]
	v_cndmask_b32_e64 v55, v231, v51, s[98:99]
	v_cndmask_b32_e64 v228, v48, v228, s[98:99]
	v_cndmask_b32_e64 v229, v49, v229, s[98:99]
	v_cndmask_b32_e64 v230, v50, v230, s[98:99]
	v_cndmask_b32_e64 v231, v51, v231, s[98:99]
	v_lshl_add_u64 v[232:233], v[72:73], 0, v[236:237]
	v_lshl_add_u64 v[234:235], v[72:73], 0, v[238:239]
	global_store_dwordx4 v[232:233], v[52:55], off offset:512 sc0 sc1
	global_store_dwordx4 v[234:235], v[228:231], off offset:512 sc0 sc1
	global_load_dword v58, v[112:113], off offset:576 sc1
	s_nop 0
	global_load_dwordx4 v[48:51], v[140:141], off
	global_load_dwordx4 v[52:55], v[140:141], off offset:16
	s_waitcnt vmcnt(2)
	v_fmamk_f32 v58, v58, 0x3a800000, v137
	v_mul_f32_e32 v59, 0x4b800000, v58
	v_cmp_gt_f32_e32 vcc, s0, v58
	s_nop 1
	v_cndmask_b32_e32 v58, v58, v59, vcc
	v_rsq_f32_e32 v58, v58
	s_nop 0
	v_mul_f32_e32 v59, 0x45800000, v58
	v_cndmask_b32_e32 v58, v58, v59, vcc
	v_pk_mul_f32 v[60:61], v[162:163], v[58:59] op_sel_hi:[1,0]
	v_pk_mul_f32 v[46:47], v[46:47], v[58:59] op_sel_hi:[1,0]
	v_pk_mul_f32 v[62:63], v[44:45], v[58:59] op_sel_hi:[1,0]
	v_pk_mul_f32 v[64:65], v[42:43], v[58:59] op_sel_hi:[1,0]
	s_waitcnt vmcnt(1)
	v_pk_mul_f32 v[44:45], v[50:51], v[46:47]
	v_pk_mul_f32 v[42:43], v[48:49], v[60:61]
	s_waitcnt vmcnt(0)
	v_pk_mul_f32 v[48:49], v[54:55], v[64:65]
	v_pk_mul_f32 v[46:47], v[52:53], v[62:63]
	s_nop 1
	v_mov_b32_dpp v228, v46 row_ror:8 row_mask:0xf bank_mask:0xf
	v_mov_b32_dpp v229, v47 row_ror:8 row_mask:0xf bank_mask:0xf
	v_mov_b32_dpp v230, v48 row_ror:8 row_mask:0xf bank_mask:0xf
	v_mov_b32_dpp v231, v49 row_ror:8 row_mask:0xf bank_mask:0xf
	v_cndmask_b32_e64 v46, v228, v42, s[98:99]
	v_cndmask_b32_e64 v47, v229, v43, s[98:99]
	v_cndmask_b32_e64 v48, v230, v44, s[98:99]
	v_cndmask_b32_e64 v49, v231, v45, s[98:99]
	v_cndmask_b32_e64 v228, v42, v228, s[98:99]
	v_cndmask_b32_e64 v229, v43, v229, s[98:99]
	v_cndmask_b32_e64 v230, v44, v230, s[98:99]
	v_cndmask_b32_e64 v231, v45, v231, s[98:99]
	v_lshl_add_u64 v[232:233], v[56:57], 0, v[236:237]
	v_lshl_add_u64 v[234:235], v[56:57], 0, v[238:239]
	global_store_dwordx4 v[232:233], v[46:49], off sc0 sc1
	global_store_dwordx4 v[234:235], v[228:231], off sc0 sc1
	global_load_dwordx4 v[42:45], v[140:141], off offset:512
	s_nop 0
	global_load_dwordx4 v[46:49], v[140:141], off offset:528
	v_pk_mul_f32 v[38:39], v[38:39], v[58:59] op_sel_hi:[1,0]
	v_pk_mul_f32 v[36:37], v[36:37], v[58:59] op_sel_hi:[1,0]
	v_pk_mul_f32 v[50:51], v[34:35], v[58:59] op_sel_hi:[1,0]
	v_pk_mul_f32 v[52:53], v[32:33], v[58:59] op_sel_hi:[1,0]
	s_waitcnt vmcnt(1)
	v_pk_mul_f32 v[32:33], v[42:43], v[36:37]
	v_pk_mul_f32 v[34:35], v[44:45], v[38:39]
	s_waitcnt vmcnt(0)
	v_pk_mul_f32 v[36:37], v[46:47], v[52:53]
	v_pk_mul_f32 v[38:39], v[48:49], v[50:51]
	s_nop 1
	v_mov_b32_dpp v228, v36 row_ror:8 row_mask:0xf bank_mask:0xf
	v_mov_b32_dpp v229, v37 row_ror:8 row_mask:0xf bank_mask:0xf
	v_mov_b32_dpp v230, v38 row_ror:8 row_mask:0xf bank_mask:0xf
	v_mov_b32_dpp v231, v39 row_ror:8 row_mask:0xf bank_mask:0xf
	v_cndmask_b32_e64 v36, v228, v32, s[98:99]
	v_cndmask_b32_e64 v37, v229, v33, s[98:99]
	v_cndmask_b32_e64 v38, v230, v34, s[98:99]
	v_cndmask_b32_e64 v39, v231, v35, s[98:99]
	v_cndmask_b32_e64 v228, v32, v228, s[98:99]
	v_cndmask_b32_e64 v229, v33, v229, s[98:99]
	v_cndmask_b32_e64 v230, v34, v230, s[98:99]
	v_cndmask_b32_e64 v231, v35, v231, s[98:99]
	v_lshl_add_u64 v[232:233], v[56:57], 0, v[236:237]
	v_lshl_add_u64 v[234:235], v[56:57], 0, v[238:239]
	global_store_dwordx4 v[232:233], v[36:39], off offset:512 sc0 sc1
	global_store_dwordx4 v[234:235], v[228:231], off offset:512 sc0 sc1
	global_load_dword v42, v[112:113], off offset:640 sc1
	s_nop 0
	global_load_dwordx4 v[32:35], v[140:141], off
	global_load_dwordx4 v[36:39], v[140:141], off offset:16
	s_waitcnt vmcnt(2)
	v_fmamk_f32 v42, v42, 0x3a800000, v137
	v_mul_f32_e32 v43, 0x4b800000, v42
	v_cmp_gt_f32_e32 vcc, s0, v42
	s_nop 1
	v_cndmask_b32_e32 v42, v42, v43, vcc
	v_rsq_f32_e32 v42, v42
	s_nop 0
	v_mul_f32_e32 v43, 0x45800000, v42
	v_cndmask_b32_e32 v42, v42, v43, vcc
	v_pk_mul_f32 v[44:45], v[164:165], v[42:43] op_sel_hi:[1,0]
	v_pk_mul_f32 v[30:31], v[30:31], v[42:43] op_sel_hi:[1,0]
	v_pk_mul_f32 v[46:47], v[28:29], v[42:43] op_sel_hi:[1,0]
	v_pk_mul_f32 v[48:49], v[26:27], v[42:43] op_sel_hi:[1,0]
	s_waitcnt vmcnt(1)
	v_pk_mul_f32 v[28:29], v[34:35], v[30:31]
	v_pk_mul_f32 v[26:27], v[32:33], v[44:45]
	s_waitcnt vmcnt(0)
;     __device__ __forceinline__ void operator()(f32x4 (&acc)[2][2][4][2], const pg8::Unit& u, int wr, int wc, int fr, int fq) const {
;     ...
; #pragma unroll
;         for (int ai = 0; ai < 2; ++ai)
; #pragma unroll
;             for (int m = 0; m < 4; ++m) {
;                 const int row = row0 + ai * 128 + m * 16;
;                 const float rstd = rsqrtf(__hip_atomic_load(rowss + row, __ATOMIC_RELAXED, __HIP_MEMORY_SCOPE_AGENT) * (1.f / 1024.f) + EPS);
; #pragma unroll
;                 for (int bj = 0; bj < 2; ++bj) {
;                     const int c = col0 + bj * 128;
;                     const f32x4 w0 = *(const f32x4*)(nw + c), w1 = *(const f32x4*)(nw + c + 4);
;                     float* op = out + (size_t)row * D + c;
;                     *(f32x4*)op = acc[ai][bj][m][0] * rstd * w0; *(f32x4*)(op + 4) = acc[ai][bj][m][1] * rstd * w1;
;                 }
;             }
	v_pk_mul_f32 v[32:33], v[38:39], v[48:49]
	v_pk_mul_f32 v[30:31], v[36:37], v[46:47]
	s_nop 1
	v_mov_b32_dpp v228, v30 row_ror:8 row_mask:0xf bank_mask:0xf
	v_mov_b32_dpp v229, v31 row_ror:8 row_mask:0xf bank_mask:0xf
	v_mov_b32_dpp v230, v32 row_ror:8 row_mask:0xf bank_mask:0xf
	v_mov_b32_dpp v231, v33 row_ror:8 row_mask:0xf bank_mask:0xf
	v_cndmask_b32_e64 v30, v228, v26, s[98:99]
	v_cndmask_b32_e64 v31, v229, v27, s[98:99]
	v_cndmask_b32_e64 v32, v230, v28, s[98:99]
	v_cndmask_b32_e64 v33, v231, v29, s[98:99]
	v_cndmask_b32_e64 v228, v26, v228, s[98:99]
	v_cndmask_b32_e64 v229, v27, v229, s[98:99]
	v_cndmask_b32_e64 v230, v28, v230, s[98:99]
	v_cndmask_b32_e64 v231, v29, v231, s[98:99]
	v_lshl_add_u64 v[232:233], v[40:41], 0, v[236:237]
	v_lshl_add_u64 v[234:235], v[40:41], 0, v[238:239]
	global_store_dwordx4 v[232:233], v[30:33], off sc0 sc1
	global_store_dwordx4 v[234:235], v[228:231], off sc0 sc1
	global_load_dwordx4 v[26:29], v[140:141], off offset:512
	s_nop 0
	global_load_dwordx4 v[30:33], v[140:141], off offset:528
	v_pk_mul_f32 v[22:23], v[22:23], v[42:43] op_sel_hi:[1,0]
	v_pk_mul_f32 v[20:21], v[20:21], v[42:43] op_sel_hi:[1,0]
	v_pk_mul_f32 v[34:35], v[18:19], v[42:43] op_sel_hi:[1,0]
	v_pk_mul_f32 v[36:37], v[16:17], v[42:43] op_sel_hi:[1,0]
	s_waitcnt vmcnt(1)
	v_pk_mul_f32 v[16:17], v[26:27], v[20:21]
	v_pk_mul_f32 v[18:19], v[28:29], v[22:23]
	s_waitcnt vmcnt(0)
	v_pk_mul_f32 v[20:21], v[30:31], v[36:37]
	v_pk_mul_f32 v[22:23], v[32:33], v[34:35]
	s_nop 1
	v_mov_b32_dpp v228, v20 row_ror:8 row_mask:0xf bank_mask:0xf
	v_mov_b32_dpp v229, v21 row_ror:8 row_mask:0xf bank_mask:0xf
	v_mov_b32_dpp v230, v22 row_ror:8 row_mask:0xf bank_mask:0xf
	v_mov_b32_dpp v231, v23 row_ror:8 row_mask:0xf bank_mask:0xf
	v_cndmask_b32_e64 v20, v228, v16, s[98:99]
	v_cndmask_b32_e64 v21, v229, v17, s[98:99]
	v_cndmask_b32_e64 v22, v230, v18, s[98:99]
	v_cndmask_b32_e64 v23, v231, v19, s[98:99]
	v_cndmask_b32_e64 v228, v16, v228, s[98:99]
	v_cndmask_b32_e64 v229, v17, v229, s[98:99]
	v_cndmask_b32_e64 v230, v18, v230, s[98:99]
	v_cndmask_b32_e64 v231, v19, v231, s[98:99]
	v_lshl_add_u64 v[232:233], v[40:41], 0, v[236:237]
	v_lshl_add_u64 v[234:235], v[40:41], 0, v[238:239]
	global_store_dwordx4 v[232:233], v[20:23], off offset:512 sc0 sc1
	global_store_dwordx4 v[234:235], v[228:231], off offset:512 sc0 sc1
	global_load_dword v26, v[112:113], off offset:704 sc1
	s_nop 0
	global_load_dwordx4 v[16:19], v[140:141], off
	global_load_dwordx4 v[20:23], v[140:141], off offset:16
	s_waitcnt vmcnt(2)
	v_fmac_f32_e32 v137, 0x3a800000, v26
	v_mul_f32_e32 v26, 0x4b800000, v137
	v_cmp_gt_f32_e32 vcc, s0, v137
	s_nop 1
	v_cndmask_b32_e32 v26, v137, v26, vcc
	v_rsq_f32_e32 v26, v26
	s_nop 0
	v_mul_f32_e32 v27, 0x45800000, v26
	v_cndmask_b32_e32 v26, v26, v27, vcc
	v_pk_mul_f32 v[12:13], v[12:13], v[26:27] op_sel_hi:[1,0]
	v_pk_mul_f32 v[14:15], v[14:15], v[26:27] op_sel_hi:[1,0]
	v_pk_mul_f32 v[28:29], v[8:9], v[26:27] op_sel_hi:[1,0]
	v_pk_mul_f32 v[30:31], v[10:11], v[26:27] op_sel_hi:[1,0]
	s_waitcnt vmcnt(1)
	v_pk_mul_f32 v[10:11], v[18:19], v[14:15]
	v_pk_mul_f32 v[8:9], v[16:17], v[12:13]
	s_waitcnt vmcnt(0)
	v_pk_mul_f32 v[14:15], v[22:23], v[30:31]
	v_pk_mul_f32 v[12:13], v[20:21], v[28:29]
	s_nop 1
	v_mov_b32_dpp v228, v12 row_ror:8 row_mask:0xf bank_mask:0xf
	v_mov_b32_dpp v229, v13 row_ror:8 row_mask:0xf bank_mask:0xf
	v_mov_b32_dpp v230, v14 row_ror:8 row_mask:0xf bank_mask:0xf
	v_mov_b32_dpp v231, v15 row_ror:8 row_mask:0xf bank_mask:0xf
	v_cndmask_b32_e64 v12, v228, v8, s[98:99]
	v_cndmask_b32_e64 v13, v229, v9, s[98:99]
	v_cndmask_b32_e64 v14, v230, v10, s[98:99]
	v_cndmask_b32_e64 v15, v231, v11, s[98:99]
	v_cndmask_b32_e64 v228, v8, v228, s[98:99]
	v_cndmask_b32_e64 v229, v9, v229, s[98:99]
	v_cndmask_b32_e64 v230, v10, v230, s[98:99]
	v_cndmask_b32_e64 v231, v11, v231, s[98:99]
	v_lshl_add_u64 v[232:233], v[24:25], 0, v[236:237]
	v_lshl_add_u64 v[234:235], v[24:25], 0, v[238:239]
	global_store_dwordx4 v[232:233], v[12:15], off sc0 sc1
	global_store_dwordx4 v[234:235], v[228:231], off sc0 sc1
	global_load_dwordx4 v[8:11], v[140:141], off offset:512
	s_nop 0
	global_load_dwordx4 v[12:15], v[140:141], off offset:528
	v_pk_mul_f32 v[6:7], v[6:7], v[26:27] op_sel_hi:[1,0]
	v_pk_mul_f32 v[4:5], v[4:5], v[26:27] op_sel_hi:[1,0]
	v_pk_mul_f32 v[16:17], v[2:3], v[26:27] op_sel_hi:[1,0]
	v_pk_mul_f32 v[18:19], v[0:1], v[26:27] op_sel_hi:[1,0]
	s_waitcnt vmcnt(1)
	v_pk_mul_f32 v[0:1], v[8:9], v[4:5]
	v_pk_mul_f32 v[2:3], v[10:11], v[6:7]
	s_waitcnt vmcnt(0)
	v_pk_mul_f32 v[4:5], v[12:13], v[18:19]
	v_pk_mul_f32 v[6:7], v[14:15], v[16:17]
	s_nop 1
	v_mov_b32_dpp v228, v4 row_ror:8 row_mask:0xf bank_mask:0xf
	v_mov_b32_dpp v229, v5 row_ror:8 row_mask:0xf bank_mask:0xf
	v_mov_b32_dpp v230, v6 row_ror:8 row_mask:0xf bank_mask:0xf
	v_mov_b32_dpp v231, v7 row_ror:8 row_mask:0xf bank_mask:0xf
	v_cndmask_b32_e64 v4, v228, v0, s[98:99]
	v_cndmask_b32_e64 v5, v229, v1, s[98:99]
	v_cndmask_b32_e64 v6, v230, v2, s[98:99]
	v_cndmask_b32_e64 v7, v231, v3, s[98:99]
	v_cndmask_b32_e64 v228, v0, v228, s[98:99]
	v_cndmask_b32_e64 v229, v1, v229, s[98:99]
	v_cndmask_b32_e64 v230, v2, v230, s[98:99]
	v_cndmask_b32_e64 v231, v3, v231, s[98:99]
	v_lshl_add_u64 v[232:233], v[24:25], 0, v[236:237]
	v_lshl_add_u64 v[234:235], v[24:25], 0, v[238:239]
	global_store_dwordx4 v[232:233], v[4:7], off offset:512 sc0 sc1
	global_store_dwordx4 v[234:235], v[228:231], off offset:512 sc0 sc1
